# GEMM K-loops: first trip of every unit peeled (C=0 first MFMAs, no accumulator zeroing) and its first segment wait counted past the previous unit's epilogue stores (vmcnt 16/24); on top of v92
# speedup vs baseline: 1.0056x; 1.0017x over previous
; #define PG8_STAGE(bufoff, gbase, voff) do { _Pragma("unroll") for (int _i = 0; _i < 2; ++_i) \
;         __builtin_amdgcn_global_load_lds((const unsigned*)((const char*)(gbase) + (voff)[_i]), (LAS unsigned*)(lds + (bufoff) + ldsw + _i * 8192), 16, 0, 0); } while (0)
; #define PG8_LDA(dst, b, h) do { _Pragma("unroll") for (int m = 0; m < 4; ++m) _Pragma("unroll") for (int k = 0; k < 2; ++k) dst[m][k] = *(const LAS bf16x8*)(lds + PG8_SA(b, h) + aoff + m * 2048 + k * 1024); } while (0)
; #define PG8_LDB(dst, b, h) do { _Pragma("unroll") for (int n = 0; n < 2; ++n) _Pragma("unroll") for (int k = 0; k < 2; ++k) dst[n][k] = *(const LAS bf16x8*)(lds + PG8_SB(b, h) + boff + n * 2048 + k * 1024); } while (0)
; #define PG8_MMA(ai, bj, At, Bt) do { __builtin_amdgcn_s_setprio(1); _Pragma("unroll") for (int m = 0; m < 4; ++m) _Pragma("unroll") for (int n = 0; n < 2; ++n) _Pragma("unroll") for (int k = 0; k < 2; ++k) \
;         acc[ai][bj][m][n] = __builtin_amdgcn_mfma_f32_16x16x32_bf16(Bt[n][k], At[m][k], acc[ai][bj][m][n], 0, 0, 0); __builtin_amdgcn_s_setprio(0); } while (0)
; #define PG8_WAIT_V(n) asm volatile("s_waitcnt vmcnt(" #n ")" ::: "memory")
; #define PG8_WAIT_L(n) asm volatile("s_waitcnt lgkmcnt(" #n ")" ::: "memory")
; #define PG8_BAR __builtin_amdgcn_s_barrier()
; #define PG8_SCHED __builtin_amdgcn_sched_barrier(0)
; template <class Epi, bool SP2 = false>
; __device__ __forceinline__ void gemm_phase(LAS unsigned char* lds, const Gemm g, const StaticOrder& S, const Epi& E) {
;     ...
;         const bool has_next = S.next(ui + 1, nxt);
;         const char* nA = has_next ? (const char*)g.A + (size_t)nxt.pm * tstepA : cA; const char* nB = has_next ? (const char*)g.Bt + (size_t)nxt.pn * tstepB : cB;
;         for (int t = 0; t < nt; t += 2) {
;             const bool last = (t == nt - 2);
;             const char* a1 = cA + (size_t)(t + 1) * kstep;
;             const char* a2 = last ? nA : cA + (size_t)(t + 2) * kstep; const char* b2 = last ? nB : cB + (size_t)(t + 2) * kstep;
;             const char* a3 = a2 + kstep; const char* b3 = b2 + kstep;
;             if constexpr (SP2) {
;             PG8_LDB(B0, 0, 0); PG8_LDB(B1, 0, 1); PG8_SCHED; PG8_LDA(At, 0, 0); PG8_STAGE(PG8_SA(1, 1), a1 + hstepA, voffA);
;             PG8_WAIT_V(8); PG8_WAIT_L(0); PG8_BAR; PG8_MMA(0, 0, At, B0); PG8_MMA(0, 1, At, B1); PG8_BAR; PG8_SCHED;
.LBB0_262:
	s_ashr_i32 s27, s26, 31
	s_lshl_b64 s[28:29], s[26:27], 19
	s_add_u32 s28, s14, s28
	s_addc_u32 s29, s15, s29
	s_and_b64 s[30:31], s[0:1], exec
	s_cselect_b32 s27, s29, s35
	s_cselect_b32 s67, s28, s34
	s_ashr_i32 s25, s24, 31
	s_lshl_b64 s[30:31], s[24:25], 19
	s_add_u32 s30, s92, s30
	s_addc_u32 s31, s93, s31
	s_and_b64 s[50:51], s[0:1], exec
	s_cselect_b32 s25, s31, s45
	s_cselect_b32 s72, s30, s44
	s_add_u32 s34, s34, 0x40080
	s_addc_u32 s35, s35, 0
	s_add_u32 s73, s44, 0x100
	s_addc_u32 s74, s45, 0
	s_mov_b32 s75, -2
	ds_read_b128 v[152:155], v149
	ds_read_b128 v[156:159], v149 offset:1024
	ds_read_b128 v[160:163], v149 offset:2048
	ds_read_b128 v[164:167], v149 offset:3072
	ds_read_b128 v[168:171], v150
	ds_read_b128 v[172:175], v150 offset:1024
	ds_read_b128 v[176:179], v150 offset:2048
	ds_read_b128 v[180:183], v150 offset:3072
	s_add_u32 s44, s34, 0xfffc0080
	s_addc_u32 s45, s35, -1
	s_cmp_eq_u32 s75, 12
	s_cselect_b32 s51, s27, s45
	s_cselect_b32 s50, s67, s44
	s_cselect_b32 s45, s25, s74
	s_cselect_b32 s44, s72, s73
	v_lshl_add_u64 v[146:147], s[34:35], 0, v[138:139]
	s_add_i32 m0, s41, 0xc000
	ds_read_b128 v[184:187], v151
	ds_read_b128 v[188:191], v151 offset:1024
	ds_read_b128 v[192:195], v151 offset:2048
	ds_read_b128 v[196:199], v151 offset:3072
	ds_read_b128 v[200:203], v151 offset:4096
	ds_read_b128 v[204:207], v151 offset:5120
	ds_read_b128 v[208:211], v151 offset:6144
	ds_read_b128 v[212:215], v151 offset:7168
	global_load_lds_dwordx4 v[146:147], off
	v_lshl_add_u64 v[146:147], s[34:35], 0, v[140:141]
	s_add_i32 m0, s41, 0xe000
	s_nop 0
	global_load_lds_dwordx4 v[146:147], off
	s_waitcnt vmcnt(16)
	s_waitcnt lgkmcnt(0)
	s_barrier
	v_mfma_f32_16x16x32_bf16 v[124:127], v[152:155], v[184:187], 0
	v_mfma_f32_16x16x32_bf16 v[120:123], v[160:163], v[184:187], 0
	v_mfma_f32_16x16x32_bf16 v[108:111], v[152:155], v[192:195], 0
	v_mfma_f32_16x16x32_bf16 v[104:107], v[160:163], v[192:195], 0
	v_mfma_f32_16x16x32_bf16 v[92:95], v[152:155], v[200:203], 0
	v_mfma_f32_16x16x32_bf16 v[88:91], v[160:163], v[200:203], 0
	v_mfma_f32_16x16x32_bf16 v[76:79], v[152:155], v[208:211], 0
	v_mfma_f32_16x16x32_bf16 v[72:75], v[160:163], v[208:211], 0
	v_mfma_f32_16x16x32_bf16 v[124:127], v[156:159], v[188:191], v[124:127]
	v_mfma_f32_16x16x32_bf16 v[120:123], v[164:167], v[188:191], v[120:123]
	v_mfma_f32_16x16x32_bf16 v[108:111], v[156:159], v[196:199], v[108:111]
	v_mfma_f32_16x16x32_bf16 v[104:107], v[164:167], v[196:199], v[104:107]
	v_mfma_f32_16x16x32_bf16 v[92:95], v[156:159], v[204:207], v[92:95]
	v_mfma_f32_16x16x32_bf16 v[88:91], v[164:167], v[204:207], v[88:91]
	v_mfma_f32_16x16x32_bf16 v[76:79], v[156:159], v[212:215], v[76:79]
	v_mfma_f32_16x16x32_bf16 v[72:75], v[164:167], v[212:215], v[72:75]
	v_mfma_f32_16x16x32_bf16 v[116:119], v[168:171], v[184:187], 0
	v_mfma_f32_16x16x32_bf16 v[112:115], v[176:179], v[184:187], 0
	v_mfma_f32_16x16x32_bf16 v[100:103], v[168:171], v[192:195], 0
	v_mfma_f32_16x16x32_bf16 v[96:99], v[176:179], v[192:195], 0
	v_mfma_f32_16x16x32_bf16 v[84:87], v[168:171], v[200:203], 0
	v_mfma_f32_16x16x32_bf16 v[80:83], v[176:179], v[200:203], 0
	v_mfma_f32_16x16x32_bf16 v[68:71], v[168:171], v[208:211], 0
	v_mfma_f32_16x16x32_bf16 v[64:67], v[176:179], v[208:211], 0
	v_mfma_f32_16x16x32_bf16 v[116:119], v[172:175], v[188:191], v[116:119]
	v_mfma_f32_16x16x32_bf16 v[112:115], v[180:183], v[188:191], v[112:115]
	v_mfma_f32_16x16x32_bf16 v[100:103], v[172:175], v[196:199], v[100:103]
	v_mfma_f32_16x16x32_bf16 v[96:99], v[180:183], v[196:199], v[96:99]
	v_mfma_f32_16x16x32_bf16 v[84:87], v[172:175], v[204:207], v[84:87]
	v_mfma_f32_16x16x32_bf16 v[80:83], v[180:183], v[204:207], v[80:83]
	v_mfma_f32_16x16x32_bf16 v[68:71], v[172:175], v[212:215], v[68:71]
	v_mfma_f32_16x16x32_bf16 v[64:67], v[180:183], v[212:215], v[64:67]
	s_barrier
	s_add_i32 s68, s64, s3
	v_lshl_add_u64 v[146:147], s[44:45], 0, v[134:135]
	s_mov_b32 m0, s68
	ds_read_b128 v[184:187], v151 offset:16384
	ds_read_b128 v[188:191], v151 offset:17408
	ds_read_b128 v[192:195], v151 offset:18432
	ds_read_b128 v[196:199], v151 offset:19456
	ds_read_b128 v[200:203], v151 offset:20480
	ds_read_b128 v[204:207], v151 offset:21504
	ds_read_b128 v[208:211], v151 offset:22528
	ds_read_b128 v[212:215], v151 offset:23552
	global_load_lds_dwordx4 v[146:147], off
	s_add_i32 m0, s68, 0x2000
	s_add_u32 s68, s44, 0x40000
	v_lshl_add_u64 v[216:217], s[44:45], 0, v[130:131]
	s_addc_u32 s69, s45, 0
	s_add_i32 s70, s65, s3
	global_load_lds_dwordx4 v[216:217], off
	v_lshl_add_u64 v[218:219], s[68:69], 0, v[134:135]
	s_mov_b32 m0, s70
	v_lshl_add_u64 v[220:221], s[50:51], 0, v[132:133]
	global_load_lds_dwordx4 v[218:219], off
	v_lshl_add_u64 v[218:219], s[68:69], 0, v[130:131]
	s_add_i32 m0, s70, 0x2000
	s_nop 0
	global_load_lds_dwordx4 v[218:219], off
	v_lshl_add_u64 v[218:219], s[50:51], 0, v[136:137]
	s_mov_b32 m0, s41
	s_nop 0
	global_load_lds_dwordx4 v[218:219], off
	s_mov_b32 m0, s54
	s_nop 0
	global_load_lds_dwordx4 v[220:221], off
	s_waitcnt vmcnt(8)
	s_waitcnt lgkmcnt(0)
	s_barrier
; #define PG8_STAGE(bufoff, gbase, voff) do { _Pragma("unroll") for (int _i = 0; _i < 2; ++_i) \
;         __builtin_amdgcn_global_load_lds((const unsigned*)((const char*)(gbase) + (voff)[_i]), (LAS unsigned*)(lds + (bufoff) + ldsw + _i * 8192), 16, 0, 0); } while (0)
; #define PG8_LDA(dst, b, h) do { _Pragma("unroll") for (int m = 0; m < 4; ++m) _Pragma("unroll") for (int k = 0; k < 2; ++k) dst[m][k] = *(const LAS bf16x8*)(lds + PG8_SA(b, h) + aoff + m * 2048 + k * 1024); } while (0)
; #define PG8_LDB(dst, b, h) do { _Pragma("unroll") for (int n = 0; n < 2; ++n) _Pragma("unroll") for (int k = 0; k < 2; ++k) dst[n][k] = *(const LAS bf16x8*)(lds + PG8_SB(b, h) + boff + n * 2048 + k * 1024); } while (0)
; #define PG8_MMA(ai, bj, At, Bt) do { __builtin_amdgcn_s_setprio(1); _Pragma("unroll") for (int m = 0; m < 4; ++m) _Pragma("unroll") for (int n = 0; n < 2; ++n) _Pragma("unroll") for (int k = 0; k < 2; ++k) \
;         acc[ai][bj][m][n] = __builtin_amdgcn_mfma_f32_16x16x32_bf16(Bt[n][k], At[m][k], acc[ai][bj][m][n], 0, 0, 0); __builtin_amdgcn_s_setprio(0); } while (0)
; #define PG8_WAIT_V(n) asm volatile("s_waitcnt vmcnt(" #n ")" ::: "memory")
; #define PG8_WAIT_L(n) asm volatile("s_waitcnt lgkmcnt(" #n ")" ::: "memory")
; #define PG8_BAR __builtin_amdgcn_s_barrier()
; #define PG8_SCHED __builtin_amdgcn_sched_barrier(0)
; template <class Epi, bool SP2 = false>
; __device__ __forceinline__ void gemm_phase(LAS unsigned char* lds, const Gemm g, const StaticOrder& S, const Epi& E) {
;     ...
;             PG8_WAIT_V(8); PG8_WAIT_L(0); PG8_BAR; PG8_MMA(1, 0, At, B0); PG8_MMA(1, 1, At, B1); PG8_BAR; PG8_SCHED;
;             PG8_LDB(B0, 1, 0); PG8_LDB(B1, 1, 1); PG8_SCHED; PG8_LDA(At, 1, 0); PG8_STAGE(PG8_SA(0, 1), a2 + hstepA, voffA);
;             PG8_WAIT_V(8); PG8_WAIT_L(0); PG8_BAR; PG8_MMA(0, 0, At, B0); PG8_MMA(0, 1, At, B1); PG8_BAR; PG8_SCHED;
	v_mfma_f32_16x16x32_bf16 v[60:63], v[152:155], v[184:187], 0
	v_mfma_f32_16x16x32_bf16 v[56:59], v[160:163], v[184:187], 0
	v_mfma_f32_16x16x32_bf16 v[44:47], v[152:155], v[192:195], 0
	v_mfma_f32_16x16x32_bf16 v[40:43], v[160:163], v[192:195], 0
	v_mfma_f32_16x16x32_bf16 v[28:31], v[152:155], v[200:203], 0
	v_mfma_f32_16x16x32_bf16 v[24:27], v[160:163], v[200:203], 0
	v_mfma_f32_16x16x32_bf16 v[12:15], v[152:155], v[208:211], 0
	v_mfma_f32_16x16x32_bf16 v[8:11], v[160:163], v[208:211], 0
	v_mfma_f32_16x16x32_bf16 v[60:63], v[156:159], v[188:191], v[60:63]
	v_mfma_f32_16x16x32_bf16 v[56:59], v[164:167], v[188:191], v[56:59]
	v_mfma_f32_16x16x32_bf16 v[44:47], v[156:159], v[196:199], v[44:47]
	v_mfma_f32_16x16x32_bf16 v[40:43], v[164:167], v[196:199], v[40:43]
	v_mfma_f32_16x16x32_bf16 v[28:31], v[156:159], v[204:207], v[28:31]
	v_mfma_f32_16x16x32_bf16 v[24:27], v[164:167], v[204:207], v[24:27]
	v_mfma_f32_16x16x32_bf16 v[12:15], v[156:159], v[212:215], v[12:15]
	v_mfma_f32_16x16x32_bf16 v[8:11], v[164:167], v[212:215], v[8:11]
	v_mfma_f32_16x16x32_bf16 v[52:55], v[168:171], v[184:187], 0
	v_mfma_f32_16x16x32_bf16 v[48:51], v[176:179], v[184:187], 0
	v_mfma_f32_16x16x32_bf16 v[36:39], v[168:171], v[192:195], 0
	v_mfma_f32_16x16x32_bf16 v[32:35], v[176:179], v[192:195], 0
	v_mfma_f32_16x16x32_bf16 v[20:23], v[168:171], v[200:203], 0
	v_mfma_f32_16x16x32_bf16 v[16:19], v[176:179], v[200:203], 0
	v_mfma_f32_16x16x32_bf16 v[4:7], v[168:171], v[208:211], 0
	v_mfma_f32_16x16x32_bf16 v[0:3], v[176:179], v[208:211], 0
	v_mfma_f32_16x16x32_bf16 v[52:55], v[172:175], v[188:191], v[52:55]
	v_mfma_f32_16x16x32_bf16 v[48:51], v[180:183], v[188:191], v[48:51]
	v_mfma_f32_16x16x32_bf16 v[36:39], v[172:175], v[196:199], v[36:39]
	v_mfma_f32_16x16x32_bf16 v[32:35], v[180:183], v[196:199], v[32:35]
	v_mfma_f32_16x16x32_bf16 v[20:23], v[172:175], v[204:207], v[20:23]
	v_mfma_f32_16x16x32_bf16 v[16:19], v[180:183], v[204:207], v[16:19]
	v_mfma_f32_16x16x32_bf16 v[4:7], v[172:175], v[212:215], v[4:7]
	v_mfma_f32_16x16x32_bf16 v[0:3], v[180:183], v[212:215], v[0:3]
	s_barrier
	s_add_i32 s68, 0, 0x18000
	s_add_i32 s69, 0, 0x1c000
	v_add_u32_e32 v164, s68, v148
	v_add_u32_e32 v180, s69, v148
	ds_read_b128 v[152:155], v164
	ds_read_b128 v[156:159], v164 offset:1024
	ds_read_b128 v[160:163], v164 offset:2048
	ds_read_b128 v[164:167], v164 offset:3072
	ds_read_b128 v[168:171], v180
	ds_read_b128 v[172:175], v180 offset:1024
	ds_read_b128 v[176:179], v180 offset:2048
	ds_read_b128 v[180:183], v180 offset:3072
	s_add_u32 s50, s50, 0x40000
	s_addc_u32 s51, s51, 0
	s_mov_b32 m0, s55
	v_lshl_add_u64 v[222:223], s[50:51], 0, v[136:137]
	ds_read_b128 v[184:187], v151 offset:32768
	ds_read_b128 v[188:191], v151 offset:33792
	ds_read_b128 v[192:195], v151 offset:34816
	ds_read_b128 v[196:199], v151 offset:35840
	ds_read_b128 v[200:203], v151 offset:36864
	ds_read_b128 v[204:207], v151 offset:37888
	ds_read_b128 v[208:211], v151 offset:38912
	ds_read_b128 v[212:215], v151 offset:39936
	global_load_lds_dwordx4 v[222:223], off
	v_lshl_add_u64 v[222:223], s[50:51], 0, v[132:133]
	s_mov_b32 m0, s56
	s_nop 0
	global_load_lds_dwordx4 v[222:223], off
	s_waitcnt vmcnt(8)
	s_waitcnt lgkmcnt(0)
	s_barrier
	v_mfma_f32_16x16x32_bf16 v[124:127], v[152:155], v[184:187], v[124:127]
	v_mfma_f32_16x16x32_bf16 v[120:123], v[160:163], v[184:187], v[120:123]
	v_mfma_f32_16x16x32_bf16 v[108:111], v[152:155], v[192:195], v[108:111]
	v_mfma_f32_16x16x32_bf16 v[104:107], v[160:163], v[192:195], v[104:107]
	v_mfma_f32_16x16x32_bf16 v[92:95], v[152:155], v[200:203], v[92:95]
	v_mfma_f32_16x16x32_bf16 v[88:91], v[160:163], v[200:203], v[88:91]
	v_mfma_f32_16x16x32_bf16 v[76:79], v[152:155], v[208:211], v[76:79]
	v_mfma_f32_16x16x32_bf16 v[72:75], v[160:163], v[208:211], v[72:75]
	v_mfma_f32_16x16x32_bf16 v[124:127], v[156:159], v[188:191], v[124:127]
	v_mfma_f32_16x16x32_bf16 v[120:123], v[164:167], v[188:191], v[120:123]
	v_mfma_f32_16x16x32_bf16 v[108:111], v[156:159], v[196:199], v[108:111]
	v_mfma_f32_16x16x32_bf16 v[104:107], v[164:167], v[196:199], v[104:107]
	v_mfma_f32_16x16x32_bf16 v[92:95], v[156:159], v[204:207], v[92:95]
	v_mfma_f32_16x16x32_bf16 v[88:91], v[164:167], v[204:207], v[88:91]
	v_mfma_f32_16x16x32_bf16 v[76:79], v[156:159], v[212:215], v[76:79]
	v_mfma_f32_16x16x32_bf16 v[72:75], v[164:167], v[212:215], v[72:75]
	v_mfma_f32_16x16x32_bf16 v[116:119], v[168:171], v[184:187], v[116:119]
	v_mfma_f32_16x16x32_bf16 v[112:115], v[176:179], v[184:187], v[112:115]
	v_mfma_f32_16x16x32_bf16 v[100:103], v[168:171], v[192:195], v[100:103]
	v_mfma_f32_16x16x32_bf16 v[96:99], v[176:179], v[192:195], v[96:99]
	v_mfma_f32_16x16x32_bf16 v[84:87], v[168:171], v[200:203], v[84:87]
	v_mfma_f32_16x16x32_bf16 v[80:83], v[176:179], v[200:203], v[80:83]
	v_mfma_f32_16x16x32_bf16 v[68:71], v[168:171], v[208:211], v[68:71]
	v_mfma_f32_16x16x32_bf16 v[64:67], v[176:179], v[208:211], v[64:67]
	v_mfma_f32_16x16x32_bf16 v[116:119], v[172:175], v[188:191], v[116:119]
	v_mfma_f32_16x16x32_bf16 v[112:115], v[180:183], v[188:191], v[112:115]
	v_mfma_f32_16x16x32_bf16 v[100:103], v[172:175], v[196:199], v[100:103]
	v_mfma_f32_16x16x32_bf16 v[96:99], v[180:183], v[196:199], v[96:99]
	v_mfma_f32_16x16x32_bf16 v[84:87], v[172:175], v[204:207], v[84:87]
	v_mfma_f32_16x16x32_bf16 v[80:83], v[180:183], v[204:207], v[80:83]
	v_mfma_f32_16x16x32_bf16 v[68:71], v[172:175], v[212:215], v[68:71]
	v_mfma_f32_16x16x32_bf16 v[64:67], v[180:183], v[212:215], v[64:67]
	s_barrier
; #define PG8_STAGE(bufoff, gbase, voff) do { _Pragma("unroll") for (int _i = 0; _i < 2; ++_i) \
;         __builtin_amdgcn_global_load_lds((const unsigned*)((const char*)(gbase) + (voff)[_i]), (LAS unsigned*)(lds + (bufoff) + ldsw + _i * 8192), 16, 0, 0); } while (0)
; #define PG8_LDA(dst, b, h) do { _Pragma("unroll") for (int m = 0; m < 4; ++m) _Pragma("unroll") for (int k = 0; k < 2; ++k) dst[m][k] = *(const LAS bf16x8*)(lds + PG8_SA(b, h) + aoff + m * 2048 + k * 1024); } while (0)
; #define PG8_MMA(ai, bj, At, Bt) do { __builtin_amdgcn_s_setprio(1); _Pragma("unroll") for (int m = 0; m < 4; ++m) _Pragma("unroll") for (int n = 0; n < 2; ++n) _Pragma("unroll") for (int k = 0; k < 2; ++k) \
;         acc[ai][bj][m][n] = __builtin_amdgcn_mfma_f32_16x16x32_bf16(Bt[n][k], At[m][k], acc[ai][bj][m][n], 0, 0, 0); __builtin_amdgcn_s_setprio(0); } while (0)
; #define PG8_WAIT_V(n) asm volatile("s_waitcnt vmcnt(" #n ")" ::: "memory")
; #define PG8_WAIT_L(n) asm volatile("s_waitcnt lgkmcnt(" #n ")" ::: "memory")
; #define PG8_BAR __builtin_amdgcn_s_barrier()
; #define PG8_SCHED __builtin_amdgcn_sched_barrier(0)
; template <class Epi, bool SP2 = false>
; __device__ __forceinline__ void gemm_phase(LAS unsigned char* lds, const Gemm g, const StaticOrder& S, const Epi& E) {
;     ...
;         for (int t = 0; t < nt; t += 2) {
;             const bool last = (t == nt - 2);
;     ...
;             PG8_LDA(At, 1, 1); PG8_STAGE(PG8_SB(1, 0), b3, voffB); PG8_STAGE(PG8_SB(1, 1), b3 + hstepB, voffB); PG8_STAGE(PG8_SA(1, 0), a3, voffA);
;             PG8_WAIT_V(8); PG8_WAIT_L(0); PG8_BAR; PG8_MMA(1, 0, At, B0); PG8_MMA(1, 1, At, B1); PG8_BAR; PG8_SCHED;
	s_add_i32 s50, s68, s3
	v_lshl_add_u64 v[146:147], v[146:147], 0, s[12:13]
	s_mov_b32 m0, s50
	ds_read_b128 v[184:187], v151 offset:49152
	ds_read_b128 v[188:191], v151 offset:50176
	ds_read_b128 v[192:195], v151 offset:51200
	ds_read_b128 v[196:199], v151 offset:52224
	ds_read_b128 v[200:203], v151 offset:53248
	ds_read_b128 v[204:207], v151 offset:54272
	ds_read_b128 v[208:211], v151 offset:55296
	ds_read_b128 v[212:215], v151 offset:56320
	global_load_lds_dwordx4 v[146:147], off
	s_add_i32 m0, s50, 0x2000
	s_add_u32 s44, s44, 0x40080
	v_lshl_add_u64 v[146:147], v[216:217], 0, s[12:13]
	s_addc_u32 s45, s45, 0
	s_add_i32 s50, s69, s3
	global_load_lds_dwordx4 v[146:147], off
	v_lshl_add_u64 v[146:147], s[44:45], 0, v[134:135]
	s_mov_b32 m0, s50
	s_nop 0
	global_load_lds_dwordx4 v[146:147], off
	v_lshl_add_u64 v[146:147], s[44:45], 0, v[130:131]
	s_add_i32 m0, s50, 0x2000
	s_nop 0
	global_load_lds_dwordx4 v[146:147], off
	v_lshl_add_u64 v[146:147], v[218:219], 0, s[12:13]
	s_mov_b32 m0, s60
	s_nop 0
	global_load_lds_dwordx4 v[146:147], off
	v_lshl_add_u64 v[146:147], v[220:221], 0, s[12:13]
	s_mov_b32 m0, s61
	s_nop 0
	global_load_lds_dwordx4 v[146:147], off
	s_waitcnt vmcnt(8)
	s_waitcnt lgkmcnt(0)
	s_barrier
	v_mfma_f32_16x16x32_bf16 v[60:63], v[152:155], v[184:187], v[60:63]
	v_mfma_f32_16x16x32_bf16 v[56:59], v[160:163], v[184:187], v[56:59]
	v_mfma_f32_16x16x32_bf16 v[44:47], v[152:155], v[192:195], v[44:47]
	v_mfma_f32_16x16x32_bf16 v[40:43], v[160:163], v[192:195], v[40:43]
	v_mfma_f32_16x16x32_bf16 v[28:31], v[152:155], v[200:203], v[28:31]
	v_mfma_f32_16x16x32_bf16 v[24:27], v[160:163], v[200:203], v[24:27]
	v_mfma_f32_16x16x32_bf16 v[12:15], v[152:155], v[208:211], v[12:15]
	v_mfma_f32_16x16x32_bf16 v[8:11], v[160:163], v[208:211], v[8:11]
	v_mfma_f32_16x16x32_bf16 v[60:63], v[156:159], v[188:191], v[60:63]
	v_mfma_f32_16x16x32_bf16 v[56:59], v[164:167], v[188:191], v[56:59]
	v_mfma_f32_16x16x32_bf16 v[44:47], v[156:159], v[196:199], v[44:47]
	v_mfma_f32_16x16x32_bf16 v[40:43], v[164:167], v[196:199], v[40:43]
	v_mfma_f32_16x16x32_bf16 v[28:31], v[156:159], v[204:207], v[28:31]
	v_mfma_f32_16x16x32_bf16 v[24:27], v[164:167], v[204:207], v[24:27]
	v_mfma_f32_16x16x32_bf16 v[12:15], v[156:159], v[212:215], v[12:15]
	v_mfma_f32_16x16x32_bf16 v[8:11], v[164:167], v[212:215], v[8:11]
	v_mfma_f32_16x16x32_bf16 v[52:55], v[168:171], v[184:187], v[52:55]
	v_mfma_f32_16x16x32_bf16 v[48:51], v[176:179], v[184:187], v[48:51]
	v_mfma_f32_16x16x32_bf16 v[36:39], v[168:171], v[192:195], v[36:39]
	v_mfma_f32_16x16x32_bf16 v[32:35], v[176:179], v[192:195], v[32:35]
	v_mfma_f32_16x16x32_bf16 v[20:23], v[168:171], v[200:203], v[20:23]
	v_mfma_f32_16x16x32_bf16 v[16:19], v[176:179], v[200:203], v[16:19]
	v_mfma_f32_16x16x32_bf16 v[4:7], v[168:171], v[208:211], v[4:7]
	v_mfma_f32_16x16x32_bf16 v[0:3], v[176:179], v[208:211], v[0:3]
	v_mfma_f32_16x16x32_bf16 v[52:55], v[172:175], v[188:191], v[52:55]
	v_mfma_f32_16x16x32_bf16 v[48:51], v[180:183], v[188:191], v[48:51]
	v_mfma_f32_16x16x32_bf16 v[36:39], v[172:175], v[196:199], v[36:39]
	v_mfma_f32_16x16x32_bf16 v[32:35], v[180:183], v[196:199], v[32:35]
	v_mfma_f32_16x16x32_bf16 v[20:23], v[172:175], v[204:207], v[20:23]
	v_mfma_f32_16x16x32_bf16 v[16:19], v[180:183], v[204:207], v[16:19]
	v_mfma_f32_16x16x32_bf16 v[4:7], v[172:175], v[212:215], v[4:7]
	v_mfma_f32_16x16x32_bf16 v[0:3], v[180:183], v[212:215], v[0:3]
	s_barrier
	s_add_i32 s75, s75, 2
	s_add_u32 s34, s34, 0x100
	s_addc_u32 s35, s35, 0
	s_add_u32 s73, s73, 0x100
	s_addc_u32 s74, s74, 0
	s_cmp_gt_u32 s75, 13

; #define PG8_STAGE(bufoff, gbase, voff) do { _Pragma("unroll") for (int _i = 0; _i < 2; ++_i) \
;         __builtin_amdgcn_global_load_lds((const unsigned*)((const char*)(gbase) + (voff)[_i]), (LAS unsigned*)(lds + (bufoff) + ldsw + _i * 8192), 16, 0, 0); } while (0)
; #define PG8_LDA(dst, b, h) do { _Pragma("unroll") for (int m = 0; m < 4; ++m) _Pragma("unroll") for (int k = 0; k < 2; ++k) dst[m][k] = *(const LAS bf16x8*)(lds + PG8_SA(b, h) + aoff + m * 2048 + k * 1024); } while (0)
; #define PG8_LDB(dst, b, h) do { _Pragma("unroll") for (int n = 0; n < 2; ++n) _Pragma("unroll") for (int k = 0; k < 2; ++k) dst[n][k] = *(const LAS bf16x8*)(lds + PG8_SB(b, h) + boff + n * 2048 + k * 1024); } while (0)
; #define PG8_MMA(ai, bj, At, Bt) do { __builtin_amdgcn_s_setprio(1); _Pragma("unroll") for (int m = 0; m < 4; ++m) _Pragma("unroll") for (int n = 0; n < 2; ++n) _Pragma("unroll") for (int k = 0; k < 2; ++k) \
;         acc[ai][bj][m][n] = __builtin_amdgcn_mfma_f32_16x16x32_bf16(Bt[n][k], At[m][k], acc[ai][bj][m][n], 0, 0, 0); __builtin_amdgcn_s_setprio(0); } while (0)
; #define PG8_WAIT_V(n) asm volatile("s_waitcnt vmcnt(" #n ")" ::: "memory")
; #define PG8_WAIT_L(n) asm volatile("s_waitcnt lgkmcnt(" #n ")" ::: "memory")
; #define PG8_BAR __builtin_amdgcn_s_barrier()
; #define PG8_SCHED __builtin_amdgcn_sched_barrier(0)
; template <class Epi, bool SP2 = false>
; __device__ __forceinline__ void gemm_phase(LAS unsigned char* lds, const Gemm g, const StaticOrder& S, const Epi& E) {
;     ...
;         const bool has_next = S.next(ui + 1, nxt);
;         const char* nA = has_next ? (const char*)g.A + (size_t)nxt.pm * tstepA : cA; const char* nB = has_next ? (const char*)g.Bt + (size_t)nxt.pn * tstepB : cB;
;         for (int t = 0; t < nt; t += 2) {
;             const bool last = (t == nt - 2);
;             const char* a1 = cA + (size_t)(t + 1) * kstep;
;             const char* a2 = last ? nA : cA + (size_t)(t + 2) * kstep; const char* b2 = last ? nB : cB + (size_t)(t + 2) * kstep;
;             const char* a3 = a2 + kstep; const char* b3 = b2 + kstep;
;             if constexpr (SP2) {
;             PG8_LDB(B0, 0, 0); PG8_LDB(B1, 0, 1); PG8_SCHED; PG8_LDA(At, 0, 0); PG8_STAGE(PG8_SA(1, 1), a1 + hstepA, voffA);
;             PG8_WAIT_V(8); PG8_WAIT_L(0); PG8_BAR; PG8_MMA(0, 0, At, B0); PG8_MMA(0, 1, At, B1); PG8_BAR; PG8_SCHED;
.LBB0_333:
	s_add_u32 s34, s34, 0xb0080
	s_addc_u32 s35, s35, 0
	s_add_u32 s84, s52, 0x100
	s_addc_u32 s85, s53, 0
	s_mov_b32 s86, -2
	ds_read_b128 v[150:153], v147
	ds_read_b128 v[154:157], v147 offset:1024
	ds_read_b128 v[158:161], v147 offset:2048
	ds_read_b128 v[162:165], v147 offset:3072
	ds_read_b128 v[166:169], v148
	ds_read_b128 v[170:173], v148 offset:1024
	ds_read_b128 v[174:177], v148 offset:2048
	ds_read_b128 v[178:181], v148 offset:3072
	s_add_u32 s52, s34, 0xfff50080
	s_addc_u32 s53, s35, -1
	s_cmp_eq_u32 s86, 40
	s_cselect_b32 s55, s5, s53
	s_cselect_b32 s54, s4, s52
	s_cselect_b32 s53, s51, s85
	s_cselect_b32 s52, s50, s84
	v_lshl_add_u64 v[214:215], s[34:35], 0, v[138:139]
	s_add_i32 m0, s59, 0xc000
	ds_read_b128 v[182:185], v149
	ds_read_b128 v[186:189], v149 offset:1024
	ds_read_b128 v[190:193], v149 offset:2048
	ds_read_b128 v[194:197], v149 offset:3072
	ds_read_b128 v[198:201], v149 offset:4096
	ds_read_b128 v[202:205], v149 offset:5120
	ds_read_b128 v[206:209], v149 offset:6144
	ds_read_b128 v[210:213], v149 offset:7168
	global_load_lds_dwordx4 v[214:215], off
	v_lshl_add_u64 v[214:215], s[34:35], 0, v[140:141]
	s_add_i32 m0, s59, 0xe000
	s_nop 0
	global_load_lds_dwordx4 v[214:215], off
	s_waitcnt vmcnt(24)
	s_waitcnt lgkmcnt(0)
	s_barrier
	v_mfma_f32_16x16x32_bf16 v[124:127], v[150:153], v[182:185], 0
	v_mfma_f32_16x16x32_bf16 v[120:123], v[158:161], v[182:185], 0
	v_mfma_f32_16x16x32_bf16 v[116:119], v[150:153], v[190:193], 0
	v_mfma_f32_16x16x32_bf16 v[112:115], v[158:161], v[190:193], 0
	v_mfma_f32_16x16x32_bf16 v[100:103], v[150:153], v[198:201], 0
	v_mfma_f32_16x16x32_bf16 v[96:99], v[158:161], v[198:201], 0
	v_mfma_f32_16x16x32_bf16 v[84:87], v[150:153], v[206:209], 0
	v_mfma_f32_16x16x32_bf16 v[80:83], v[158:161], v[206:209], 0
	v_mfma_f32_16x16x32_bf16 v[124:127], v[154:157], v[186:189], v[124:127]
	v_mfma_f32_16x16x32_bf16 v[120:123], v[162:165], v[186:189], v[120:123]
	v_mfma_f32_16x16x32_bf16 v[116:119], v[154:157], v[194:197], v[116:119]
	v_mfma_f32_16x16x32_bf16 v[112:115], v[162:165], v[194:197], v[112:115]
	v_mfma_f32_16x16x32_bf16 v[100:103], v[154:157], v[202:205], v[100:103]
	v_mfma_f32_16x16x32_bf16 v[96:99], v[162:165], v[202:205], v[96:99]
	v_mfma_f32_16x16x32_bf16 v[84:87], v[154:157], v[210:213], v[84:87]
	v_mfma_f32_16x16x32_bf16 v[80:83], v[162:165], v[210:213], v[80:83]
	v_mfma_f32_16x16x32_bf16 v[108:111], v[166:169], v[182:185], 0
	v_mfma_f32_16x16x32_bf16 v[104:107], v[174:177], v[182:185], 0
	v_mfma_f32_16x16x32_bf16 v[92:95], v[166:169], v[190:193], 0
	v_mfma_f32_16x16x32_bf16 v[88:91], v[174:177], v[190:193], 0
	v_mfma_f32_16x16x32_bf16 v[76:79], v[166:169], v[198:201], 0
	v_mfma_f32_16x16x32_bf16 v[72:75], v[174:177], v[198:201], 0
	v_mfma_f32_16x16x32_bf16 v[68:71], v[166:169], v[206:209], 0
	v_mfma_f32_16x16x32_bf16 v[64:67], v[174:177], v[206:209], 0
	v_mfma_f32_16x16x32_bf16 v[108:111], v[170:173], v[186:189], v[108:111]
	v_mfma_f32_16x16x32_bf16 v[104:107], v[178:181], v[186:189], v[104:107]
	v_mfma_f32_16x16x32_bf16 v[92:95], v[170:173], v[194:197], v[92:95]
	v_mfma_f32_16x16x32_bf16 v[88:91], v[178:181], v[194:197], v[88:91]
	v_mfma_f32_16x16x32_bf16 v[76:79], v[170:173], v[202:205], v[76:79]
	v_mfma_f32_16x16x32_bf16 v[72:75], v[178:181], v[202:205], v[72:75]
	v_mfma_f32_16x16x32_bf16 v[68:71], v[170:173], v[210:213], v[68:71]
	v_mfma_f32_16x16x32_bf16 v[64:67], v[178:181], v[210:213], v[64:67]
	s_barrier
	s_add_i32 s68, s74, s56
	v_lshl_add_u64 v[214:215], s[52:53], 0, v[134:135]
	s_mov_b32 m0, s68
	ds_read_b128 v[182:185], v149 offset:16384
	ds_read_b128 v[186:189], v149 offset:17408
	ds_read_b128 v[190:193], v149 offset:18432
	ds_read_b128 v[194:197], v149 offset:19456
	ds_read_b128 v[198:201], v149 offset:20480
	ds_read_b128 v[202:205], v149 offset:21504
	ds_read_b128 v[206:209], v149 offset:22528
	ds_read_b128 v[210:213], v149 offset:23552
	global_load_lds_dwordx4 v[214:215], off
	s_add_i32 m0, s68, 0x2000
	s_add_u32 s68, s52, 0xb0000
	v_lshl_add_u64 v[216:217], s[52:53], 0, v[130:131]
	s_addc_u32 s69, s53, 0
	s_add_i32 s70, s75, s56
	global_load_lds_dwordx4 v[216:217], off
	v_lshl_add_u64 v[218:219], s[68:69], 0, v[134:135]
	s_mov_b32 m0, s70
	v_lshl_add_u64 v[220:221], s[54:55], 0, v[132:133]
	global_load_lds_dwordx4 v[218:219], off
	v_lshl_add_u64 v[218:219], s[68:69], 0, v[130:131]
	s_add_i32 m0, s70, 0x2000
	s_nop 0
	global_load_lds_dwordx4 v[218:219], off
	v_lshl_add_u64 v[218:219], s[54:55], 0, v[136:137]
	s_mov_b32 m0, s59
	s_nop 0
	global_load_lds_dwordx4 v[218:219], off
	s_mov_b32 m0, s60
	s_nop 0
	global_load_lds_dwordx4 v[220:221], off
	s_waitcnt vmcnt(8)
	s_waitcnt lgkmcnt(0)
	s_barrier
; #define PG8_STAGE(bufoff, gbase, voff) do { _Pragma("unroll") for (int _i = 0; _i < 2; ++_i) \
;         __builtin_amdgcn_global_load_lds((const unsigned*)((const char*)(gbase) + (voff)[_i]), (LAS unsigned*)(lds + (bufoff) + ldsw + _i * 8192), 16, 0, 0); } while (0)
; #define PG8_LDA(dst, b, h) do { _Pragma("unroll") for (int m = 0; m < 4; ++m) _Pragma("unroll") for (int k = 0; k < 2; ++k) dst[m][k] = *(const LAS bf16x8*)(lds + PG8_SA(b, h) + aoff + m * 2048 + k * 1024); } while (0)
; #define PG8_LDB(dst, b, h) do { _Pragma("unroll") for (int n = 0; n < 2; ++n) _Pragma("unroll") for (int k = 0; k < 2; ++k) dst[n][k] = *(const LAS bf16x8*)(lds + PG8_SB(b, h) + boff + n * 2048 + k * 1024); } while (0)
; #define PG8_MMA(ai, bj, At, Bt) do { __builtin_amdgcn_s_setprio(1); _Pragma("unroll") for (int m = 0; m < 4; ++m) _Pragma("unroll") for (int n = 0; n < 2; ++n) _Pragma("unroll") for (int k = 0; k < 2; ++k) \
;         acc[ai][bj][m][n] = __builtin_amdgcn_mfma_f32_16x16x32_bf16(Bt[n][k], At[m][k], acc[ai][bj][m][n], 0, 0, 0); __builtin_amdgcn_s_setprio(0); } while (0)
; #define PG8_WAIT_V(n) asm volatile("s_waitcnt vmcnt(" #n ")" ::: "memory")
; #define PG8_WAIT_L(n) asm volatile("s_waitcnt lgkmcnt(" #n ")" ::: "memory")
; #define PG8_BAR __builtin_amdgcn_s_barrier()
; #define PG8_SCHED __builtin_amdgcn_sched_barrier(0)
; template <class Epi, bool SP2 = false>
; __device__ __forceinline__ void gemm_phase(LAS unsigned char* lds, const Gemm g, const StaticOrder& S, const Epi& E) {
;     ...
;             PG8_WAIT_V(8); PG8_WAIT_L(0); PG8_BAR; PG8_MMA(1, 0, At, B0); PG8_MMA(1, 1, At, B1); PG8_BAR; PG8_SCHED;
;             PG8_LDB(B0, 1, 0); PG8_LDB(B1, 1, 1); PG8_SCHED; PG8_LDA(At, 1, 0); PG8_STAGE(PG8_SA(0, 1), a2 + hstepA, voffA);
;             PG8_WAIT_V(8); PG8_WAIT_L(0); PG8_BAR; PG8_MMA(0, 0, At, B0); PG8_MMA(0, 1, At, B1); PG8_BAR; PG8_SCHED;
	v_mfma_f32_16x16x32_bf16 v[60:63], v[150:153], v[182:185], 0
	v_mfma_f32_16x16x32_bf16 v[56:59], v[158:161], v[182:185], 0
	v_mfma_f32_16x16x32_bf16 v[52:55], v[150:153], v[190:193], 0
	v_mfma_f32_16x16x32_bf16 v[48:51], v[158:161], v[190:193], 0
	v_mfma_f32_16x16x32_bf16 v[36:39], v[150:153], v[198:201], 0
	v_mfma_f32_16x16x32_bf16 v[32:35], v[158:161], v[198:201], 0
	v_mfma_f32_16x16x32_bf16 v[20:23], v[150:153], v[206:209], 0
	v_mfma_f32_16x16x32_bf16 v[16:19], v[158:161], v[206:209], 0
	v_mfma_f32_16x16x32_bf16 v[60:63], v[154:157], v[186:189], v[60:63]
	v_mfma_f32_16x16x32_bf16 v[56:59], v[162:165], v[186:189], v[56:59]
	v_mfma_f32_16x16x32_bf16 v[52:55], v[154:157], v[194:197], v[52:55]
	v_mfma_f32_16x16x32_bf16 v[48:51], v[162:165], v[194:197], v[48:51]
	v_mfma_f32_16x16x32_bf16 v[36:39], v[154:157], v[202:205], v[36:39]
	v_mfma_f32_16x16x32_bf16 v[32:35], v[162:165], v[202:205], v[32:35]
	v_mfma_f32_16x16x32_bf16 v[20:23], v[154:157], v[210:213], v[20:23]
	v_mfma_f32_16x16x32_bf16 v[16:19], v[162:165], v[210:213], v[16:19]
	v_mfma_f32_16x16x32_bf16 v[44:47], v[166:169], v[182:185], 0
	v_mfma_f32_16x16x32_bf16 v[40:43], v[174:177], v[182:185], 0
	v_mfma_f32_16x16x32_bf16 v[28:31], v[166:169], v[190:193], 0
	v_mfma_f32_16x16x32_bf16 v[24:27], v[174:177], v[190:193], 0
	v_mfma_f32_16x16x32_bf16 v[12:15], v[166:169], v[198:201], 0
	v_mfma_f32_16x16x32_bf16 v[8:11], v[174:177], v[198:201], 0
	v_mfma_f32_16x16x32_bf16 v[4:7], v[166:169], v[206:209], 0
	v_mfma_f32_16x16x32_bf16 v[0:3], v[174:177], v[206:209], 0
	v_mfma_f32_16x16x32_bf16 v[44:47], v[170:173], v[186:189], v[44:47]
	v_mfma_f32_16x16x32_bf16 v[40:43], v[178:181], v[186:189], v[40:43]
	v_mfma_f32_16x16x32_bf16 v[28:31], v[170:173], v[194:197], v[28:31]
	v_mfma_f32_16x16x32_bf16 v[24:27], v[178:181], v[194:197], v[24:27]
	v_mfma_f32_16x16x32_bf16 v[12:15], v[170:173], v[202:205], v[12:15]
	v_mfma_f32_16x16x32_bf16 v[8:11], v[178:181], v[202:205], v[8:11]
	v_mfma_f32_16x16x32_bf16 v[4:7], v[170:173], v[210:213], v[4:7]
	v_mfma_f32_16x16x32_bf16 v[0:3], v[178:181], v[210:213], v[0:3]
	s_barrier
	s_add_i32 s68, 0, 0x18000
	s_add_i32 s69, 0, 0x1c000
	v_add_u32_e32 v162, s68, v146
	v_add_u32_e32 v178, s69, v146
	ds_read_b128 v[150:153], v162
	ds_read_b128 v[154:157], v162 offset:1024
	ds_read_b128 v[158:161], v162 offset:2048
	ds_read_b128 v[162:165], v162 offset:3072
	ds_read_b128 v[166:169], v178
	ds_read_b128 v[170:173], v178 offset:1024
	ds_read_b128 v[174:177], v178 offset:2048
	ds_read_b128 v[178:181], v178 offset:3072
	s_add_u32 s54, s54, 0xb0000
	s_addc_u32 s55, s55, 0
	s_mov_b32 m0, s61
	v_lshl_add_u64 v[222:223], s[54:55], 0, v[136:137]
	ds_read_b128 v[182:185], v149 offset:32768
	ds_read_b128 v[186:189], v149 offset:33792
	ds_read_b128 v[190:193], v149 offset:34816
	ds_read_b128 v[194:197], v149 offset:35840
	ds_read_b128 v[198:201], v149 offset:36864
	ds_read_b128 v[202:205], v149 offset:37888
	ds_read_b128 v[206:209], v149 offset:38912
	ds_read_b128 v[210:213], v149 offset:39936
	global_load_lds_dwordx4 v[222:223], off
	v_lshl_add_u64 v[222:223], s[54:55], 0, v[132:133]
	s_mov_b32 m0, s62
	s_nop 0
	global_load_lds_dwordx4 v[222:223], off
	s_waitcnt vmcnt(8)
	s_waitcnt lgkmcnt(0)
	s_barrier
	v_mfma_f32_16x16x32_bf16 v[124:127], v[150:153], v[182:185], v[124:127]
	v_mfma_f32_16x16x32_bf16 v[120:123], v[158:161], v[182:185], v[120:123]
	v_mfma_f32_16x16x32_bf16 v[116:119], v[150:153], v[190:193], v[116:119]
	v_mfma_f32_16x16x32_bf16 v[112:115], v[158:161], v[190:193], v[112:115]
	v_mfma_f32_16x16x32_bf16 v[100:103], v[150:153], v[198:201], v[100:103]
	v_mfma_f32_16x16x32_bf16 v[96:99], v[158:161], v[198:201], v[96:99]
	v_mfma_f32_16x16x32_bf16 v[84:87], v[150:153], v[206:209], v[84:87]
	v_mfma_f32_16x16x32_bf16 v[80:83], v[158:161], v[206:209], v[80:83]
	v_mfma_f32_16x16x32_bf16 v[124:127], v[154:157], v[186:189], v[124:127]
	v_mfma_f32_16x16x32_bf16 v[120:123], v[162:165], v[186:189], v[120:123]
	v_mfma_f32_16x16x32_bf16 v[116:119], v[154:157], v[194:197], v[116:119]
	v_mfma_f32_16x16x32_bf16 v[112:115], v[162:165], v[194:197], v[112:115]
	v_mfma_f32_16x16x32_bf16 v[100:103], v[154:157], v[202:205], v[100:103]
	v_mfma_f32_16x16x32_bf16 v[96:99], v[162:165], v[202:205], v[96:99]
	v_mfma_f32_16x16x32_bf16 v[84:87], v[154:157], v[210:213], v[84:87]
	v_mfma_f32_16x16x32_bf16 v[80:83], v[162:165], v[210:213], v[80:83]
	v_mfma_f32_16x16x32_bf16 v[108:111], v[166:169], v[182:185], v[108:111]
	v_mfma_f32_16x16x32_bf16 v[104:107], v[174:177], v[182:185], v[104:107]
	v_mfma_f32_16x16x32_bf16 v[92:95], v[166:169], v[190:193], v[92:95]
	v_mfma_f32_16x16x32_bf16 v[88:91], v[174:177], v[190:193], v[88:91]
	v_mfma_f32_16x16x32_bf16 v[76:79], v[166:169], v[198:201], v[76:79]
	v_mfma_f32_16x16x32_bf16 v[72:75], v[174:177], v[198:201], v[72:75]
	v_mfma_f32_16x16x32_bf16 v[68:71], v[166:169], v[206:209], v[68:71]
	v_mfma_f32_16x16x32_bf16 v[64:67], v[174:177], v[206:209], v[64:67]
	v_mfma_f32_16x16x32_bf16 v[108:111], v[170:173], v[186:189], v[108:111]
	v_mfma_f32_16x16x32_bf16 v[104:107], v[178:181], v[186:189], v[104:107]
	v_mfma_f32_16x16x32_bf16 v[92:95], v[170:173], v[194:197], v[92:95]
	v_mfma_f32_16x16x32_bf16 v[88:91], v[178:181], v[194:197], v[88:91]
	v_mfma_f32_16x16x32_bf16 v[76:79], v[170:173], v[202:205], v[76:79]
	v_mfma_f32_16x16x32_bf16 v[72:75], v[178:181], v[202:205], v[72:75]
	v_mfma_f32_16x16x32_bf16 v[68:71], v[170:173], v[210:213], v[68:71]
	v_mfma_f32_16x16x32_bf16 v[64:67], v[178:181], v[210:213], v[64:67]
	s_barrier
; #define PG8_STAGE(bufoff, gbase, voff) do { _Pragma("unroll") for (int _i = 0; _i < 2; ++_i) \
;         __builtin_amdgcn_global_load_lds((const unsigned*)((const char*)(gbase) + (voff)[_i]), (LAS unsigned*)(lds + (bufoff) + ldsw + _i * 8192), 16, 0, 0); } while (0)
; #define PG8_LDA(dst, b, h) do { _Pragma("unroll") for (int m = 0; m < 4; ++m) _Pragma("unroll") for (int k = 0; k < 2; ++k) dst[m][k] = *(const LAS bf16x8*)(lds + PG8_SA(b, h) + aoff + m * 2048 + k * 1024); } while (0)
; #define PG8_MMA(ai, bj, At, Bt) do { __builtin_amdgcn_s_setprio(1); _Pragma("unroll") for (int m = 0; m < 4; ++m) _Pragma("unroll") for (int n = 0; n < 2; ++n) _Pragma("unroll") for (int k = 0; k < 2; ++k) \
;         acc[ai][bj][m][n] = __builtin_amdgcn_mfma_f32_16x16x32_bf16(Bt[n][k], At[m][k], acc[ai][bj][m][n], 0, 0, 0); __builtin_amdgcn_s_setprio(0); } while (0)
; #define PG8_WAIT_V(n) asm volatile("s_waitcnt vmcnt(" #n ")" ::: "memory")
; #define PG8_WAIT_L(n) asm volatile("s_waitcnt lgkmcnt(" #n ")" ::: "memory")
; #define PG8_BAR __builtin_amdgcn_s_barrier()
; #define PG8_SCHED __builtin_amdgcn_sched_barrier(0)
; template <class Epi, bool SP2 = false>
; __device__ __forceinline__ void gemm_phase(LAS unsigned char* lds, const Gemm g, const StaticOrder& S, const Epi& E) {
;     ...
;         for (int t = 0; t < nt; t += 2) {
;             const bool last = (t == nt - 2);
;     ...
;             PG8_LDA(At, 1, 1); PG8_STAGE(PG8_SB(1, 0), b3, voffB); PG8_STAGE(PG8_SB(1, 1), b3 + hstepB, voffB); PG8_STAGE(PG8_SA(1, 0), a3, voffA);
;             PG8_WAIT_V(8); PG8_WAIT_L(0); PG8_BAR; PG8_MMA(1, 0, At, B0); PG8_MMA(1, 1, At, B1); PG8_BAR; PG8_SCHED;
	s_add_i32 s54, s68, s56
	v_lshl_add_u64 v[214:215], v[214:215], 0, s[24:25]
	s_mov_b32 m0, s54
	ds_read_b128 v[182:185], v149 offset:49152
	ds_read_b128 v[186:189], v149 offset:50176
	ds_read_b128 v[190:193], v149 offset:51200
	ds_read_b128 v[194:197], v149 offset:52224
	ds_read_b128 v[198:201], v149 offset:53248
	ds_read_b128 v[202:205], v149 offset:54272
	ds_read_b128 v[206:209], v149 offset:55296
	ds_read_b128 v[210:213], v149 offset:56320
	global_load_lds_dwordx4 v[214:215], off
	s_add_i32 m0, s54, 0x2000
	s_add_u32 s52, s52, 0xb0080
	v_lshl_add_u64 v[214:215], v[216:217], 0, s[24:25]
	s_addc_u32 s53, s53, 0
	s_add_i32 s54, s69, s56
	global_load_lds_dwordx4 v[214:215], off
	v_lshl_add_u64 v[214:215], s[52:53], 0, v[134:135]
	s_mov_b32 m0, s54
	s_nop 0
	global_load_lds_dwordx4 v[214:215], off
	v_lshl_add_u64 v[214:215], s[52:53], 0, v[130:131]
	s_add_i32 m0, s54, 0x2000
	s_nop 0
	global_load_lds_dwordx4 v[214:215], off
	v_lshl_add_u64 v[214:215], v[218:219], 0, s[24:25]
	s_mov_b32 m0, s66
	s_nop 0
	global_load_lds_dwordx4 v[214:215], off
	v_lshl_add_u64 v[214:215], v[220:221], 0, s[24:25]
	s_mov_b32 m0, s67
	s_nop 0
	global_load_lds_dwordx4 v[214:215], off
	s_waitcnt vmcnt(8)
	s_waitcnt lgkmcnt(0)
	s_barrier
	v_mfma_f32_16x16x32_bf16 v[60:63], v[150:153], v[182:185], v[60:63]
	v_mfma_f32_16x16x32_bf16 v[56:59], v[158:161], v[182:185], v[56:59]
	v_mfma_f32_16x16x32_bf16 v[52:55], v[150:153], v[190:193], v[52:55]
	v_mfma_f32_16x16x32_bf16 v[48:51], v[158:161], v[190:193], v[48:51]
	v_mfma_f32_16x16x32_bf16 v[36:39], v[150:153], v[198:201], v[36:39]
	v_mfma_f32_16x16x32_bf16 v[32:35], v[158:161], v[198:201], v[32:35]
	v_mfma_f32_16x16x32_bf16 v[20:23], v[150:153], v[206:209], v[20:23]
	v_mfma_f32_16x16x32_bf16 v[16:19], v[158:161], v[206:209], v[16:19]
	v_mfma_f32_16x16x32_bf16 v[60:63], v[154:157], v[186:189], v[60:63]
	v_mfma_f32_16x16x32_bf16 v[56:59], v[162:165], v[186:189], v[56:59]
	v_mfma_f32_16x16x32_bf16 v[52:55], v[154:157], v[194:197], v[52:55]
	v_mfma_f32_16x16x32_bf16 v[48:51], v[162:165], v[194:197], v[48:51]
	v_mfma_f32_16x16x32_bf16 v[36:39], v[154:157], v[202:205], v[36:39]
	v_mfma_f32_16x16x32_bf16 v[32:35], v[162:165], v[202:205], v[32:35]
	v_mfma_f32_16x16x32_bf16 v[20:23], v[154:157], v[210:213], v[20:23]
	v_mfma_f32_16x16x32_bf16 v[16:19], v[162:165], v[210:213], v[16:19]
	v_mfma_f32_16x16x32_bf16 v[44:47], v[166:169], v[182:185], v[44:47]
	v_mfma_f32_16x16x32_bf16 v[40:43], v[174:177], v[182:185], v[40:43]
	v_mfma_f32_16x16x32_bf16 v[28:31], v[166:169], v[190:193], v[28:31]
	v_mfma_f32_16x16x32_bf16 v[24:27], v[174:177], v[190:193], v[24:27]
	v_mfma_f32_16x16x32_bf16 v[12:15], v[166:169], v[198:201], v[12:15]
	v_mfma_f32_16x16x32_bf16 v[8:11], v[174:177], v[198:201], v[8:11]
	v_mfma_f32_16x16x32_bf16 v[4:7], v[166:169], v[206:209], v[4:7]
	v_mfma_f32_16x16x32_bf16 v[0:3], v[174:177], v[206:209], v[0:3]
	v_mfma_f32_16x16x32_bf16 v[44:47], v[170:173], v[186:189], v[44:47]
	v_mfma_f32_16x16x32_bf16 v[40:43], v[178:181], v[186:189], v[40:43]
	v_mfma_f32_16x16x32_bf16 v[28:31], v[170:173], v[194:197], v[28:31]
	v_mfma_f32_16x16x32_bf16 v[24:27], v[178:181], v[194:197], v[24:27]
	v_mfma_f32_16x16x32_bf16 v[12:15], v[170:173], v[202:205], v[12:15]
	v_mfma_f32_16x16x32_bf16 v[8:11], v[178:181], v[202:205], v[8:11]
	v_mfma_f32_16x16x32_bf16 v[4:7], v[170:173], v[210:213], v[4:7]
	v_mfma_f32_16x16x32_bf16 v[0:3], v[178:181], v[210:213], v[0:3]
	s_barrier
	s_add_i32 s86, s86, 2
	s_add_u32 s34, s34, 0x100
	s_addc_u32 s35, s35, 0
	s_add_u32 s84, s84, 0x100
	s_addc_u32 s85, s85, 0
	s_cmp_gt_u32 s86, 41

; #define PG8_STAGE(bufoff, gbase, voff) do { _Pragma("unroll") for (int _i = 0; _i < 2; ++_i) \
;         __builtin_amdgcn_global_load_lds((const unsigned*)((const char*)(gbase) + (voff)[_i]), (LAS unsigned*)(lds + (bufoff) + ldsw + _i * 8192), 16, 0, 0); } while (0)
; #define PG8_LDA(dst, b, h) do { _Pragma("unroll") for (int m = 0; m < 4; ++m) _Pragma("unroll") for (int k = 0; k < 2; ++k) dst[m][k] = *(const LAS bf16x8*)(lds + PG8_SA(b, h) + aoff + m * 2048 + k * 1024); } while (0)
; #define PG8_LDB(dst, b, h) do { _Pragma("unroll") for (int n = 0; n < 2; ++n) _Pragma("unroll") for (int k = 0; k < 2; ++k) dst[n][k] = *(const LAS bf16x8*)(lds + PG8_SB(b, h) + boff + n * 2048 + k * 1024); } while (0)
; #define PG8_MMA(ai, bj, At, Bt) do { __builtin_amdgcn_s_setprio(1); _Pragma("unroll") for (int m = 0; m < 4; ++m) _Pragma("unroll") for (int n = 0; n < 2; ++n) _Pragma("unroll") for (int k = 0; k < 2; ++k) \
;         acc[ai][bj][m][n] = __builtin_amdgcn_mfma_f32_16x16x32_bf16(Bt[n][k], At[m][k], acc[ai][bj][m][n], 0, 0, 0); __builtin_amdgcn_s_setprio(0); } while (0)
; #define PG8_WAIT_V(n) asm volatile("s_waitcnt vmcnt(" #n ")" ::: "memory")
; #define PG8_WAIT_L(n) asm volatile("s_waitcnt lgkmcnt(" #n ")" ::: "memory")
; #define PG8_BAR __builtin_amdgcn_s_barrier()
; #define PG8_SCHED __builtin_amdgcn_sched_barrier(0)
; template <class Epi, bool SP2 = false>
; __device__ __forceinline__ void gemm_phase(LAS unsigned char* lds, const Gemm g, const StaticOrder& S, const Epi& E) {
;     ...
;         const bool has_next = S.next(ui + 1, nxt);
;         const char* nA = has_next ? (const char*)g.A + (size_t)nxt.pm * tstepA : cA; const char* nB = has_next ? (const char*)g.Bt + (size_t)nxt.pn * tstepB : cB;
;         for (int t = 0; t < nt; t += 2) {
;             const bool last = (t == nt - 2);
;             const char* a1 = cA + (size_t)(t + 1) * kstep;
;             const char* a2 = last ? nA : cA + (size_t)(t + 2) * kstep; const char* b2 = last ? nB : cB + (size_t)(t + 2) * kstep;
;             const char* a3 = a2 + kstep; const char* b3 = b2 + kstep;
;             if constexpr (SP2) {
;             PG8_LDB(B0, 0, 0); PG8_LDB(B1, 0, 1); PG8_SCHED; PG8_LDA(At, 0, 0); PG8_STAGE(PG8_SA(1, 1), a1 + hstepA, voffA);
;             PG8_WAIT_V(8); PG8_WAIT_L(0); PG8_BAR; PG8_MMA(0, 0, At, B0); PG8_MMA(0, 1, At, B1); PG8_BAR; PG8_SCHED;
.LBB0_461:
	s_ashr_i32 s27, s26, 31
	s_lshl_b64 s[28:29], s[26:27], 19
	s_add_u32 s28, s14, s28
	s_addc_u32 s29, s15, s29
	s_and_b64 s[40:41], s[0:1], exec
	s_cselect_b32 s5, s29, s35
	s_cselect_b32 s27, s28, s34
	s_ashr_i32 s25, s24, 31
	s_lshl_b64 s[40:41], s[24:25], 19
	s_add_u32 s40, s3, s40
	s_addc_u32 s41, s52, s41
	s_and_b64 s[50:51], s[0:1], exec
	s_cselect_b32 s25, s41, s45
	s_cselect_b32 s33, s40, s44
	s_add_u32 s34, s34, 0x40080
	s_addc_u32 s35, s35, 0
	s_add_u32 s72, s44, 0x100
	s_addc_u32 s73, s45, 0
	s_mov_b32 s74, -2
	ds_read_b128 v[146:149], v153
	ds_read_b128 v[156:159], v153 offset:1024
	ds_read_b128 v[160:163], v153 offset:2048
	ds_read_b128 v[164:167], v153 offset:3072
	ds_read_b128 v[168:171], v154
	ds_read_b128 v[172:175], v154 offset:1024
	ds_read_b128 v[176:179], v154 offset:2048
	ds_read_b128 v[180:183], v154 offset:3072
	s_add_u32 s44, s34, 0xfffc0080
	s_addc_u32 s45, s35, -1
	s_cmp_eq_u32 s74, 12
	s_cselect_b32 s51, s5, s45
	s_cselect_b32 s50, s27, s44
	s_cselect_b32 s45, s25, s73
	s_cselect_b32 s44, s33, s72
	v_lshl_add_u64 v[150:151], s[34:35], 0, v[138:139]
	s_add_i32 m0, s31, 0xc000
	ds_read_b128 v[184:187], v155
	ds_read_b128 v[188:191], v155 offset:1024
	ds_read_b128 v[192:195], v155 offset:2048
	ds_read_b128 v[196:199], v155 offset:3072
	ds_read_b128 v[200:203], v155 offset:4096
	ds_read_b128 v[204:207], v155 offset:5120
	ds_read_b128 v[208:211], v155 offset:6144
	ds_read_b128 v[212:215], v155 offset:7168
	global_load_lds_dwordx4 v[150:151], off
	v_lshl_add_u64 v[150:151], s[34:35], 0, v[140:141]
	s_add_i32 m0, s31, 0xe000
	s_nop 0
	global_load_lds_dwordx4 v[150:151], off
	s_waitcnt vmcnt(24)
	s_waitcnt lgkmcnt(0)
	s_barrier
	v_mfma_f32_16x16x32_bf16 v[124:127], v[146:149], v[184:187], 0
	v_mfma_f32_16x16x32_bf16 v[120:123], v[160:163], v[184:187], 0
	v_mfma_f32_16x16x32_bf16 v[108:111], v[146:149], v[192:195], 0
	v_mfma_f32_16x16x32_bf16 v[104:107], v[160:163], v[192:195], 0
	v_mfma_f32_16x16x32_bf16 v[92:95], v[146:149], v[200:203], 0
	v_mfma_f32_16x16x32_bf16 v[88:91], v[160:163], v[200:203], 0
	v_mfma_f32_16x16x32_bf16 v[76:79], v[146:149], v[208:211], 0
	v_mfma_f32_16x16x32_bf16 v[72:75], v[160:163], v[208:211], 0
	v_mfma_f32_16x16x32_bf16 v[124:127], v[156:159], v[188:191], v[124:127]
	v_mfma_f32_16x16x32_bf16 v[120:123], v[164:167], v[188:191], v[120:123]
	v_mfma_f32_16x16x32_bf16 v[108:111], v[156:159], v[196:199], v[108:111]
	v_mfma_f32_16x16x32_bf16 v[104:107], v[164:167], v[196:199], v[104:107]
	v_mfma_f32_16x16x32_bf16 v[92:95], v[156:159], v[204:207], v[92:95]
	v_mfma_f32_16x16x32_bf16 v[88:91], v[164:167], v[204:207], v[88:91]
	v_mfma_f32_16x16x32_bf16 v[76:79], v[156:159], v[212:215], v[76:79]
	v_mfma_f32_16x16x32_bf16 v[72:75], v[164:167], v[212:215], v[72:75]
	v_mfma_f32_16x16x32_bf16 v[116:119], v[168:171], v[184:187], 0
	v_mfma_f32_16x16x32_bf16 v[112:115], v[176:179], v[184:187], 0
	v_mfma_f32_16x16x32_bf16 v[100:103], v[168:171], v[192:195], 0
	v_mfma_f32_16x16x32_bf16 v[96:99], v[176:179], v[192:195], 0
	v_mfma_f32_16x16x32_bf16 v[84:87], v[168:171], v[200:203], 0
	v_mfma_f32_16x16x32_bf16 v[80:83], v[176:179], v[200:203], 0
	v_mfma_f32_16x16x32_bf16 v[68:71], v[168:171], v[208:211], 0
	v_mfma_f32_16x16x32_bf16 v[64:67], v[176:179], v[208:211], 0
	v_mfma_f32_16x16x32_bf16 v[116:119], v[172:175], v[188:191], v[116:119]
	v_mfma_f32_16x16x32_bf16 v[112:115], v[180:183], v[188:191], v[112:115]
	v_mfma_f32_16x16x32_bf16 v[100:103], v[172:175], v[196:199], v[100:103]
	v_mfma_f32_16x16x32_bf16 v[96:99], v[180:183], v[196:199], v[96:99]
	v_mfma_f32_16x16x32_bf16 v[84:87], v[172:175], v[204:207], v[84:87]
	v_mfma_f32_16x16x32_bf16 v[80:83], v[180:183], v[204:207], v[80:83]
	v_mfma_f32_16x16x32_bf16 v[68:71], v[172:175], v[212:215], v[68:71]
	v_mfma_f32_16x16x32_bf16 v[64:67], v[180:183], v[212:215], v[64:67]
	s_barrier
	s_add_i32 s68, s66, s53
	v_lshl_add_u64 v[150:151], s[44:45], 0, v[132:133]
	s_mov_b32 m0, s68
	ds_read_b128 v[184:187], v155 offset:16384
	ds_read_b128 v[188:191], v155 offset:17408
	ds_read_b128 v[192:195], v155 offset:18432
	ds_read_b128 v[196:199], v155 offset:19456
	ds_read_b128 v[200:203], v155 offset:20480
	ds_read_b128 v[204:207], v155 offset:21504
	ds_read_b128 v[208:211], v155 offset:22528
	ds_read_b128 v[212:215], v155 offset:23552
	global_load_lds_dwordx4 v[150:151], off
	s_add_i32 m0, s68, 0x2000
	s_add_u32 s68, s44, 0x40000
	v_lshl_add_u64 v[216:217], s[44:45], 0, v[136:137]
	s_addc_u32 s69, s45, 0
	s_add_i32 s70, s67, s53
	global_load_lds_dwordx4 v[216:217], off
	v_lshl_add_u64 v[218:219], s[68:69], 0, v[132:133]
	s_mov_b32 m0, s70
	v_lshl_add_u64 v[220:221], s[50:51], 0, v[134:135]
	global_load_lds_dwordx4 v[218:219], off
	v_lshl_add_u64 v[218:219], s[68:69], 0, v[136:137]
	s_add_i32 m0, s70, 0x2000
	s_nop 0
	global_load_lds_dwordx4 v[218:219], off
	v_lshl_add_u64 v[218:219], s[50:51], 0, v[130:131]
	s_mov_b32 m0, s31
	s_nop 0
	global_load_lds_dwordx4 v[218:219], off
	s_mov_b32 m0, s54
	s_nop 0
	global_load_lds_dwordx4 v[220:221], off
	s_waitcnt vmcnt(8)
	s_waitcnt lgkmcnt(0)
	s_barrier
; #define PG8_STAGE(bufoff, gbase, voff) do { _Pragma("unroll") for (int _i = 0; _i < 2; ++_i) \
;         __builtin_amdgcn_global_load_lds((const unsigned*)((const char*)(gbase) + (voff)[_i]), (LAS unsigned*)(lds + (bufoff) + ldsw + _i * 8192), 16, 0, 0); } while (0)
; #define PG8_LDA(dst, b, h) do { _Pragma("unroll") for (int m = 0; m < 4; ++m) _Pragma("unroll") for (int k = 0; k < 2; ++k) dst[m][k] = *(const LAS bf16x8*)(lds + PG8_SA(b, h) + aoff + m * 2048 + k * 1024); } while (0)
; #define PG8_LDB(dst, b, h) do { _Pragma("unroll") for (int n = 0; n < 2; ++n) _Pragma("unroll") for (int k = 0; k < 2; ++k) dst[n][k] = *(const LAS bf16x8*)(lds + PG8_SB(b, h) + boff + n * 2048 + k * 1024); } while (0)
; #define PG8_MMA(ai, bj, At, Bt) do { __builtin_amdgcn_s_setprio(1); _Pragma("unroll") for (int m = 0; m < 4; ++m) _Pragma("unroll") for (int n = 0; n < 2; ++n) _Pragma("unroll") for (int k = 0; k < 2; ++k) \
;         acc[ai][bj][m][n] = __builtin_amdgcn_mfma_f32_16x16x32_bf16(Bt[n][k], At[m][k], acc[ai][bj][m][n], 0, 0, 0); __builtin_amdgcn_s_setprio(0); } while (0)
; #define PG8_WAIT_V(n) asm volatile("s_waitcnt vmcnt(" #n ")" ::: "memory")
; #define PG8_WAIT_L(n) asm volatile("s_waitcnt lgkmcnt(" #n ")" ::: "memory")
; #define PG8_BAR __builtin_amdgcn_s_barrier()
; #define PG8_SCHED __builtin_amdgcn_sched_barrier(0)
; template <class Epi, bool SP2 = false>
; __device__ __forceinline__ void gemm_phase(LAS unsigned char* lds, const Gemm g, const StaticOrder& S, const Epi& E) {
;     ...
;             PG8_WAIT_V(8); PG8_WAIT_L(0); PG8_BAR; PG8_MMA(1, 0, At, B0); PG8_MMA(1, 1, At, B1); PG8_BAR; PG8_SCHED;
;             PG8_LDB(B0, 1, 0); PG8_LDB(B1, 1, 1); PG8_SCHED; PG8_LDA(At, 1, 0); PG8_STAGE(PG8_SA(0, 1), a2 + hstepA, voffA);
;             PG8_WAIT_V(8); PG8_WAIT_L(0); PG8_BAR; PG8_MMA(0, 0, At, B0); PG8_MMA(0, 1, At, B1); PG8_BAR; PG8_SCHED;
	v_mfma_f32_16x16x32_bf16 v[60:63], v[146:149], v[184:187], 0
	v_mfma_f32_16x16x32_bf16 v[56:59], v[160:163], v[184:187], 0
	v_mfma_f32_16x16x32_bf16 v[44:47], v[146:149], v[192:195], 0
	v_mfma_f32_16x16x32_bf16 v[40:43], v[160:163], v[192:195], 0
	v_mfma_f32_16x16x32_bf16 v[28:31], v[146:149], v[200:203], 0
	v_mfma_f32_16x16x32_bf16 v[24:27], v[160:163], v[200:203], 0
	v_mfma_f32_16x16x32_bf16 v[12:15], v[146:149], v[208:211], 0
	v_mfma_f32_16x16x32_bf16 v[8:11], v[160:163], v[208:211], 0
	v_mfma_f32_16x16x32_bf16 v[60:63], v[156:159], v[188:191], v[60:63]
	v_mfma_f32_16x16x32_bf16 v[56:59], v[164:167], v[188:191], v[56:59]
	v_mfma_f32_16x16x32_bf16 v[44:47], v[156:159], v[196:199], v[44:47]
	v_mfma_f32_16x16x32_bf16 v[40:43], v[164:167], v[196:199], v[40:43]
	v_mfma_f32_16x16x32_bf16 v[28:31], v[156:159], v[204:207], v[28:31]
	v_mfma_f32_16x16x32_bf16 v[24:27], v[164:167], v[204:207], v[24:27]
	v_mfma_f32_16x16x32_bf16 v[12:15], v[156:159], v[212:215], v[12:15]
	v_mfma_f32_16x16x32_bf16 v[8:11], v[164:167], v[212:215], v[8:11]
	v_mfma_f32_16x16x32_bf16 v[52:55], v[168:171], v[184:187], 0
	v_mfma_f32_16x16x32_bf16 v[48:51], v[176:179], v[184:187], 0
	v_mfma_f32_16x16x32_bf16 v[36:39], v[168:171], v[192:195], 0
	v_mfma_f32_16x16x32_bf16 v[32:35], v[176:179], v[192:195], 0
	v_mfma_f32_16x16x32_bf16 v[20:23], v[168:171], v[200:203], 0
	v_mfma_f32_16x16x32_bf16 v[16:19], v[176:179], v[200:203], 0
	v_mfma_f32_16x16x32_bf16 v[4:7], v[168:171], v[208:211], 0
	v_mfma_f32_16x16x32_bf16 v[0:3], v[176:179], v[208:211], 0
	v_mfma_f32_16x16x32_bf16 v[52:55], v[172:175], v[188:191], v[52:55]
	v_mfma_f32_16x16x32_bf16 v[48:51], v[180:183], v[188:191], v[48:51]
	v_mfma_f32_16x16x32_bf16 v[36:39], v[172:175], v[196:199], v[36:39]
	v_mfma_f32_16x16x32_bf16 v[32:35], v[180:183], v[196:199], v[32:35]
	v_mfma_f32_16x16x32_bf16 v[20:23], v[172:175], v[204:207], v[20:23]
	v_mfma_f32_16x16x32_bf16 v[16:19], v[180:183], v[204:207], v[16:19]
	v_mfma_f32_16x16x32_bf16 v[4:7], v[172:175], v[212:215], v[4:7]
	v_mfma_f32_16x16x32_bf16 v[0:3], v[180:183], v[212:215], v[0:3]
	s_barrier
	s_add_i32 s68, 0, 0x18000
	s_add_i32 s69, 0, 0x1c000
	v_add_u32_e32 v164, s68, v152
	v_add_u32_e32 v180, s69, v152
	ds_read_b128 v[146:149], v164
	ds_read_b128 v[156:159], v164 offset:1024
	ds_read_b128 v[160:163], v164 offset:2048
	ds_read_b128 v[164:167], v164 offset:3072
	ds_read_b128 v[168:171], v180
	ds_read_b128 v[172:175], v180 offset:1024
	ds_read_b128 v[176:179], v180 offset:2048
	ds_read_b128 v[180:183], v180 offset:3072
	s_add_u32 s50, s50, 0x40000
	s_addc_u32 s51, s51, 0
	s_mov_b32 m0, s55
	v_lshl_add_u64 v[222:223], s[50:51], 0, v[130:131]
	ds_read_b128 v[184:187], v155 offset:32768
	ds_read_b128 v[188:191], v155 offset:33792
	ds_read_b128 v[192:195], v155 offset:34816
	ds_read_b128 v[196:199], v155 offset:35840
	ds_read_b128 v[200:203], v155 offset:36864
	ds_read_b128 v[204:207], v155 offset:37888
	ds_read_b128 v[208:211], v155 offset:38912
	ds_read_b128 v[212:215], v155 offset:39936
	global_load_lds_dwordx4 v[222:223], off
	v_lshl_add_u64 v[222:223], s[50:51], 0, v[134:135]
	s_mov_b32 m0, s56
	s_nop 0
	global_load_lds_dwordx4 v[222:223], off
	s_waitcnt vmcnt(8)
	s_waitcnt lgkmcnt(0)
	s_barrier
	v_mfma_f32_16x16x32_bf16 v[124:127], v[146:149], v[184:187], v[124:127]
	v_mfma_f32_16x16x32_bf16 v[120:123], v[160:163], v[184:187], v[120:123]
	v_mfma_f32_16x16x32_bf16 v[108:111], v[146:149], v[192:195], v[108:111]
	v_mfma_f32_16x16x32_bf16 v[104:107], v[160:163], v[192:195], v[104:107]
	v_mfma_f32_16x16x32_bf16 v[92:95], v[146:149], v[200:203], v[92:95]
	v_mfma_f32_16x16x32_bf16 v[88:91], v[160:163], v[200:203], v[88:91]
	v_mfma_f32_16x16x32_bf16 v[76:79], v[146:149], v[208:211], v[76:79]
	v_mfma_f32_16x16x32_bf16 v[72:75], v[160:163], v[208:211], v[72:75]
	v_mfma_f32_16x16x32_bf16 v[124:127], v[156:159], v[188:191], v[124:127]
	v_mfma_f32_16x16x32_bf16 v[120:123], v[164:167], v[188:191], v[120:123]
	v_mfma_f32_16x16x32_bf16 v[108:111], v[156:159], v[196:199], v[108:111]
	v_mfma_f32_16x16x32_bf16 v[104:107], v[164:167], v[196:199], v[104:107]
	v_mfma_f32_16x16x32_bf16 v[92:95], v[156:159], v[204:207], v[92:95]
	v_mfma_f32_16x16x32_bf16 v[88:91], v[164:167], v[204:207], v[88:91]
	v_mfma_f32_16x16x32_bf16 v[76:79], v[156:159], v[212:215], v[76:79]
	v_mfma_f32_16x16x32_bf16 v[72:75], v[164:167], v[212:215], v[72:75]
	v_mfma_f32_16x16x32_bf16 v[116:119], v[168:171], v[184:187], v[116:119]
	v_mfma_f32_16x16x32_bf16 v[112:115], v[176:179], v[184:187], v[112:115]
	v_mfma_f32_16x16x32_bf16 v[100:103], v[168:171], v[192:195], v[100:103]
	v_mfma_f32_16x16x32_bf16 v[96:99], v[176:179], v[192:195], v[96:99]
	v_mfma_f32_16x16x32_bf16 v[84:87], v[168:171], v[200:203], v[84:87]
	v_mfma_f32_16x16x32_bf16 v[80:83], v[176:179], v[200:203], v[80:83]
	v_mfma_f32_16x16x32_bf16 v[68:71], v[168:171], v[208:211], v[68:71]
	v_mfma_f32_16x16x32_bf16 v[64:67], v[176:179], v[208:211], v[64:67]
	v_mfma_f32_16x16x32_bf16 v[116:119], v[172:175], v[188:191], v[116:119]
	v_mfma_f32_16x16x32_bf16 v[112:115], v[180:183], v[188:191], v[112:115]
	v_mfma_f32_16x16x32_bf16 v[100:103], v[172:175], v[196:199], v[100:103]
	v_mfma_f32_16x16x32_bf16 v[96:99], v[180:183], v[196:199], v[96:99]
	v_mfma_f32_16x16x32_bf16 v[84:87], v[172:175], v[204:207], v[84:87]
	v_mfma_f32_16x16x32_bf16 v[80:83], v[180:183], v[204:207], v[80:83]
	v_mfma_f32_16x16x32_bf16 v[68:71], v[172:175], v[212:215], v[68:71]
	v_mfma_f32_16x16x32_bf16 v[64:67], v[180:183], v[212:215], v[64:67]
	s_barrier
; #define PG8_STAGE(bufoff, gbase, voff) do { _Pragma("unroll") for (int _i = 0; _i < 2; ++_i) \
;         __builtin_amdgcn_global_load_lds((const unsigned*)((const char*)(gbase) + (voff)[_i]), (LAS unsigned*)(lds + (bufoff) + ldsw + _i * 8192), 16, 0, 0); } while (0)
; #define PG8_LDA(dst, b, h) do { _Pragma("unroll") for (int m = 0; m < 4; ++m) _Pragma("unroll") for (int k = 0; k < 2; ++k) dst[m][k] = *(const LAS bf16x8*)(lds + PG8_SA(b, h) + aoff + m * 2048 + k * 1024); } while (0)
; #define PG8_MMA(ai, bj, At, Bt) do { __builtin_amdgcn_s_setprio(1); _Pragma("unroll") for (int m = 0; m < 4; ++m) _Pragma("unroll") for (int n = 0; n < 2; ++n) _Pragma("unroll") for (int k = 0; k < 2; ++k) \
;         acc[ai][bj][m][n] = __builtin_amdgcn_mfma_f32_16x16x32_bf16(Bt[n][k], At[m][k], acc[ai][bj][m][n], 0, 0, 0); __builtin_amdgcn_s_setprio(0); } while (0)
; #define PG8_WAIT_V(n) asm volatile("s_waitcnt vmcnt(" #n ")" ::: "memory")
; #define PG8_WAIT_L(n) asm volatile("s_waitcnt lgkmcnt(" #n ")" ::: "memory")
; #define PG8_BAR __builtin_amdgcn_s_barrier()
; #define PG8_SCHED __builtin_amdgcn_sched_barrier(0)
; template <class Epi, bool SP2 = false>
; __device__ __forceinline__ void gemm_phase(LAS unsigned char* lds, const Gemm g, const StaticOrder& S, const Epi& E) {
;     ...
;         for (int t = 0; t < nt; t += 2) {
;             const bool last = (t == nt - 2);
;     ...
;             PG8_LDA(At, 1, 1); PG8_STAGE(PG8_SB(1, 0), b3, voffB); PG8_STAGE(PG8_SB(1, 1), b3 + hstepB, voffB); PG8_STAGE(PG8_SA(1, 0), a3, voffA);
;             PG8_WAIT_V(8); PG8_WAIT_L(0); PG8_BAR; PG8_MMA(1, 0, At, B0); PG8_MMA(1, 1, At, B1); PG8_BAR; PG8_SCHED;
	s_add_i32 s50, s68, s53
	v_lshl_add_u64 v[150:151], v[150:151], 0, s[10:11]
	s_mov_b32 m0, s50
	ds_read_b128 v[184:187], v155 offset:49152
	ds_read_b128 v[188:191], v155 offset:50176
	ds_read_b128 v[192:195], v155 offset:51200
	ds_read_b128 v[196:199], v155 offset:52224
	ds_read_b128 v[200:203], v155 offset:53248
	ds_read_b128 v[204:207], v155 offset:54272
	ds_read_b128 v[208:211], v155 offset:55296
	ds_read_b128 v[212:215], v155 offset:56320
	global_load_lds_dwordx4 v[150:151], off
	s_add_i32 m0, s50, 0x2000
	s_add_u32 s44, s44, 0x40080
	v_lshl_add_u64 v[150:151], v[216:217], 0, s[10:11]
	s_addc_u32 s45, s45, 0
	s_add_i32 s50, s69, s53
	global_load_lds_dwordx4 v[150:151], off
	v_lshl_add_u64 v[150:151], s[44:45], 0, v[132:133]
	s_mov_b32 m0, s50
	s_nop 0
	global_load_lds_dwordx4 v[150:151], off
	v_lshl_add_u64 v[150:151], s[44:45], 0, v[136:137]
	s_add_i32 m0, s50, 0x2000
	s_nop 0
	global_load_lds_dwordx4 v[150:151], off
	v_lshl_add_u64 v[150:151], v[218:219], 0, s[10:11]
	s_mov_b32 m0, s60
	s_nop 0
	global_load_lds_dwordx4 v[150:151], off
	v_lshl_add_u64 v[150:151], v[220:221], 0, s[10:11]
	s_mov_b32 m0, s61
	s_nop 0
	global_load_lds_dwordx4 v[150:151], off
	s_waitcnt vmcnt(8)
	s_waitcnt lgkmcnt(0)
	s_barrier
	v_mfma_f32_16x16x32_bf16 v[60:63], v[146:149], v[184:187], v[60:63]
	v_mfma_f32_16x16x32_bf16 v[56:59], v[160:163], v[184:187], v[56:59]
	v_mfma_f32_16x16x32_bf16 v[44:47], v[146:149], v[192:195], v[44:47]
	v_mfma_f32_16x16x32_bf16 v[40:43], v[160:163], v[192:195], v[40:43]
	v_mfma_f32_16x16x32_bf16 v[28:31], v[146:149], v[200:203], v[28:31]
	v_mfma_f32_16x16x32_bf16 v[24:27], v[160:163], v[200:203], v[24:27]
	v_mfma_f32_16x16x32_bf16 v[12:15], v[146:149], v[208:211], v[12:15]
	v_mfma_f32_16x16x32_bf16 v[8:11], v[160:163], v[208:211], v[8:11]
	v_mfma_f32_16x16x32_bf16 v[60:63], v[156:159], v[188:191], v[60:63]
	v_mfma_f32_16x16x32_bf16 v[56:59], v[164:167], v[188:191], v[56:59]
	v_mfma_f32_16x16x32_bf16 v[44:47], v[156:159], v[196:199], v[44:47]
	v_mfma_f32_16x16x32_bf16 v[40:43], v[164:167], v[196:199], v[40:43]
	v_mfma_f32_16x16x32_bf16 v[28:31], v[156:159], v[204:207], v[28:31]
	v_mfma_f32_16x16x32_bf16 v[24:27], v[164:167], v[204:207], v[24:27]
	v_mfma_f32_16x16x32_bf16 v[12:15], v[156:159], v[212:215], v[12:15]
	v_mfma_f32_16x16x32_bf16 v[8:11], v[164:167], v[212:215], v[8:11]
	v_mfma_f32_16x16x32_bf16 v[52:55], v[168:171], v[184:187], v[52:55]
	v_mfma_f32_16x16x32_bf16 v[48:51], v[176:179], v[184:187], v[48:51]
	v_mfma_f32_16x16x32_bf16 v[36:39], v[168:171], v[192:195], v[36:39]
	v_mfma_f32_16x16x32_bf16 v[32:35], v[176:179], v[192:195], v[32:35]
	v_mfma_f32_16x16x32_bf16 v[20:23], v[168:171], v[200:203], v[20:23]
	v_mfma_f32_16x16x32_bf16 v[16:19], v[176:179], v[200:203], v[16:19]
	v_mfma_f32_16x16x32_bf16 v[4:7], v[168:171], v[208:211], v[4:7]
	v_mfma_f32_16x16x32_bf16 v[0:3], v[176:179], v[208:211], v[0:3]
	v_mfma_f32_16x16x32_bf16 v[52:55], v[172:175], v[188:191], v[52:55]
	v_mfma_f32_16x16x32_bf16 v[48:51], v[180:183], v[188:191], v[48:51]
	v_mfma_f32_16x16x32_bf16 v[36:39], v[172:175], v[196:199], v[36:39]
	v_mfma_f32_16x16x32_bf16 v[32:35], v[180:183], v[196:199], v[32:35]
	v_mfma_f32_16x16x32_bf16 v[20:23], v[172:175], v[204:207], v[20:23]
	v_mfma_f32_16x16x32_bf16 v[16:19], v[180:183], v[204:207], v[16:19]
	v_mfma_f32_16x16x32_bf16 v[4:7], v[172:175], v[212:215], v[4:7]
	v_mfma_f32_16x16x32_bf16 v[0:3], v[180:183], v[212:215], v[0:3]
	s_barrier
	s_add_i32 s74, s74, 2
	s_add_u32 s34, s34, 0x100
	s_addc_u32 s35, s35, 0
	s_add_u32 s72, s72, 0x100
	s_addc_u32 s73, s73, 0
	s_cmp_gt_u32 s74, 13

; #define PG8_STAGE(bufoff, gbase, voff) do { _Pragma("unroll") for (int _i = 0; _i < 2; ++_i) \
;         __builtin_amdgcn_global_load_lds((const unsigned*)((const char*)(gbase) + (voff)[_i]), (LAS unsigned*)(lds + (bufoff) + ldsw + _i * 8192), 16, 0, 0); } while (0)
; #define PG8_LDA(dst, b, h) do { _Pragma("unroll") for (int m = 0; m < 4; ++m) _Pragma("unroll") for (int k = 0; k < 2; ++k) dst[m][k] = *(const LAS bf16x8*)(lds + PG8_SA(b, h) + aoff + m * 2048 + k * 1024); } while (0)
; #define PG8_LDB(dst, b, h) do { _Pragma("unroll") for (int n = 0; n < 2; ++n) _Pragma("unroll") for (int k = 0; k < 2; ++k) dst[n][k] = *(const LAS bf16x8*)(lds + PG8_SB(b, h) + boff + n * 2048 + k * 1024); } while (0)
; #define PG8_MMA(ai, bj, At, Bt) do { __builtin_amdgcn_s_setprio(1); _Pragma("unroll") for (int m = 0; m < 4; ++m) _Pragma("unroll") for (int n = 0; n < 2; ++n) _Pragma("unroll") for (int k = 0; k < 2; ++k) \
;         acc[ai][bj][m][n] = __builtin_amdgcn_mfma_f32_16x16x32_bf16(Bt[n][k], At[m][k], acc[ai][bj][m][n], 0, 0, 0); __builtin_amdgcn_s_setprio(0); } while (0)
; #define PG8_WAIT_V(n) asm volatile("s_waitcnt vmcnt(" #n ")" ::: "memory")
; #define PG8_WAIT_L(n) asm volatile("s_waitcnt lgkmcnt(" #n ")" ::: "memory")
; #define PG8_BAR __builtin_amdgcn_s_barrier()
; #define PG8_SCHED __builtin_amdgcn_sched_barrier(0)
; template <class Epi, bool SP2 = false>
; __device__ __forceinline__ void gemm_phase(LAS unsigned char* lds, const Gemm g, const StaticOrder& S, const Epi& E) {
;     ...
;         const bool has_next = S.next(ui + 1, nxt);
;         const char* nA = has_next ? (const char*)g.A + (size_t)nxt.pm * tstepA : cA; const char* nB = has_next ? (const char*)g.Bt + (size_t)nxt.pn * tstepB : cB;
;         for (int t = 0; t < nt; t += 2) {
;             const bool last = (t == nt - 2);
;             const char* a1 = cA + (size_t)(t + 1) * kstep;
;             const char* a2 = last ? nA : cA + (size_t)(t + 2) * kstep; const char* b2 = last ? nB : cB + (size_t)(t + 2) * kstep;
;             const char* a3 = a2 + kstep; const char* b3 = b2 + kstep;
;             if constexpr (SP2) {
;             PG8_LDB(B0, 0, 0); PG8_LDB(B1, 0, 1); PG8_SCHED; PG8_LDA(At, 0, 0); PG8_STAGE(PG8_SA(1, 1), a1 + hstepA, voffA);
;             PG8_WAIT_V(8); PG8_WAIT_L(0); PG8_BAR; PG8_MMA(0, 0, At, B0); PG8_MMA(0, 1, At, B1); PG8_BAR; PG8_SCHED;
.LBB0_804:
	s_ashr_i32 s43, s42, 31
	s_lshl_b64 s[44:45], s[42:43], 19
	s_add_u32 s44, s14, s44
	s_addc_u32 s45, s15, s45
	s_and_b64 s[46:47], s[0:1], exec
	s_cselect_b32 s43, s45, s35
	s_cselect_b32 s76, s44, s34
	s_ashr_i32 s41, s40, 31
	s_lshl_b64 s[46:47], s[40:41], 19
	s_add_u32 s46, s3, s46
	s_addc_u32 s47, s52, s47
	s_and_b64 s[50:51], s[0:1], exec
	s_cselect_b32 s41, s47, s49
	s_cselect_b32 s77, s46, s48
	s_add_u32 s34, s34, 0x40080
	s_addc_u32 s35, s35, 0
	s_add_u32 s78, s48, 0x100
	s_addc_u32 s79, s49, 0
	s_mov_b32 s80, -2
	ds_read_b128 v[146:149], v153
	ds_read_b128 v[156:159], v153 offset:1024
	ds_read_b128 v[160:163], v153 offset:2048
	ds_read_b128 v[164:167], v153 offset:3072
	ds_read_b128 v[168:171], v154
	ds_read_b128 v[172:175], v154 offset:1024
	ds_read_b128 v[176:179], v154 offset:2048
	ds_read_b128 v[180:183], v154 offset:3072
	s_add_u32 s48, s34, 0xfffc0080
	s_addc_u32 s49, s35, -1
	s_cmp_eq_u32 s80, 12
	s_cselect_b32 s51, s43, s49
	s_cselect_b32 s50, s76, s48
	s_cselect_b32 s49, s41, s79
	s_cselect_b32 s48, s77, s78
	v_lshl_add_u64 v[150:151], s[34:35], 0, v[138:139]
	s_add_i32 m0, s31, 0xc000
	ds_read_b128 v[184:187], v155
	ds_read_b128 v[188:191], v155 offset:1024
	ds_read_b128 v[192:195], v155 offset:2048
	ds_read_b128 v[196:199], v155 offset:3072
	ds_read_b128 v[200:203], v155 offset:4096
	ds_read_b128 v[204:207], v155 offset:5120
	ds_read_b128 v[208:211], v155 offset:6144
	ds_read_b128 v[212:215], v155 offset:7168
	global_load_lds_dwordx4 v[150:151], off
	v_lshl_add_u64 v[150:151], s[34:35], 0, v[140:141]
	s_add_i32 m0, s31, 0xe000
	s_nop 0
	global_load_lds_dwordx4 v[150:151], off
	s_waitcnt vmcnt(24)
	s_waitcnt lgkmcnt(0)
	s_barrier
	v_mfma_f32_16x16x32_bf16 v[124:127], v[146:149], v[184:187], 0
	v_mfma_f32_16x16x32_bf16 v[120:123], v[160:163], v[184:187], 0
	v_mfma_f32_16x16x32_bf16 v[108:111], v[146:149], v[192:195], 0
	v_mfma_f32_16x16x32_bf16 v[104:107], v[160:163], v[192:195], 0
	v_mfma_f32_16x16x32_bf16 v[92:95], v[146:149], v[200:203], 0
	v_mfma_f32_16x16x32_bf16 v[88:91], v[160:163], v[200:203], 0
	v_mfma_f32_16x16x32_bf16 v[76:79], v[146:149], v[208:211], 0
	v_mfma_f32_16x16x32_bf16 v[72:75], v[160:163], v[208:211], 0
	v_mfma_f32_16x16x32_bf16 v[124:127], v[156:159], v[188:191], v[124:127]
	v_mfma_f32_16x16x32_bf16 v[120:123], v[164:167], v[188:191], v[120:123]
	v_mfma_f32_16x16x32_bf16 v[108:111], v[156:159], v[196:199], v[108:111]
	v_mfma_f32_16x16x32_bf16 v[104:107], v[164:167], v[196:199], v[104:107]
	v_mfma_f32_16x16x32_bf16 v[92:95], v[156:159], v[204:207], v[92:95]
	v_mfma_f32_16x16x32_bf16 v[88:91], v[164:167], v[204:207], v[88:91]
	v_mfma_f32_16x16x32_bf16 v[76:79], v[156:159], v[212:215], v[76:79]
	v_mfma_f32_16x16x32_bf16 v[72:75], v[164:167], v[212:215], v[72:75]
	v_mfma_f32_16x16x32_bf16 v[116:119], v[168:171], v[184:187], 0
	v_mfma_f32_16x16x32_bf16 v[112:115], v[176:179], v[184:187], 0
	v_mfma_f32_16x16x32_bf16 v[100:103], v[168:171], v[192:195], 0
	v_mfma_f32_16x16x32_bf16 v[96:99], v[176:179], v[192:195], 0
	v_mfma_f32_16x16x32_bf16 v[84:87], v[168:171], v[200:203], 0
	v_mfma_f32_16x16x32_bf16 v[80:83], v[176:179], v[200:203], 0
	v_mfma_f32_16x16x32_bf16 v[68:71], v[168:171], v[208:211], 0
	v_mfma_f32_16x16x32_bf16 v[64:67], v[176:179], v[208:211], 0
	v_mfma_f32_16x16x32_bf16 v[116:119], v[172:175], v[188:191], v[116:119]
	v_mfma_f32_16x16x32_bf16 v[112:115], v[180:183], v[188:191], v[112:115]
	v_mfma_f32_16x16x32_bf16 v[100:103], v[172:175], v[196:199], v[100:103]
	v_mfma_f32_16x16x32_bf16 v[96:99], v[180:183], v[196:199], v[96:99]
	v_mfma_f32_16x16x32_bf16 v[84:87], v[172:175], v[204:207], v[84:87]
	v_mfma_f32_16x16x32_bf16 v[80:83], v[180:183], v[204:207], v[80:83]
	v_mfma_f32_16x16x32_bf16 v[68:71], v[172:175], v[212:215], v[68:71]
	v_mfma_f32_16x16x32_bf16 v[64:67], v[180:183], v[212:215], v[64:67]
	s_barrier
	s_add_i32 s68, s66, s53
	v_lshl_add_u64 v[150:151], s[48:49], 0, v[134:135]
	s_mov_b32 m0, s68
	ds_read_b128 v[184:187], v155 offset:16384
	ds_read_b128 v[188:191], v155 offset:17408
	ds_read_b128 v[192:195], v155 offset:18432
	ds_read_b128 v[196:199], v155 offset:19456
	ds_read_b128 v[200:203], v155 offset:20480
	ds_read_b128 v[204:207], v155 offset:21504
	ds_read_b128 v[208:211], v155 offset:22528
	ds_read_b128 v[212:215], v155 offset:23552
	global_load_lds_dwordx4 v[150:151], off
	s_add_i32 m0, s68, 0x2000
	s_add_u32 s68, s48, 0x40000
	v_lshl_add_u64 v[216:217], s[48:49], 0, v[130:131]
	s_addc_u32 s69, s49, 0
	s_add_i32 s70, s67, s53
	global_load_lds_dwordx4 v[216:217], off
	v_lshl_add_u64 v[218:219], s[68:69], 0, v[134:135]
	s_mov_b32 m0, s70
	v_lshl_add_u64 v[220:221], s[50:51], 0, v[132:133]
	global_load_lds_dwordx4 v[218:219], off
	v_lshl_add_u64 v[218:219], s[68:69], 0, v[130:131]
	s_add_i32 m0, s70, 0x2000
	s_nop 0
	global_load_lds_dwordx4 v[218:219], off
	v_lshl_add_u64 v[218:219], s[50:51], 0, v[136:137]
	s_mov_b32 m0, s31
	s_nop 0
	global_load_lds_dwordx4 v[218:219], off
	s_mov_b32 m0, s56
	s_nop 0
	global_load_lds_dwordx4 v[220:221], off
	s_waitcnt vmcnt(8)
	s_waitcnt lgkmcnt(0)
	s_barrier
; #define PG8_STAGE(bufoff, gbase, voff) do { _Pragma("unroll") for (int _i = 0; _i < 2; ++_i) \
;         __builtin_amdgcn_global_load_lds((const unsigned*)((const char*)(gbase) + (voff)[_i]), (LAS unsigned*)(lds + (bufoff) + ldsw + _i * 8192), 16, 0, 0); } while (0)
; #define PG8_LDA(dst, b, h) do { _Pragma("unroll") for (int m = 0; m < 4; ++m) _Pragma("unroll") for (int k = 0; k < 2; ++k) dst[m][k] = *(const LAS bf16x8*)(lds + PG8_SA(b, h) + aoff + m * 2048 + k * 1024); } while (0)
; #define PG8_LDB(dst, b, h) do { _Pragma("unroll") for (int n = 0; n < 2; ++n) _Pragma("unroll") for (int k = 0; k < 2; ++k) dst[n][k] = *(const LAS bf16x8*)(lds + PG8_SB(b, h) + boff + n * 2048 + k * 1024); } while (0)
; #define PG8_MMA(ai, bj, At, Bt) do { __builtin_amdgcn_s_setprio(1); _Pragma("unroll") for (int m = 0; m < 4; ++m) _Pragma("unroll") for (int n = 0; n < 2; ++n) _Pragma("unroll") for (int k = 0; k < 2; ++k) \
;         acc[ai][bj][m][n] = __builtin_amdgcn_mfma_f32_16x16x32_bf16(Bt[n][k], At[m][k], acc[ai][bj][m][n], 0, 0, 0); __builtin_amdgcn_s_setprio(0); } while (0)
; #define PG8_WAIT_V(n) asm volatile("s_waitcnt vmcnt(" #n ")" ::: "memory")
; #define PG8_WAIT_L(n) asm volatile("s_waitcnt lgkmcnt(" #n ")" ::: "memory")
; #define PG8_BAR __builtin_amdgcn_s_barrier()
; #define PG8_SCHED __builtin_amdgcn_sched_barrier(0)
; template <class Epi, bool SP2 = false>
; __device__ __forceinline__ void gemm_phase(LAS unsigned char* lds, const Gemm g, const StaticOrder& S, const Epi& E) {
;     ...
;             PG8_WAIT_V(8); PG8_WAIT_L(0); PG8_BAR; PG8_MMA(1, 0, At, B0); PG8_MMA(1, 1, At, B1); PG8_BAR; PG8_SCHED;
;             PG8_LDB(B0, 1, 0); PG8_LDB(B1, 1, 1); PG8_SCHED; PG8_LDA(At, 1, 0); PG8_STAGE(PG8_SA(0, 1), a2 + hstepA, voffA);
;             PG8_WAIT_V(8); PG8_WAIT_L(0); PG8_BAR; PG8_MMA(0, 0, At, B0); PG8_MMA(0, 1, At, B1); PG8_BAR; PG8_SCHED;
	v_mfma_f32_16x16x32_bf16 v[60:63], v[146:149], v[184:187], 0
	v_mfma_f32_16x16x32_bf16 v[56:59], v[160:163], v[184:187], 0
	v_mfma_f32_16x16x32_bf16 v[44:47], v[146:149], v[192:195], 0
	v_mfma_f32_16x16x32_bf16 v[40:43], v[160:163], v[192:195], 0
	v_mfma_f32_16x16x32_bf16 v[28:31], v[146:149], v[200:203], 0
	v_mfma_f32_16x16x32_bf16 v[24:27], v[160:163], v[200:203], 0
	v_mfma_f32_16x16x32_bf16 v[12:15], v[146:149], v[208:211], 0
	v_mfma_f32_16x16x32_bf16 v[8:11], v[160:163], v[208:211], 0
	v_mfma_f32_16x16x32_bf16 v[60:63], v[156:159], v[188:191], v[60:63]
	v_mfma_f32_16x16x32_bf16 v[56:59], v[164:167], v[188:191], v[56:59]
	v_mfma_f32_16x16x32_bf16 v[44:47], v[156:159], v[196:199], v[44:47]
	v_mfma_f32_16x16x32_bf16 v[40:43], v[164:167], v[196:199], v[40:43]
	v_mfma_f32_16x16x32_bf16 v[28:31], v[156:159], v[204:207], v[28:31]
	v_mfma_f32_16x16x32_bf16 v[24:27], v[164:167], v[204:207], v[24:27]
	v_mfma_f32_16x16x32_bf16 v[12:15], v[156:159], v[212:215], v[12:15]
	v_mfma_f32_16x16x32_bf16 v[8:11], v[164:167], v[212:215], v[8:11]
	v_mfma_f32_16x16x32_bf16 v[52:55], v[168:171], v[184:187], 0
	v_mfma_f32_16x16x32_bf16 v[48:51], v[176:179], v[184:187], 0
	v_mfma_f32_16x16x32_bf16 v[36:39], v[168:171], v[192:195], 0
	v_mfma_f32_16x16x32_bf16 v[32:35], v[176:179], v[192:195], 0
	v_mfma_f32_16x16x32_bf16 v[20:23], v[168:171], v[200:203], 0
	v_mfma_f32_16x16x32_bf16 v[16:19], v[176:179], v[200:203], 0
	v_mfma_f32_16x16x32_bf16 v[4:7], v[168:171], v[208:211], 0
	v_mfma_f32_16x16x32_bf16 v[0:3], v[176:179], v[208:211], 0
	v_mfma_f32_16x16x32_bf16 v[52:55], v[172:175], v[188:191], v[52:55]
	v_mfma_f32_16x16x32_bf16 v[48:51], v[180:183], v[188:191], v[48:51]
	v_mfma_f32_16x16x32_bf16 v[36:39], v[172:175], v[196:199], v[36:39]
	v_mfma_f32_16x16x32_bf16 v[32:35], v[180:183], v[196:199], v[32:35]
	v_mfma_f32_16x16x32_bf16 v[20:23], v[172:175], v[204:207], v[20:23]
	v_mfma_f32_16x16x32_bf16 v[16:19], v[180:183], v[204:207], v[16:19]
	v_mfma_f32_16x16x32_bf16 v[4:7], v[172:175], v[212:215], v[4:7]
	v_mfma_f32_16x16x32_bf16 v[0:3], v[180:183], v[212:215], v[0:3]
	s_barrier
	s_add_i32 s68, 0, 0x18000
	s_add_i32 s69, 0, 0x1c000
	v_add_u32_e32 v164, s68, v152
	v_add_u32_e32 v180, s69, v152
	ds_read_b128 v[146:149], v164
	ds_read_b128 v[156:159], v164 offset:1024
	ds_read_b128 v[160:163], v164 offset:2048
	ds_read_b128 v[164:167], v164 offset:3072
	ds_read_b128 v[168:171], v180
	ds_read_b128 v[172:175], v180 offset:1024
	ds_read_b128 v[176:179], v180 offset:2048
	ds_read_b128 v[180:183], v180 offset:3072
	s_add_u32 s50, s50, 0x40000
	s_addc_u32 s51, s51, 0
	s_mov_b32 m0, s57
	v_lshl_add_u64 v[222:223], s[50:51], 0, v[136:137]
	ds_read_b128 v[184:187], v155 offset:32768
	ds_read_b128 v[188:191], v155 offset:33792
	ds_read_b128 v[192:195], v155 offset:34816
	ds_read_b128 v[196:199], v155 offset:35840
	ds_read_b128 v[200:203], v155 offset:36864
	ds_read_b128 v[204:207], v155 offset:37888
	ds_read_b128 v[208:211], v155 offset:38912
	ds_read_b128 v[212:215], v155 offset:39936
	global_load_lds_dwordx4 v[222:223], off
	v_lshl_add_u64 v[222:223], s[50:51], 0, v[132:133]
	s_mov_b32 m0, s58
	s_nop 0
	global_load_lds_dwordx4 v[222:223], off
	s_waitcnt vmcnt(8)
	s_waitcnt lgkmcnt(0)
	s_barrier
	v_mfma_f32_16x16x32_bf16 v[124:127], v[146:149], v[184:187], v[124:127]
	v_mfma_f32_16x16x32_bf16 v[120:123], v[160:163], v[184:187], v[120:123]
	v_mfma_f32_16x16x32_bf16 v[108:111], v[146:149], v[192:195], v[108:111]
	v_mfma_f32_16x16x32_bf16 v[104:107], v[160:163], v[192:195], v[104:107]
	v_mfma_f32_16x16x32_bf16 v[92:95], v[146:149], v[200:203], v[92:95]
	v_mfma_f32_16x16x32_bf16 v[88:91], v[160:163], v[200:203], v[88:91]
	v_mfma_f32_16x16x32_bf16 v[76:79], v[146:149], v[208:211], v[76:79]
	v_mfma_f32_16x16x32_bf16 v[72:75], v[160:163], v[208:211], v[72:75]
	v_mfma_f32_16x16x32_bf16 v[124:127], v[156:159], v[188:191], v[124:127]
	v_mfma_f32_16x16x32_bf16 v[120:123], v[164:167], v[188:191], v[120:123]
	v_mfma_f32_16x16x32_bf16 v[108:111], v[156:159], v[196:199], v[108:111]
	v_mfma_f32_16x16x32_bf16 v[104:107], v[164:167], v[196:199], v[104:107]
	v_mfma_f32_16x16x32_bf16 v[92:95], v[156:159], v[204:207], v[92:95]
	v_mfma_f32_16x16x32_bf16 v[88:91], v[164:167], v[204:207], v[88:91]
	v_mfma_f32_16x16x32_bf16 v[76:79], v[156:159], v[212:215], v[76:79]
	v_mfma_f32_16x16x32_bf16 v[72:75], v[164:167], v[212:215], v[72:75]
	v_mfma_f32_16x16x32_bf16 v[116:119], v[168:171], v[184:187], v[116:119]
	v_mfma_f32_16x16x32_bf16 v[112:115], v[176:179], v[184:187], v[112:115]
	v_mfma_f32_16x16x32_bf16 v[100:103], v[168:171], v[192:195], v[100:103]
	v_mfma_f32_16x16x32_bf16 v[96:99], v[176:179], v[192:195], v[96:99]
	v_mfma_f32_16x16x32_bf16 v[84:87], v[168:171], v[200:203], v[84:87]
	v_mfma_f32_16x16x32_bf16 v[80:83], v[176:179], v[200:203], v[80:83]
	v_mfma_f32_16x16x32_bf16 v[68:71], v[168:171], v[208:211], v[68:71]
	v_mfma_f32_16x16x32_bf16 v[64:67], v[176:179], v[208:211], v[64:67]
	v_mfma_f32_16x16x32_bf16 v[116:119], v[172:175], v[188:191], v[116:119]
	v_mfma_f32_16x16x32_bf16 v[112:115], v[180:183], v[188:191], v[112:115]
	v_mfma_f32_16x16x32_bf16 v[100:103], v[172:175], v[196:199], v[100:103]
	v_mfma_f32_16x16x32_bf16 v[96:99], v[180:183], v[196:199], v[96:99]
	v_mfma_f32_16x16x32_bf16 v[84:87], v[172:175], v[204:207], v[84:87]
	v_mfma_f32_16x16x32_bf16 v[80:83], v[180:183], v[204:207], v[80:83]
	v_mfma_f32_16x16x32_bf16 v[68:71], v[172:175], v[212:215], v[68:71]
	v_mfma_f32_16x16x32_bf16 v[64:67], v[180:183], v[212:215], v[64:67]
	s_barrier
; #define PG8_STAGE(bufoff, gbase, voff) do { _Pragma("unroll") for (int _i = 0; _i < 2; ++_i) \
;         __builtin_amdgcn_global_load_lds((const unsigned*)((const char*)(gbase) + (voff)[_i]), (LAS unsigned*)(lds + (bufoff) + ldsw + _i * 8192), 16, 0, 0); } while (0)
; #define PG8_LDA(dst, b, h) do { _Pragma("unroll") for (int m = 0; m < 4; ++m) _Pragma("unroll") for (int k = 0; k < 2; ++k) dst[m][k] = *(const LAS bf16x8*)(lds + PG8_SA(b, h) + aoff + m * 2048 + k * 1024); } while (0)
; #define PG8_MMA(ai, bj, At, Bt) do { __builtin_amdgcn_s_setprio(1); _Pragma("unroll") for (int m = 0; m < 4; ++m) _Pragma("unroll") for (int n = 0; n < 2; ++n) _Pragma("unroll") for (int k = 0; k < 2; ++k) \
;         acc[ai][bj][m][n] = __builtin_amdgcn_mfma_f32_16x16x32_bf16(Bt[n][k], At[m][k], acc[ai][bj][m][n], 0, 0, 0); __builtin_amdgcn_s_setprio(0); } while (0)
; #define PG8_WAIT_V(n) asm volatile("s_waitcnt vmcnt(" #n ")" ::: "memory")
; #define PG8_WAIT_L(n) asm volatile("s_waitcnt lgkmcnt(" #n ")" ::: "memory")
; #define PG8_BAR __builtin_amdgcn_s_barrier()
; #define PG8_SCHED __builtin_amdgcn_sched_barrier(0)
; template <class Epi, bool SP2 = false>
; __device__ __forceinline__ void gemm_phase(LAS unsigned char* lds, const Gemm g, const StaticOrder& S, const Epi& E) {
;     ...
;         for (int t = 0; t < nt; t += 2) {
;             const bool last = (t == nt - 2);
;     ...
;             PG8_LDA(At, 1, 1); PG8_STAGE(PG8_SB(1, 0), b3, voffB); PG8_STAGE(PG8_SB(1, 1), b3 + hstepB, voffB); PG8_STAGE(PG8_SA(1, 0), a3, voffA);
;             PG8_WAIT_V(8); PG8_WAIT_L(0); PG8_BAR; PG8_MMA(1, 0, At, B0); PG8_MMA(1, 1, At, B1); PG8_BAR; PG8_SCHED;
	s_add_i32 s50, s68, s53
	v_lshl_add_u64 v[150:151], v[150:151], 0, s[10:11]
	s_mov_b32 m0, s50
	ds_read_b128 v[184:187], v155 offset:49152
	ds_read_b128 v[188:191], v155 offset:50176
	ds_read_b128 v[192:195], v155 offset:51200
	ds_read_b128 v[196:199], v155 offset:52224
	ds_read_b128 v[200:203], v155 offset:53248
	ds_read_b128 v[204:207], v155 offset:54272
	ds_read_b128 v[208:211], v155 offset:55296
	ds_read_b128 v[212:215], v155 offset:56320
	global_load_lds_dwordx4 v[150:151], off
	s_add_i32 m0, s50, 0x2000
	s_add_u32 s48, s48, 0x40080
	v_lshl_add_u64 v[150:151], v[216:217], 0, s[10:11]
	s_addc_u32 s49, s49, 0
	s_add_i32 s50, s69, s53
	global_load_lds_dwordx4 v[150:151], off
	v_lshl_add_u64 v[150:151], s[48:49], 0, v[134:135]
	s_mov_b32 m0, s50
	s_nop 0
	global_load_lds_dwordx4 v[150:151], off
	v_lshl_add_u64 v[150:151], s[48:49], 0, v[130:131]
	s_add_i32 m0, s50, 0x2000
	s_nop 0
	global_load_lds_dwordx4 v[150:151], off
	v_lshl_add_u64 v[150:151], v[218:219], 0, s[10:11]
	s_mov_b32 m0, s62
	s_nop 0
	global_load_lds_dwordx4 v[150:151], off
	v_lshl_add_u64 v[150:151], v[220:221], 0, s[10:11]
	s_mov_b32 m0, s63
	s_nop 0
	global_load_lds_dwordx4 v[150:151], off
	s_waitcnt vmcnt(8)
	s_waitcnt lgkmcnt(0)
	s_barrier
	v_mfma_f32_16x16x32_bf16 v[60:63], v[146:149], v[184:187], v[60:63]
	v_mfma_f32_16x16x32_bf16 v[56:59], v[160:163], v[184:187], v[56:59]
	v_mfma_f32_16x16x32_bf16 v[44:47], v[146:149], v[192:195], v[44:47]
	v_mfma_f32_16x16x32_bf16 v[40:43], v[160:163], v[192:195], v[40:43]
	v_mfma_f32_16x16x32_bf16 v[28:31], v[146:149], v[200:203], v[28:31]
	v_mfma_f32_16x16x32_bf16 v[24:27], v[160:163], v[200:203], v[24:27]
	v_mfma_f32_16x16x32_bf16 v[12:15], v[146:149], v[208:211], v[12:15]
	v_mfma_f32_16x16x32_bf16 v[8:11], v[160:163], v[208:211], v[8:11]
	v_mfma_f32_16x16x32_bf16 v[60:63], v[156:159], v[188:191], v[60:63]
	v_mfma_f32_16x16x32_bf16 v[56:59], v[164:167], v[188:191], v[56:59]
	v_mfma_f32_16x16x32_bf16 v[44:47], v[156:159], v[196:199], v[44:47]
	v_mfma_f32_16x16x32_bf16 v[40:43], v[164:167], v[196:199], v[40:43]
	v_mfma_f32_16x16x32_bf16 v[28:31], v[156:159], v[204:207], v[28:31]
	v_mfma_f32_16x16x32_bf16 v[24:27], v[164:167], v[204:207], v[24:27]
	v_mfma_f32_16x16x32_bf16 v[12:15], v[156:159], v[212:215], v[12:15]
	v_mfma_f32_16x16x32_bf16 v[8:11], v[164:167], v[212:215], v[8:11]
	v_mfma_f32_16x16x32_bf16 v[52:55], v[168:171], v[184:187], v[52:55]
	v_mfma_f32_16x16x32_bf16 v[48:51], v[176:179], v[184:187], v[48:51]
	v_mfma_f32_16x16x32_bf16 v[36:39], v[168:171], v[192:195], v[36:39]
	v_mfma_f32_16x16x32_bf16 v[32:35], v[176:179], v[192:195], v[32:35]
	v_mfma_f32_16x16x32_bf16 v[20:23], v[168:171], v[200:203], v[20:23]
	v_mfma_f32_16x16x32_bf16 v[16:19], v[176:179], v[200:203], v[16:19]
	v_mfma_f32_16x16x32_bf16 v[4:7], v[168:171], v[208:211], v[4:7]
	v_mfma_f32_16x16x32_bf16 v[0:3], v[176:179], v[208:211], v[0:3]
	v_mfma_f32_16x16x32_bf16 v[52:55], v[172:175], v[188:191], v[52:55]
	v_mfma_f32_16x16x32_bf16 v[48:51], v[180:183], v[188:191], v[48:51]
	v_mfma_f32_16x16x32_bf16 v[36:39], v[172:175], v[196:199], v[36:39]
	v_mfma_f32_16x16x32_bf16 v[32:35], v[180:183], v[196:199], v[32:35]
	v_mfma_f32_16x16x32_bf16 v[20:23], v[172:175], v[204:207], v[20:23]
	v_mfma_f32_16x16x32_bf16 v[16:19], v[180:183], v[204:207], v[16:19]
	v_mfma_f32_16x16x32_bf16 v[4:7], v[172:175], v[212:215], v[4:7]
	v_mfma_f32_16x16x32_bf16 v[0:3], v[180:183], v[212:215], v[0:3]
	s_barrier
	s_add_i32 s80, s80, 2
	s_add_u32 s34, s34, 0x100
	s_addc_u32 s35, s35, 0
	s_add_u32 s78, s78, 0x100
	s_addc_u32 s79, s79, 0
	s_cmp_gt_u32 s80, 13

; #define PG8_STAGE(bufoff, gbase, voff) do { _Pragma("unroll") for (int _i = 0; _i < 2; ++_i) \
;         __builtin_amdgcn_global_load_lds((const unsigned*)((const char*)(gbase) + (voff)[_i]), (LAS unsigned*)(lds + (bufoff) + ldsw + _i * 8192), 16, 0, 0); } while (0)
; #define PG8_LDA(dst, b, h) do { _Pragma("unroll") for (int m = 0; m < 4; ++m) _Pragma("unroll") for (int k = 0; k < 2; ++k) dst[m][k] = *(const LAS bf16x8*)(lds + PG8_SA(b, h) + aoff + m * 2048 + k * 1024); } while (0)
; #define PG8_LDB(dst, b, h) do { _Pragma("unroll") for (int n = 0; n < 2; ++n) _Pragma("unroll") for (int k = 0; k < 2; ++k) dst[n][k] = *(const LAS bf16x8*)(lds + PG8_SB(b, h) + boff + n * 2048 + k * 1024); } while (0)
; #define PG8_MMA(ai, bj, At, Bt) do { __builtin_amdgcn_s_setprio(1); _Pragma("unroll") for (int m = 0; m < 4; ++m) _Pragma("unroll") for (int n = 0; n < 2; ++n) _Pragma("unroll") for (int k = 0; k < 2; ++k) \
;         acc[ai][bj][m][n] = __builtin_amdgcn_mfma_f32_16x16x32_bf16(Bt[n][k], At[m][k], acc[ai][bj][m][n], 0, 0, 0); __builtin_amdgcn_s_setprio(0); } while (0)
; #define PG8_WAIT_V(n) asm volatile("s_waitcnt vmcnt(" #n ")" ::: "memory")
; #define PG8_WAIT_L(n) asm volatile("s_waitcnt lgkmcnt(" #n ")" ::: "memory")
; #define PG8_BAR __builtin_amdgcn_s_barrier()
; #define PG8_SCHED __builtin_amdgcn_sched_barrier(0)
; template <class Epi, bool SP2 = false>
; __device__ __forceinline__ void gemm_phase(LAS unsigned char* lds, const Gemm g, const StaticOrder& S, const Epi& E) {
;     ...
;         const bool has_next = S.next(ui + 1, nxt);
;         const char* nA = has_next ? (const char*)g.A + (size_t)nxt.pm * tstepA : cA; const char* nB = has_next ? (const char*)g.Bt + (size_t)nxt.pn * tstepB : cB;
;         for (int t = 0; t < nt; t += 2) {
;             const bool last = (t == nt - 2);
;             const char* a1 = cA + (size_t)(t + 1) * kstep;
;             const char* a2 = last ? nA : cA + (size_t)(t + 2) * kstep; const char* b2 = last ? nB : cB + (size_t)(t + 2) * kstep;
;             const char* a3 = a2 + kstep; const char* b3 = b2 + kstep;
;             if constexpr (SP2) {
;             PG8_LDB(B0, 0, 0); PG8_LDB(B1, 0, 1); PG8_SCHED; PG8_LDA(At, 0, 0); PG8_STAGE(PG8_SA(1, 1), a1 + hstepA, voffA);
;             PG8_WAIT_V(8); PG8_WAIT_L(0); PG8_BAR; PG8_MMA(0, 0, At, B0); PG8_MMA(0, 1, At, B1); PG8_BAR; PG8_SCHED;
.LBB0_871:
	s_ashr_i32 s45, s44, 31
	s_lshl_b64 s[46:47], s[44:45], 18
	s_add_u32 s46, s16, s46
	s_addc_u32 s47, s17, s47
	s_and_b64 s[48:49], s[0:1], exec
	s_cselect_b32 s45, s47, s35
	s_cselect_b32 s78, s46, s34
	s_ashr_i32 s43, s42, 31
	s_lshl_b64 s[48:49], s[42:43], 18
	s_add_u32 s48, s3, s48
	s_addc_u32 s49, s54, s49
	s_and_b64 s[52:53], s[0:1], exec
	s_cselect_b32 s43, s49, s51
	s_cselect_b32 s79, s48, s50
	s_add_u32 s34, s34, 0x20080
	s_addc_u32 s35, s35, 0
	s_add_u32 s80, s50, 0x100
	s_addc_u32 s81, s51, 0
	s_mov_b32 s82, -2
	s_waitcnt vmcnt(0)
	ds_read_b128 v[146:149], v166
	ds_read_b128 v[170:173], v166 offset:1024
	ds_read_b128 v[174:177], v166 offset:2048
	ds_read_b128 v[178:181], v166 offset:3072
	ds_read_b128 v[182:185], v167
	ds_read_b128 v[186:189], v167 offset:1024
	ds_read_b128 v[190:193], v167 offset:2048
	ds_read_b128 v[194:197], v167 offset:3072
	s_add_u32 s50, s34, 0xfffe0080
	s_addc_u32 s51, s35, -1
	s_cmp_eq_u32 s82, 4
	s_cselect_b32 s53, s45, s51
	s_cselect_b32 s52, s78, s50
	s_cselect_b32 s51, s43, s81
	s_cselect_b32 s50, s79, s80
	v_lshl_add_u64 v[150:151], s[34:35], 0, v[138:139]
	s_add_i32 m0, s31, 0xc000
	ds_read_b128 v[198:201], v168
	ds_read_b128 v[202:205], v168 offset:1024
	ds_read_b128 v[206:209], v168 offset:2048
	ds_read_b128 v[210:213], v168 offset:3072
	ds_read_b128 v[214:217], v168 offset:4096
	ds_read_b128 v[218:221], v168 offset:5120
	ds_read_b128 v[222:225], v168 offset:6144
	ds_read_b128 v[226:229], v168 offset:7168
	global_load_lds_dwordx4 v[150:151], off
	v_lshl_add_u64 v[150:151], s[34:35], 0, v[140:141]
	s_add_i32 m0, s31, 0xe000
	s_nop 0
	global_load_lds_dwordx4 v[150:151], off
	s_waitcnt vmcnt(24)
	s_waitcnt lgkmcnt(0)
	s_barrier
	v_mfma_f32_16x16x32_bf16 v[124:127], v[146:149], v[198:201], 0
	v_mfma_f32_16x16x32_bf16 v[120:123], v[174:177], v[198:201], 0
	v_mfma_f32_16x16x32_bf16 v[108:111], v[146:149], v[206:209], 0
	v_mfma_f32_16x16x32_bf16 v[104:107], v[174:177], v[206:209], 0
	v_mfma_f32_16x16x32_bf16 v[92:95], v[146:149], v[214:217], 0
	v_mfma_f32_16x16x32_bf16 v[88:91], v[174:177], v[214:217], 0
	v_mfma_f32_16x16x32_bf16 v[76:79], v[146:149], v[222:225], 0
	v_mfma_f32_16x16x32_bf16 v[72:75], v[174:177], v[222:225], 0
	v_mfma_f32_16x16x32_bf16 v[124:127], v[170:173], v[202:205], v[124:127]
	v_mfma_f32_16x16x32_bf16 v[120:123], v[178:181], v[202:205], v[120:123]
	v_mfma_f32_16x16x32_bf16 v[108:111], v[170:173], v[210:213], v[108:111]
	v_mfma_f32_16x16x32_bf16 v[104:107], v[178:181], v[210:213], v[104:107]
	v_mfma_f32_16x16x32_bf16 v[92:95], v[170:173], v[218:221], v[92:95]
	v_mfma_f32_16x16x32_bf16 v[88:91], v[178:181], v[218:221], v[88:91]
	v_mfma_f32_16x16x32_bf16 v[76:79], v[170:173], v[226:229], v[76:79]
	v_mfma_f32_16x16x32_bf16 v[72:75], v[178:181], v[226:229], v[72:75]
	v_mfma_f32_16x16x32_bf16 v[116:119], v[182:185], v[198:201], 0
	v_mfma_f32_16x16x32_bf16 v[112:115], v[190:193], v[198:201], 0
	v_mfma_f32_16x16x32_bf16 v[100:103], v[182:185], v[206:209], 0
	v_mfma_f32_16x16x32_bf16 v[96:99], v[190:193], v[206:209], 0
	v_mfma_f32_16x16x32_bf16 v[84:87], v[182:185], v[214:217], 0
	v_mfma_f32_16x16x32_bf16 v[80:83], v[190:193], v[214:217], 0
	v_mfma_f32_16x16x32_bf16 v[68:71], v[182:185], v[222:225], 0
	v_mfma_f32_16x16x32_bf16 v[64:67], v[190:193], v[222:225], 0
	v_mfma_f32_16x16x32_bf16 v[116:119], v[186:189], v[202:205], v[116:119]
	v_mfma_f32_16x16x32_bf16 v[112:115], v[194:197], v[202:205], v[112:115]
	v_mfma_f32_16x16x32_bf16 v[100:103], v[186:189], v[210:213], v[100:103]
	v_mfma_f32_16x16x32_bf16 v[96:99], v[194:197], v[210:213], v[96:99]
	v_mfma_f32_16x16x32_bf16 v[84:87], v[186:189], v[218:221], v[84:87]
	v_mfma_f32_16x16x32_bf16 v[80:83], v[194:197], v[218:221], v[80:83]
	v_mfma_f32_16x16x32_bf16 v[68:71], v[186:189], v[226:229], v[68:71]
	v_mfma_f32_16x16x32_bf16 v[64:67], v[194:197], v[226:229], v[64:67]
	s_barrier
	s_add_i32 s68, s72, s55
	v_lshl_add_u64 v[150:151], s[50:51], 0, v[134:135]
	s_mov_b32 m0, s68
	ds_read_b128 v[198:201], v168 offset:16384
	ds_read_b128 v[202:205], v168 offset:17408
	ds_read_b128 v[206:209], v168 offset:18432
	ds_read_b128 v[210:213], v168 offset:19456
	ds_read_b128 v[214:217], v168 offset:20480
	ds_read_b128 v[218:221], v168 offset:21504
	ds_read_b128 v[222:225], v168 offset:22528
	ds_read_b128 v[226:229], v168 offset:23552
	global_load_lds_dwordx4 v[150:151], off
	s_add_i32 m0, s68, 0x2000
	s_add_u32 s68, s50, 0x20000
	v_lshl_add_u64 v[230:231], s[50:51], 0, v[130:131]
	s_addc_u32 s69, s51, 0
	s_add_i32 s70, s73, s55
	global_load_lds_dwordx4 v[230:231], off
	v_lshl_add_u64 v[232:233], s[68:69], 0, v[134:135]
	s_mov_b32 m0, s70
	v_lshl_add_u64 v[234:235], s[52:53], 0, v[132:133]
	global_load_lds_dwordx4 v[232:233], off
	v_lshl_add_u64 v[232:233], s[68:69], 0, v[130:131]
	s_add_i32 m0, s70, 0x2000
	s_nop 0
	global_load_lds_dwordx4 v[232:233], off
	v_lshl_add_u64 v[232:233], s[52:53], 0, v[136:137]
	s_mov_b32 m0, s31
	s_nop 0
	global_load_lds_dwordx4 v[232:233], off
	s_mov_b32 m0, s58
	s_nop 0
	global_load_lds_dwordx4 v[234:235], off
	s_waitcnt vmcnt(8)
	s_waitcnt lgkmcnt(0)
	s_barrier
; #define PG8_STAGE(bufoff, gbase, voff) do { _Pragma("unroll") for (int _i = 0; _i < 2; ++_i) \
;         __builtin_amdgcn_global_load_lds((const unsigned*)((const char*)(gbase) + (voff)[_i]), (LAS unsigned*)(lds + (bufoff) + ldsw + _i * 8192), 16, 0, 0); } while (0)
; #define PG8_LDA(dst, b, h) do { _Pragma("unroll") for (int m = 0; m < 4; ++m) _Pragma("unroll") for (int k = 0; k < 2; ++k) dst[m][k] = *(const LAS bf16x8*)(lds + PG8_SA(b, h) + aoff + m * 2048 + k * 1024); } while (0)
; #define PG8_LDB(dst, b, h) do { _Pragma("unroll") for (int n = 0; n < 2; ++n) _Pragma("unroll") for (int k = 0; k < 2; ++k) dst[n][k] = *(const LAS bf16x8*)(lds + PG8_SB(b, h) + boff + n * 2048 + k * 1024); } while (0)
; #define PG8_MMA(ai, bj, At, Bt) do { __builtin_amdgcn_s_setprio(1); _Pragma("unroll") for (int m = 0; m < 4; ++m) _Pragma("unroll") for (int n = 0; n < 2; ++n) _Pragma("unroll") for (int k = 0; k < 2; ++k) \
;         acc[ai][bj][m][n] = __builtin_amdgcn_mfma_f32_16x16x32_bf16(Bt[n][k], At[m][k], acc[ai][bj][m][n], 0, 0, 0); __builtin_amdgcn_s_setprio(0); } while (0)
; #define PG8_WAIT_V(n) asm volatile("s_waitcnt vmcnt(" #n ")" ::: "memory")
; #define PG8_WAIT_L(n) asm volatile("s_waitcnt lgkmcnt(" #n ")" ::: "memory")
; #define PG8_BAR __builtin_amdgcn_s_barrier()
; #define PG8_SCHED __builtin_amdgcn_sched_barrier(0)
; template <class Epi, bool SP2 = false>
; __device__ __forceinline__ void gemm_phase(LAS unsigned char* lds, const Gemm g, const StaticOrder& S, const Epi& E) {
;     ...
;             PG8_WAIT_V(8); PG8_WAIT_L(0); PG8_BAR; PG8_MMA(1, 0, At, B0); PG8_MMA(1, 1, At, B1); PG8_BAR; PG8_SCHED;
;             PG8_LDB(B0, 1, 0); PG8_LDB(B1, 1, 1); PG8_SCHED; PG8_LDA(At, 1, 0); PG8_STAGE(PG8_SA(0, 1), a2 + hstepA, voffA);
;             PG8_WAIT_V(8); PG8_WAIT_L(0); PG8_BAR; PG8_MMA(0, 0, At, B0); PG8_MMA(0, 1, At, B1); PG8_BAR; PG8_SCHED;
	v_mfma_f32_16x16x32_bf16 v[60:63], v[146:149], v[198:201], 0
	v_mfma_f32_16x16x32_bf16 v[56:59], v[174:177], v[198:201], 0
	v_mfma_f32_16x16x32_bf16 v[44:47], v[146:149], v[206:209], 0
	v_mfma_f32_16x16x32_bf16 v[40:43], v[174:177], v[206:209], 0
	v_mfma_f32_16x16x32_bf16 v[28:31], v[146:149], v[214:217], 0
	v_mfma_f32_16x16x32_bf16 v[24:27], v[174:177], v[214:217], 0
	v_mfma_f32_16x16x32_bf16 v[12:15], v[146:149], v[222:225], 0
	v_mfma_f32_16x16x32_bf16 v[8:11], v[174:177], v[222:225], 0
	v_mfma_f32_16x16x32_bf16 v[60:63], v[170:173], v[202:205], v[60:63]
	v_mfma_f32_16x16x32_bf16 v[56:59], v[178:181], v[202:205], v[56:59]
	v_mfma_f32_16x16x32_bf16 v[44:47], v[170:173], v[210:213], v[44:47]
	v_mfma_f32_16x16x32_bf16 v[40:43], v[178:181], v[210:213], v[40:43]
	v_mfma_f32_16x16x32_bf16 v[28:31], v[170:173], v[218:221], v[28:31]
	v_mfma_f32_16x16x32_bf16 v[24:27], v[178:181], v[218:221], v[24:27]
	v_mfma_f32_16x16x32_bf16 v[12:15], v[170:173], v[226:229], v[12:15]
	v_mfma_f32_16x16x32_bf16 v[8:11], v[178:181], v[226:229], v[8:11]
	v_mfma_f32_16x16x32_bf16 v[52:55], v[182:185], v[198:201], 0
	v_mfma_f32_16x16x32_bf16 v[48:51], v[190:193], v[198:201], 0
	v_mfma_f32_16x16x32_bf16 v[36:39], v[182:185], v[206:209], 0
	v_mfma_f32_16x16x32_bf16 v[32:35], v[190:193], v[206:209], 0
	v_mfma_f32_16x16x32_bf16 v[20:23], v[182:185], v[214:217], 0
	v_mfma_f32_16x16x32_bf16 v[16:19], v[190:193], v[214:217], 0
	v_mfma_f32_16x16x32_bf16 v[4:7], v[182:185], v[222:225], 0
	v_mfma_f32_16x16x32_bf16 v[0:3], v[190:193], v[222:225], 0
	v_mfma_f32_16x16x32_bf16 v[52:55], v[186:189], v[202:205], v[52:55]
	v_mfma_f32_16x16x32_bf16 v[48:51], v[194:197], v[202:205], v[48:51]
	v_mfma_f32_16x16x32_bf16 v[36:39], v[186:189], v[210:213], v[36:39]
	v_mfma_f32_16x16x32_bf16 v[32:35], v[194:197], v[210:213], v[32:35]
	v_mfma_f32_16x16x32_bf16 v[20:23], v[186:189], v[218:221], v[20:23]
	v_mfma_f32_16x16x32_bf16 v[16:19], v[194:197], v[218:221], v[16:19]
	v_mfma_f32_16x16x32_bf16 v[4:7], v[186:189], v[226:229], v[4:7]
	v_mfma_f32_16x16x32_bf16 v[0:3], v[194:197], v[226:229], v[0:3]
	s_barrier
	s_add_i32 s68, 0, 0x18000
	v_add_u32_e32 v169, s68, v165
	s_add_i32 s69, 0, 0x1c000
	ds_read_b128 v[146:149], v169
	ds_read_b128 v[170:173], v169 offset:1024
	ds_read_b128 v[174:177], v169 offset:2048
	ds_read_b128 v[178:181], v169 offset:3072
	v_add_u32_e32 v169, s69, v165
	ds_read_b128 v[182:185], v169
	ds_read_b128 v[186:189], v169 offset:1024
	ds_read_b128 v[190:193], v169 offset:2048
	ds_read_b128 v[194:197], v169 offset:3072
	s_add_u32 s52, s52, 0x20000
	s_addc_u32 s53, s53, 0
	s_mov_b32 m0, s59
	v_lshl_add_u64 v[236:237], s[52:53], 0, v[136:137]
	ds_read_b128 v[198:201], v168 offset:32768
	ds_read_b128 v[202:205], v168 offset:33792
	ds_read_b128 v[206:209], v168 offset:34816
	ds_read_b128 v[210:213], v168 offset:35840
	ds_read_b128 v[214:217], v168 offset:36864
	ds_read_b128 v[218:221], v168 offset:37888
	ds_read_b128 v[222:225], v168 offset:38912
	ds_read_b128 v[226:229], v168 offset:39936
	global_load_lds_dwordx4 v[236:237], off
	v_lshl_add_u64 v[236:237], s[52:53], 0, v[132:133]
	s_mov_b32 m0, s60
	s_nop 0
	global_load_lds_dwordx4 v[236:237], off
	s_waitcnt vmcnt(8)
	s_waitcnt lgkmcnt(0)
	s_barrier
	v_mfma_f32_16x16x32_bf16 v[124:127], v[146:149], v[198:201], v[124:127]
	v_mfma_f32_16x16x32_bf16 v[120:123], v[174:177], v[198:201], v[120:123]
	v_mfma_f32_16x16x32_bf16 v[108:111], v[146:149], v[206:209], v[108:111]
	v_mfma_f32_16x16x32_bf16 v[104:107], v[174:177], v[206:209], v[104:107]
	v_mfma_f32_16x16x32_bf16 v[92:95], v[146:149], v[214:217], v[92:95]
	v_mfma_f32_16x16x32_bf16 v[88:91], v[174:177], v[214:217], v[88:91]
	v_mfma_f32_16x16x32_bf16 v[76:79], v[146:149], v[222:225], v[76:79]
	v_mfma_f32_16x16x32_bf16 v[72:75], v[174:177], v[222:225], v[72:75]
	v_mfma_f32_16x16x32_bf16 v[124:127], v[170:173], v[202:205], v[124:127]
	v_mfma_f32_16x16x32_bf16 v[120:123], v[178:181], v[202:205], v[120:123]
	v_mfma_f32_16x16x32_bf16 v[108:111], v[170:173], v[210:213], v[108:111]
	v_mfma_f32_16x16x32_bf16 v[104:107], v[178:181], v[210:213], v[104:107]
	v_mfma_f32_16x16x32_bf16 v[92:95], v[170:173], v[218:221], v[92:95]
	v_mfma_f32_16x16x32_bf16 v[88:91], v[178:181], v[218:221], v[88:91]
	v_mfma_f32_16x16x32_bf16 v[76:79], v[170:173], v[226:229], v[76:79]
	v_mfma_f32_16x16x32_bf16 v[72:75], v[178:181], v[226:229], v[72:75]
	v_mfma_f32_16x16x32_bf16 v[116:119], v[182:185], v[198:201], v[116:119]
	v_mfma_f32_16x16x32_bf16 v[112:115], v[190:193], v[198:201], v[112:115]
	v_mfma_f32_16x16x32_bf16 v[100:103], v[182:185], v[206:209], v[100:103]
	v_mfma_f32_16x16x32_bf16 v[96:99], v[190:193], v[206:209], v[96:99]
	v_mfma_f32_16x16x32_bf16 v[84:87], v[182:185], v[214:217], v[84:87]
	v_mfma_f32_16x16x32_bf16 v[80:83], v[190:193], v[214:217], v[80:83]
	v_mfma_f32_16x16x32_bf16 v[68:71], v[182:185], v[222:225], v[68:71]
	v_mfma_f32_16x16x32_bf16 v[64:67], v[190:193], v[222:225], v[64:67]
	v_mfma_f32_16x16x32_bf16 v[116:119], v[186:189], v[202:205], v[116:119]
	v_mfma_f32_16x16x32_bf16 v[112:115], v[194:197], v[202:205], v[112:115]
	v_mfma_f32_16x16x32_bf16 v[100:103], v[186:189], v[210:213], v[100:103]
	v_mfma_f32_16x16x32_bf16 v[96:99], v[194:197], v[210:213], v[96:99]
	v_mfma_f32_16x16x32_bf16 v[84:87], v[186:189], v[218:221], v[84:87]
	v_mfma_f32_16x16x32_bf16 v[80:83], v[194:197], v[218:221], v[80:83]
	v_mfma_f32_16x16x32_bf16 v[68:71], v[186:189], v[226:229], v[68:71]
	v_mfma_f32_16x16x32_bf16 v[64:67], v[194:197], v[226:229], v[64:67]
	s_barrier
; #define PG8_STAGE(bufoff, gbase, voff) do { _Pragma("unroll") for (int _i = 0; _i < 2; ++_i) \
;         __builtin_amdgcn_global_load_lds((const unsigned*)((const char*)(gbase) + (voff)[_i]), (LAS unsigned*)(lds + (bufoff) + ldsw + _i * 8192), 16, 0, 0); } while (0)
; #define PG8_LDA(dst, b, h) do { _Pragma("unroll") for (int m = 0; m < 4; ++m) _Pragma("unroll") for (int k = 0; k < 2; ++k) dst[m][k] = *(const LAS bf16x8*)(lds + PG8_SA(b, h) + aoff + m * 2048 + k * 1024); } while (0)
; #define PG8_MMA(ai, bj, At, Bt) do { __builtin_amdgcn_s_setprio(1); _Pragma("unroll") for (int m = 0; m < 4; ++m) _Pragma("unroll") for (int n = 0; n < 2; ++n) _Pragma("unroll") for (int k = 0; k < 2; ++k) \
;         acc[ai][bj][m][n] = __builtin_amdgcn_mfma_f32_16x16x32_bf16(Bt[n][k], At[m][k], acc[ai][bj][m][n], 0, 0, 0); __builtin_amdgcn_s_setprio(0); } while (0)
; #define PG8_WAIT_V(n) asm volatile("s_waitcnt vmcnt(" #n ")" ::: "memory")
; #define PG8_WAIT_L(n) asm volatile("s_waitcnt lgkmcnt(" #n ")" ::: "memory")
; #define PG8_BAR __builtin_amdgcn_s_barrier()
; #define PG8_SCHED __builtin_amdgcn_sched_barrier(0)
; template <class Epi, bool SP2 = false>
; __device__ __forceinline__ void gemm_phase(LAS unsigned char* lds, const Gemm g, const StaticOrder& S, const Epi& E) {
;     ...
;         for (int t = 0; t < nt; t += 2) {
;             const bool last = (t == nt - 2);
;     ...
;             PG8_LDA(At, 1, 1); PG8_STAGE(PG8_SB(1, 0), b3, voffB); PG8_STAGE(PG8_SB(1, 1), b3 + hstepB, voffB); PG8_STAGE(PG8_SA(1, 0), a3, voffA);
;             PG8_WAIT_V(8); PG8_WAIT_L(0); PG8_BAR; PG8_MMA(1, 0, At, B0); PG8_MMA(1, 1, At, B1); PG8_BAR; PG8_SCHED;
	s_add_i32 s52, s68, s55
	v_lshl_add_u64 v[150:151], v[150:151], 0, s[10:11]
	s_mov_b32 m0, s52
	ds_read_b128 v[198:201], v168 offset:49152
	ds_read_b128 v[202:205], v168 offset:50176
	ds_read_b128 v[206:209], v168 offset:51200
	ds_read_b128 v[210:213], v168 offset:52224
	ds_read_b128 v[214:217], v168 offset:53248
	ds_read_b128 v[218:221], v168 offset:54272
	ds_read_b128 v[222:225], v168 offset:55296
	ds_read_b128 v[226:229], v168 offset:56320
	global_load_lds_dwordx4 v[150:151], off
	s_add_i32 m0, s52, 0x2000
	s_add_u32 s50, s50, 0x20080
	v_lshl_add_u64 v[150:151], v[230:231], 0, s[10:11]
	s_addc_u32 s51, s51, 0
	s_add_i32 s52, s69, s55
	global_load_lds_dwordx4 v[150:151], off
	v_lshl_add_u64 v[150:151], s[50:51], 0, v[134:135]
	s_mov_b32 m0, s52
	s_nop 0
	global_load_lds_dwordx4 v[150:151], off
	v_lshl_add_u64 v[150:151], s[50:51], 0, v[130:131]
	s_add_i32 m0, s52, 0x2000
	s_nop 0
	global_load_lds_dwordx4 v[150:151], off
	v_lshl_add_u64 v[150:151], v[232:233], 0, s[10:11]
	s_mov_b32 m0, s64
	s_nop 0
	global_load_lds_dwordx4 v[150:151], off
	v_lshl_add_u64 v[150:151], v[234:235], 0, s[10:11]
	s_mov_b32 m0, s65
	s_nop 0
	global_load_lds_dwordx4 v[150:151], off
	s_waitcnt vmcnt(8)
	s_waitcnt lgkmcnt(0)
	s_barrier
	v_mfma_f32_16x16x32_bf16 v[60:63], v[146:149], v[198:201], v[60:63]
	v_mfma_f32_16x16x32_bf16 v[56:59], v[174:177], v[198:201], v[56:59]
	v_mfma_f32_16x16x32_bf16 v[44:47], v[146:149], v[206:209], v[44:47]
	v_mfma_f32_16x16x32_bf16 v[40:43], v[174:177], v[206:209], v[40:43]
	v_mfma_f32_16x16x32_bf16 v[28:31], v[146:149], v[214:217], v[28:31]
	v_mfma_f32_16x16x32_bf16 v[24:27], v[174:177], v[214:217], v[24:27]
	v_mfma_f32_16x16x32_bf16 v[12:15], v[146:149], v[222:225], v[12:15]
	v_mfma_f32_16x16x32_bf16 v[8:11], v[174:177], v[222:225], v[8:11]
	v_mfma_f32_16x16x32_bf16 v[60:63], v[170:173], v[202:205], v[60:63]
	v_mfma_f32_16x16x32_bf16 v[56:59], v[178:181], v[202:205], v[56:59]
	v_mfma_f32_16x16x32_bf16 v[44:47], v[170:173], v[210:213], v[44:47]
	v_mfma_f32_16x16x32_bf16 v[40:43], v[178:181], v[210:213], v[40:43]
	v_mfma_f32_16x16x32_bf16 v[28:31], v[170:173], v[218:221], v[28:31]
	v_mfma_f32_16x16x32_bf16 v[24:27], v[178:181], v[218:221], v[24:27]
	v_mfma_f32_16x16x32_bf16 v[12:15], v[170:173], v[226:229], v[12:15]
	v_mfma_f32_16x16x32_bf16 v[8:11], v[178:181], v[226:229], v[8:11]
	v_mfma_f32_16x16x32_bf16 v[52:55], v[182:185], v[198:201], v[52:55]
	v_mfma_f32_16x16x32_bf16 v[48:51], v[190:193], v[198:201], v[48:51]
	v_mfma_f32_16x16x32_bf16 v[36:39], v[182:185], v[206:209], v[36:39]
	v_mfma_f32_16x16x32_bf16 v[32:35], v[190:193], v[206:209], v[32:35]
	v_mfma_f32_16x16x32_bf16 v[20:23], v[182:185], v[214:217], v[20:23]
	v_mfma_f32_16x16x32_bf16 v[16:19], v[190:193], v[214:217], v[16:19]
	v_mfma_f32_16x16x32_bf16 v[4:7], v[182:185], v[222:225], v[4:7]
	v_mfma_f32_16x16x32_bf16 v[0:3], v[190:193], v[222:225], v[0:3]
	v_mfma_f32_16x16x32_bf16 v[52:55], v[186:189], v[202:205], v[52:55]
	v_mfma_f32_16x16x32_bf16 v[48:51], v[194:197], v[202:205], v[48:51]
	v_mfma_f32_16x16x32_bf16 v[36:39], v[186:189], v[210:213], v[36:39]
	v_mfma_f32_16x16x32_bf16 v[32:35], v[194:197], v[210:213], v[32:35]
	v_mfma_f32_16x16x32_bf16 v[20:23], v[186:189], v[218:221], v[20:23]
	v_mfma_f32_16x16x32_bf16 v[16:19], v[194:197], v[218:221], v[16:19]
	v_mfma_f32_16x16x32_bf16 v[4:7], v[186:189], v[226:229], v[4:7]
	v_mfma_f32_16x16x32_bf16 v[0:3], v[194:197], v[226:229], v[0:3]
	s_barrier
	s_add_i32 s82, s82, 2
	s_add_u32 s34, s34, 0x100
	s_addc_u32 s35, s35, 0
	s_add_u32 s80, s80, 0x100
	s_addc_u32 s81, s81, 0
	s_cmp_gt_u32 s82, 5

; #define PG8_STAGE(bufoff, gbase, voff) do { _Pragma("unroll") for (int _i = 0; _i < 2; ++_i) \
;         __builtin_amdgcn_global_load_lds((const unsigned*)((const char*)(gbase) + (voff)[_i]), (LAS unsigned*)(lds + (bufoff) + ldsw + _i * 8192), 16, 0, 0); } while (0)
; #define PG8_LDA(dst, b, h) do { _Pragma("unroll") for (int m = 0; m < 4; ++m) _Pragma("unroll") for (int k = 0; k < 2; ++k) dst[m][k] = *(const LAS bf16x8*)(lds + PG8_SA(b, h) + aoff + m * 2048 + k * 1024); } while (0)
; #define PG8_LDB(dst, b, h) do { _Pragma("unroll") for (int n = 0; n < 2; ++n) _Pragma("unroll") for (int k = 0; k < 2; ++k) dst[n][k] = *(const LAS bf16x8*)(lds + PG8_SB(b, h) + boff + n * 2048 + k * 1024); } while (0)
; #define PG8_MMA(ai, bj, At, Bt) do { __builtin_amdgcn_s_setprio(1); _Pragma("unroll") for (int m = 0; m < 4; ++m) _Pragma("unroll") for (int n = 0; n < 2; ++n) _Pragma("unroll") for (int k = 0; k < 2; ++k) \
;         acc[ai][bj][m][n] = __builtin_amdgcn_mfma_f32_16x16x32_bf16(Bt[n][k], At[m][k], acc[ai][bj][m][n], 0, 0, 0); __builtin_amdgcn_s_setprio(0); } while (0)
; #define PG8_WAIT_V(n) asm volatile("s_waitcnt vmcnt(" #n ")" ::: "memory")
; #define PG8_WAIT_L(n) asm volatile("s_waitcnt lgkmcnt(" #n ")" ::: "memory")
; #define PG8_BAR __builtin_amdgcn_s_barrier()
; #define PG8_SCHED __builtin_amdgcn_sched_barrier(0)
; template <class Epi, bool SP2 = false>
; __device__ __forceinline__ void gemm_phase(LAS unsigned char* lds, const Gemm g, const StaticOrder& S, const Epi& E) {
;     ...
;         const bool has_next = S.next(ui + 1, nxt);
;         const char* nA = has_next ? (const char*)g.A + (size_t)nxt.pm * tstepA : cA; const char* nB = has_next ? (const char*)g.Bt + (size_t)nxt.pn * tstepB : cB;
;         for (int t = 0; t < nt; t += 2) {
;             const bool last = (t == nt - 2);
;             const char* a1 = cA + (size_t)(t + 1) * kstep;
;             const char* a2 = last ? nA : cA + (size_t)(t + 2) * kstep; const char* b2 = last ? nB : cB + (size_t)(t + 2) * kstep;
;             const char* a3 = a2 + kstep; const char* b3 = b2 + kstep;
;             if constexpr (SP2) {
;             PG8_LDB(B0, 0, 0); PG8_LDB(B1, 0, 1); PG8_SCHED; PG8_LDA(At, 0, 0); PG8_STAGE(PG8_SA(1, 1), a1 + hstepA, voffA);
;             PG8_WAIT_V(8); PG8_WAIT_L(0); PG8_BAR; PG8_MMA(0, 0, At, B0); PG8_MMA(0, 1, At, B1); PG8_BAR; PG8_SCHED;
.LBB0_887:
	s_ashr_i32 s43, s42, 31
	s_lshl_b64 s[44:45], s[42:43], 19
	s_add_u32 s44, s26, s44
	s_addc_u32 s45, s27, s45
	s_and_b64 s[46:47], s[0:1], exec
	s_cselect_b32 s43, s45, s35
	s_cselect_b32 s72, s44, s34
	s_ashr_i32 s41, s40, 31
	s_lshl_b64 s[46:47], s[40:41], 19
	s_add_u32 s46, s3, s46
	s_addc_u32 s47, s52, s47
	s_and_b64 s[50:51], s[0:1], exec
	s_cselect_b32 s41, s47, s49
	s_cselect_b32 s73, s46, s48
	s_add_u32 s34, s34, 0x40080
	s_addc_u32 s35, s35, 0
	s_add_u32 s74, s48, 0x100
	s_addc_u32 s75, s49, 0
	s_mov_b32 s76, -2
	s_waitcnt vmcnt(0)
	ds_read_b128 v[146:149], v152
	ds_read_b128 v[156:159], v152 offset:1024
	ds_read_b128 v[160:163], v152 offset:2048
	ds_read_b128 v[164:167], v152 offset:3072
	ds_read_b128 v[168:171], v153
	ds_read_b128 v[172:175], v153 offset:1024
	ds_read_b128 v[176:179], v153 offset:2048
	ds_read_b128 v[180:183], v153 offset:3072
	s_add_u32 s48, s34, 0xfffc0080
	s_addc_u32 s49, s35, -1
	s_cmp_eq_u32 s76, 12
	s_cselect_b32 s51, s43, s49
	s_cselect_b32 s50, s72, s48
	s_cselect_b32 s49, s41, s75
	s_cselect_b32 s48, s73, s74
	v_lshl_add_u64 v[150:151], s[34:35], 0, v[138:139]
	s_add_i32 m0, s31, 0xc000
	ds_read_b128 v[184:187], v155
	ds_read_b128 v[188:191], v155 offset:1024
	ds_read_b128 v[192:195], v155 offset:2048
	ds_read_b128 v[196:199], v155 offset:3072
	ds_read_b128 v[200:203], v155 offset:4096
	ds_read_b128 v[204:207], v155 offset:5120
	ds_read_b128 v[208:211], v155 offset:6144
	ds_read_b128 v[212:215], v155 offset:7168
	global_load_lds_dwordx4 v[150:151], off
	v_lshl_add_u64 v[150:151], s[34:35], 0, v[140:141]
	s_add_i32 m0, s31, 0xe000
	s_nop 0
	global_load_lds_dwordx4 v[150:151], off
	s_waitcnt vmcnt(24)
	s_waitcnt lgkmcnt(0)
	s_barrier
	v_mfma_f32_16x16x32_bf16 v[124:127], v[146:149], v[184:187], 0
	v_mfma_f32_16x16x32_bf16 v[120:123], v[160:163], v[184:187], 0
	v_mfma_f32_16x16x32_bf16 v[108:111], v[146:149], v[192:195], 0
	v_mfma_f32_16x16x32_bf16 v[104:107], v[160:163], v[192:195], 0
	v_mfma_f32_16x16x32_bf16 v[92:95], v[146:149], v[200:203], 0
	v_mfma_f32_16x16x32_bf16 v[88:91], v[160:163], v[200:203], 0
	v_mfma_f32_16x16x32_bf16 v[76:79], v[146:149], v[208:211], 0
	v_mfma_f32_16x16x32_bf16 v[72:75], v[160:163], v[208:211], 0
	v_mfma_f32_16x16x32_bf16 v[124:127], v[156:159], v[188:191], v[124:127]
	v_mfma_f32_16x16x32_bf16 v[120:123], v[164:167], v[188:191], v[120:123]
	v_mfma_f32_16x16x32_bf16 v[108:111], v[156:159], v[196:199], v[108:111]
	v_mfma_f32_16x16x32_bf16 v[104:107], v[164:167], v[196:199], v[104:107]
	v_mfma_f32_16x16x32_bf16 v[92:95], v[156:159], v[204:207], v[92:95]
	v_mfma_f32_16x16x32_bf16 v[88:91], v[164:167], v[204:207], v[88:91]
	v_mfma_f32_16x16x32_bf16 v[76:79], v[156:159], v[212:215], v[76:79]
	v_mfma_f32_16x16x32_bf16 v[72:75], v[164:167], v[212:215], v[72:75]
	v_mfma_f32_16x16x32_bf16 v[116:119], v[168:171], v[184:187], 0
	v_mfma_f32_16x16x32_bf16 v[112:115], v[176:179], v[184:187], 0
	v_mfma_f32_16x16x32_bf16 v[100:103], v[168:171], v[192:195], 0
	v_mfma_f32_16x16x32_bf16 v[96:99], v[176:179], v[192:195], 0
	v_mfma_f32_16x16x32_bf16 v[84:87], v[168:171], v[200:203], 0
	v_mfma_f32_16x16x32_bf16 v[80:83], v[176:179], v[200:203], 0
	v_mfma_f32_16x16x32_bf16 v[68:71], v[168:171], v[208:211], 0
	v_mfma_f32_16x16x32_bf16 v[64:67], v[176:179], v[208:211], 0
	v_mfma_f32_16x16x32_bf16 v[116:119], v[172:175], v[188:191], v[116:119]
	v_mfma_f32_16x16x32_bf16 v[112:115], v[180:183], v[188:191], v[112:115]
	v_mfma_f32_16x16x32_bf16 v[100:103], v[172:175], v[196:199], v[100:103]
	v_mfma_f32_16x16x32_bf16 v[96:99], v[180:183], v[196:199], v[96:99]
	v_mfma_f32_16x16x32_bf16 v[84:87], v[172:175], v[204:207], v[84:87]
	v_mfma_f32_16x16x32_bf16 v[80:83], v[180:183], v[204:207], v[80:83]
	v_mfma_f32_16x16x32_bf16 v[68:71], v[172:175], v[212:215], v[68:71]
	v_mfma_f32_16x16x32_bf16 v[64:67], v[180:183], v[212:215], v[64:67]
	s_barrier
	s_add_i32 s68, s66, s53
	v_lshl_add_u64 v[150:151], s[48:49], 0, v[134:135]
	s_mov_b32 m0, s68
	ds_read_b128 v[184:187], v155 offset:16384
	ds_read_b128 v[188:191], v155 offset:17408
	ds_read_b128 v[192:195], v155 offset:18432
	ds_read_b128 v[196:199], v155 offset:19456
	ds_read_b128 v[200:203], v155 offset:20480
	ds_read_b128 v[204:207], v155 offset:21504
	ds_read_b128 v[208:211], v155 offset:22528
	ds_read_b128 v[212:215], v155 offset:23552
	global_load_lds_dwordx4 v[150:151], off
	s_add_i32 m0, s68, 0x2000
	s_add_u32 s68, s48, 0x40000
	v_lshl_add_u64 v[216:217], s[48:49], 0, v[130:131]
	s_addc_u32 s69, s49, 0
	s_add_i32 s70, s67, s53
	global_load_lds_dwordx4 v[216:217], off
	v_lshl_add_u64 v[218:219], s[68:69], 0, v[134:135]
	s_mov_b32 m0, s70
	v_lshl_add_u64 v[220:221], s[50:51], 0, v[132:133]
	global_load_lds_dwordx4 v[218:219], off
	v_lshl_add_u64 v[218:219], s[68:69], 0, v[130:131]
	s_add_i32 m0, s70, 0x2000
	s_nop 0
	global_load_lds_dwordx4 v[218:219], off
	v_lshl_add_u64 v[218:219], s[50:51], 0, v[136:137]
	s_mov_b32 m0, s31
	s_nop 0
	global_load_lds_dwordx4 v[218:219], off
	s_mov_b32 m0, s56
	s_nop 0
	global_load_lds_dwordx4 v[220:221], off
	s_waitcnt vmcnt(8)
	s_waitcnt lgkmcnt(0)
	s_barrier
; #define PG8_STAGE(bufoff, gbase, voff) do { _Pragma("unroll") for (int _i = 0; _i < 2; ++_i) \
;         __builtin_amdgcn_global_load_lds((const unsigned*)((const char*)(gbase) + (voff)[_i]), (LAS unsigned*)(lds + (bufoff) + ldsw + _i * 8192), 16, 0, 0); } while (0)
; #define PG8_LDA(dst, b, h) do { _Pragma("unroll") for (int m = 0; m < 4; ++m) _Pragma("unroll") for (int k = 0; k < 2; ++k) dst[m][k] = *(const LAS bf16x8*)(lds + PG8_SA(b, h) + aoff + m * 2048 + k * 1024); } while (0)
; #define PG8_LDB(dst, b, h) do { _Pragma("unroll") for (int n = 0; n < 2; ++n) _Pragma("unroll") for (int k = 0; k < 2; ++k) dst[n][k] = *(const LAS bf16x8*)(lds + PG8_SB(b, h) + boff + n * 2048 + k * 1024); } while (0)
; #define PG8_MMA(ai, bj, At, Bt) do { __builtin_amdgcn_s_setprio(1); _Pragma("unroll") for (int m = 0; m < 4; ++m) _Pragma("unroll") for (int n = 0; n < 2; ++n) _Pragma("unroll") for (int k = 0; k < 2; ++k) \
;         acc[ai][bj][m][n] = __builtin_amdgcn_mfma_f32_16x16x32_bf16(Bt[n][k], At[m][k], acc[ai][bj][m][n], 0, 0, 0); __builtin_amdgcn_s_setprio(0); } while (0)
; #define PG8_WAIT_V(n) asm volatile("s_waitcnt vmcnt(" #n ")" ::: "memory")
; #define PG8_WAIT_L(n) asm volatile("s_waitcnt lgkmcnt(" #n ")" ::: "memory")
; #define PG8_BAR __builtin_amdgcn_s_barrier()
; #define PG8_SCHED __builtin_amdgcn_sched_barrier(0)
; template <class Epi, bool SP2 = false>
; __device__ __forceinline__ void gemm_phase(LAS unsigned char* lds, const Gemm g, const StaticOrder& S, const Epi& E) {
;     ...
;             PG8_WAIT_V(8); PG8_WAIT_L(0); PG8_BAR; PG8_MMA(1, 0, At, B0); PG8_MMA(1, 1, At, B1); PG8_BAR; PG8_SCHED;
;             PG8_LDB(B0, 1, 0); PG8_LDB(B1, 1, 1); PG8_SCHED; PG8_LDA(At, 1, 0); PG8_STAGE(PG8_SA(0, 1), a2 + hstepA, voffA);
;             PG8_WAIT_V(8); PG8_WAIT_L(0); PG8_BAR; PG8_MMA(0, 0, At, B0); PG8_MMA(0, 1, At, B1); PG8_BAR; PG8_SCHED;
	v_mfma_f32_16x16x32_bf16 v[60:63], v[146:149], v[184:187], 0
	v_mfma_f32_16x16x32_bf16 v[56:59], v[160:163], v[184:187], 0
	v_mfma_f32_16x16x32_bf16 v[44:47], v[146:149], v[192:195], 0
	v_mfma_f32_16x16x32_bf16 v[40:43], v[160:163], v[192:195], 0
	v_mfma_f32_16x16x32_bf16 v[28:31], v[146:149], v[200:203], 0
	v_mfma_f32_16x16x32_bf16 v[24:27], v[160:163], v[200:203], 0
	v_mfma_f32_16x16x32_bf16 v[12:15], v[146:149], v[208:211], 0
	v_mfma_f32_16x16x32_bf16 v[8:11], v[160:163], v[208:211], 0
	v_mfma_f32_16x16x32_bf16 v[60:63], v[156:159], v[188:191], v[60:63]
	v_mfma_f32_16x16x32_bf16 v[56:59], v[164:167], v[188:191], v[56:59]
	v_mfma_f32_16x16x32_bf16 v[44:47], v[156:159], v[196:199], v[44:47]
	v_mfma_f32_16x16x32_bf16 v[40:43], v[164:167], v[196:199], v[40:43]
	v_mfma_f32_16x16x32_bf16 v[28:31], v[156:159], v[204:207], v[28:31]
	v_mfma_f32_16x16x32_bf16 v[24:27], v[164:167], v[204:207], v[24:27]
	v_mfma_f32_16x16x32_bf16 v[12:15], v[156:159], v[212:215], v[12:15]
	v_mfma_f32_16x16x32_bf16 v[8:11], v[164:167], v[212:215], v[8:11]
	v_mfma_f32_16x16x32_bf16 v[52:55], v[168:171], v[184:187], 0
	v_mfma_f32_16x16x32_bf16 v[48:51], v[176:179], v[184:187], 0
	v_mfma_f32_16x16x32_bf16 v[36:39], v[168:171], v[192:195], 0
	v_mfma_f32_16x16x32_bf16 v[32:35], v[176:179], v[192:195], 0
	v_mfma_f32_16x16x32_bf16 v[20:23], v[168:171], v[200:203], 0
	v_mfma_f32_16x16x32_bf16 v[16:19], v[176:179], v[200:203], 0
	v_mfma_f32_16x16x32_bf16 v[4:7], v[168:171], v[208:211], 0
	v_mfma_f32_16x16x32_bf16 v[0:3], v[176:179], v[208:211], 0
	v_mfma_f32_16x16x32_bf16 v[52:55], v[172:175], v[188:191], v[52:55]
	v_mfma_f32_16x16x32_bf16 v[48:51], v[180:183], v[188:191], v[48:51]
	v_mfma_f32_16x16x32_bf16 v[36:39], v[172:175], v[196:199], v[36:39]
	v_mfma_f32_16x16x32_bf16 v[32:35], v[180:183], v[196:199], v[32:35]
	v_mfma_f32_16x16x32_bf16 v[20:23], v[172:175], v[204:207], v[20:23]
	v_mfma_f32_16x16x32_bf16 v[16:19], v[180:183], v[204:207], v[16:19]
	v_mfma_f32_16x16x32_bf16 v[4:7], v[172:175], v[212:215], v[4:7]
	v_mfma_f32_16x16x32_bf16 v[0:3], v[180:183], v[212:215], v[0:3]
	s_barrier
	s_add_i32 s68, 0, 0x18000
	s_add_i32 s69, 0, 0x1c000
	v_add_u32_e32 v164, s68, v154
	v_add_u32_e32 v180, s69, v154
	ds_read_b128 v[146:149], v164
	ds_read_b128 v[156:159], v164 offset:1024
	ds_read_b128 v[160:163], v164 offset:2048
	ds_read_b128 v[164:167], v164 offset:3072
	ds_read_b128 v[168:171], v180
	ds_read_b128 v[172:175], v180 offset:1024
	ds_read_b128 v[176:179], v180 offset:2048
	ds_read_b128 v[180:183], v180 offset:3072
	s_add_u32 s50, s50, 0x40000
	s_addc_u32 s51, s51, 0
	s_mov_b32 m0, s57
	v_lshl_add_u64 v[222:223], s[50:51], 0, v[136:137]
	ds_read_b128 v[184:187], v155 offset:32768
	ds_read_b128 v[188:191], v155 offset:33792
	ds_read_b128 v[192:195], v155 offset:34816
	ds_read_b128 v[196:199], v155 offset:35840
	ds_read_b128 v[200:203], v155 offset:36864
	ds_read_b128 v[204:207], v155 offset:37888
	ds_read_b128 v[208:211], v155 offset:38912
	ds_read_b128 v[212:215], v155 offset:39936
	global_load_lds_dwordx4 v[222:223], off
	v_lshl_add_u64 v[222:223], s[50:51], 0, v[132:133]
	s_mov_b32 m0, s58
	s_nop 0
	global_load_lds_dwordx4 v[222:223], off
	s_waitcnt vmcnt(8)
	s_waitcnt lgkmcnt(0)
	s_barrier
	v_mfma_f32_16x16x32_bf16 v[124:127], v[146:149], v[184:187], v[124:127]
	v_mfma_f32_16x16x32_bf16 v[120:123], v[160:163], v[184:187], v[120:123]
	v_mfma_f32_16x16x32_bf16 v[108:111], v[146:149], v[192:195], v[108:111]
	v_mfma_f32_16x16x32_bf16 v[104:107], v[160:163], v[192:195], v[104:107]
	v_mfma_f32_16x16x32_bf16 v[92:95], v[146:149], v[200:203], v[92:95]
	v_mfma_f32_16x16x32_bf16 v[88:91], v[160:163], v[200:203], v[88:91]
	v_mfma_f32_16x16x32_bf16 v[76:79], v[146:149], v[208:211], v[76:79]
	v_mfma_f32_16x16x32_bf16 v[72:75], v[160:163], v[208:211], v[72:75]
	v_mfma_f32_16x16x32_bf16 v[124:127], v[156:159], v[188:191], v[124:127]
	v_mfma_f32_16x16x32_bf16 v[120:123], v[164:167], v[188:191], v[120:123]
	v_mfma_f32_16x16x32_bf16 v[108:111], v[156:159], v[196:199], v[108:111]
	v_mfma_f32_16x16x32_bf16 v[104:107], v[164:167], v[196:199], v[104:107]
	v_mfma_f32_16x16x32_bf16 v[92:95], v[156:159], v[204:207], v[92:95]
	v_mfma_f32_16x16x32_bf16 v[88:91], v[164:167], v[204:207], v[88:91]
	v_mfma_f32_16x16x32_bf16 v[76:79], v[156:159], v[212:215], v[76:79]
	v_mfma_f32_16x16x32_bf16 v[72:75], v[164:167], v[212:215], v[72:75]
	v_mfma_f32_16x16x32_bf16 v[116:119], v[168:171], v[184:187], v[116:119]
	v_mfma_f32_16x16x32_bf16 v[112:115], v[176:179], v[184:187], v[112:115]
	v_mfma_f32_16x16x32_bf16 v[100:103], v[168:171], v[192:195], v[100:103]
	v_mfma_f32_16x16x32_bf16 v[96:99], v[176:179], v[192:195], v[96:99]
	v_mfma_f32_16x16x32_bf16 v[84:87], v[168:171], v[200:203], v[84:87]
	v_mfma_f32_16x16x32_bf16 v[80:83], v[176:179], v[200:203], v[80:83]
	v_mfma_f32_16x16x32_bf16 v[68:71], v[168:171], v[208:211], v[68:71]
	v_mfma_f32_16x16x32_bf16 v[64:67], v[176:179], v[208:211], v[64:67]
	v_mfma_f32_16x16x32_bf16 v[116:119], v[172:175], v[188:191], v[116:119]
	v_mfma_f32_16x16x32_bf16 v[112:115], v[180:183], v[188:191], v[112:115]
	v_mfma_f32_16x16x32_bf16 v[100:103], v[172:175], v[196:199], v[100:103]
	v_mfma_f32_16x16x32_bf16 v[96:99], v[180:183], v[196:199], v[96:99]
	v_mfma_f32_16x16x32_bf16 v[84:87], v[172:175], v[204:207], v[84:87]
	v_mfma_f32_16x16x32_bf16 v[80:83], v[180:183], v[204:207], v[80:83]
	v_mfma_f32_16x16x32_bf16 v[68:71], v[172:175], v[212:215], v[68:71]
	v_mfma_f32_16x16x32_bf16 v[64:67], v[180:183], v[212:215], v[64:67]
	s_barrier
; #define PG8_STAGE(bufoff, gbase, voff) do { _Pragma("unroll") for (int _i = 0; _i < 2; ++_i) \
;         __builtin_amdgcn_global_load_lds((const unsigned*)((const char*)(gbase) + (voff)[_i]), (LAS unsigned*)(lds + (bufoff) + ldsw + _i * 8192), 16, 0, 0); } while (0)
; #define PG8_LDA(dst, b, h) do { _Pragma("unroll") for (int m = 0; m < 4; ++m) _Pragma("unroll") for (int k = 0; k < 2; ++k) dst[m][k] = *(const LAS bf16x8*)(lds + PG8_SA(b, h) + aoff + m * 2048 + k * 1024); } while (0)
; #define PG8_MMA(ai, bj, At, Bt) do { __builtin_amdgcn_s_setprio(1); _Pragma("unroll") for (int m = 0; m < 4; ++m) _Pragma("unroll") for (int n = 0; n < 2; ++n) _Pragma("unroll") for (int k = 0; k < 2; ++k) \
;         acc[ai][bj][m][n] = __builtin_amdgcn_mfma_f32_16x16x32_bf16(Bt[n][k], At[m][k], acc[ai][bj][m][n], 0, 0, 0); __builtin_amdgcn_s_setprio(0); } while (0)
; #define PG8_WAIT_V(n) asm volatile("s_waitcnt vmcnt(" #n ")" ::: "memory")
; #define PG8_WAIT_L(n) asm volatile("s_waitcnt lgkmcnt(" #n ")" ::: "memory")
; #define PG8_BAR __builtin_amdgcn_s_barrier()
; #define PG8_SCHED __builtin_amdgcn_sched_barrier(0)
; template <class Epi, bool SP2 = false>
; __device__ __forceinline__ void gemm_phase(LAS unsigned char* lds, const Gemm g, const StaticOrder& S, const Epi& E) {
;     ...
;         for (int t = 0; t < nt; t += 2) {
;             const bool last = (t == nt - 2);
;     ...
;             PG8_LDA(At, 1, 1); PG8_STAGE(PG8_SB(1, 0), b3, voffB); PG8_STAGE(PG8_SB(1, 1), b3 + hstepB, voffB); PG8_STAGE(PG8_SA(1, 0), a3, voffA);
;             PG8_WAIT_V(8); PG8_WAIT_L(0); PG8_BAR; PG8_MMA(1, 0, At, B0); PG8_MMA(1, 1, At, B1); PG8_BAR; PG8_SCHED;
	s_add_i32 s50, s68, s53
	v_lshl_add_u64 v[150:151], v[150:151], 0, s[10:11]
	s_mov_b32 m0, s50
	ds_read_b128 v[184:187], v155 offset:49152
	ds_read_b128 v[188:191], v155 offset:50176
	ds_read_b128 v[192:195], v155 offset:51200
	ds_read_b128 v[196:199], v155 offset:52224
	ds_read_b128 v[200:203], v155 offset:53248
	ds_read_b128 v[204:207], v155 offset:54272
	ds_read_b128 v[208:211], v155 offset:55296
	ds_read_b128 v[212:215], v155 offset:56320
	global_load_lds_dwordx4 v[150:151], off
	s_add_i32 m0, s50, 0x2000
	s_add_u32 s48, s48, 0x40080
	v_lshl_add_u64 v[150:151], v[216:217], 0, s[10:11]
	s_addc_u32 s49, s49, 0
	s_add_i32 s50, s69, s53
	global_load_lds_dwordx4 v[150:151], off
	v_lshl_add_u64 v[150:151], s[48:49], 0, v[134:135]
	s_mov_b32 m0, s50
	s_nop 0
	global_load_lds_dwordx4 v[150:151], off
	v_lshl_add_u64 v[150:151], s[48:49], 0, v[130:131]
	s_add_i32 m0, s50, 0x2000
	s_nop 0
	global_load_lds_dwordx4 v[150:151], off
	v_lshl_add_u64 v[150:151], v[218:219], 0, s[10:11]
	s_mov_b32 m0, s62
	s_nop 0
	global_load_lds_dwordx4 v[150:151], off
	v_lshl_add_u64 v[150:151], v[220:221], 0, s[10:11]
	s_mov_b32 m0, s63
	s_nop 0
	global_load_lds_dwordx4 v[150:151], off
	s_waitcnt vmcnt(8)
	s_waitcnt lgkmcnt(0)
	s_barrier
	v_mfma_f32_16x16x32_bf16 v[60:63], v[146:149], v[184:187], v[60:63]
	v_mfma_f32_16x16x32_bf16 v[56:59], v[160:163], v[184:187], v[56:59]
	v_mfma_f32_16x16x32_bf16 v[44:47], v[146:149], v[192:195], v[44:47]
	v_mfma_f32_16x16x32_bf16 v[40:43], v[160:163], v[192:195], v[40:43]
	v_mfma_f32_16x16x32_bf16 v[28:31], v[146:149], v[200:203], v[28:31]
	v_mfma_f32_16x16x32_bf16 v[24:27], v[160:163], v[200:203], v[24:27]
	v_mfma_f32_16x16x32_bf16 v[12:15], v[146:149], v[208:211], v[12:15]
	v_mfma_f32_16x16x32_bf16 v[8:11], v[160:163], v[208:211], v[8:11]
	v_mfma_f32_16x16x32_bf16 v[60:63], v[156:159], v[188:191], v[60:63]
	v_mfma_f32_16x16x32_bf16 v[56:59], v[164:167], v[188:191], v[56:59]
	v_mfma_f32_16x16x32_bf16 v[44:47], v[156:159], v[196:199], v[44:47]
	v_mfma_f32_16x16x32_bf16 v[40:43], v[164:167], v[196:199], v[40:43]
	v_mfma_f32_16x16x32_bf16 v[28:31], v[156:159], v[204:207], v[28:31]
	v_mfma_f32_16x16x32_bf16 v[24:27], v[164:167], v[204:207], v[24:27]
	v_mfma_f32_16x16x32_bf16 v[12:15], v[156:159], v[212:215], v[12:15]
	v_mfma_f32_16x16x32_bf16 v[8:11], v[164:167], v[212:215], v[8:11]
	v_mfma_f32_16x16x32_bf16 v[52:55], v[168:171], v[184:187], v[52:55]
	v_mfma_f32_16x16x32_bf16 v[48:51], v[176:179], v[184:187], v[48:51]
	v_mfma_f32_16x16x32_bf16 v[36:39], v[168:171], v[192:195], v[36:39]
	v_mfma_f32_16x16x32_bf16 v[32:35], v[176:179], v[192:195], v[32:35]
	v_mfma_f32_16x16x32_bf16 v[20:23], v[168:171], v[200:203], v[20:23]
	v_mfma_f32_16x16x32_bf16 v[16:19], v[176:179], v[200:203], v[16:19]
	v_mfma_f32_16x16x32_bf16 v[4:7], v[168:171], v[208:211], v[4:7]
	v_mfma_f32_16x16x32_bf16 v[0:3], v[176:179], v[208:211], v[0:3]
	v_mfma_f32_16x16x32_bf16 v[52:55], v[172:175], v[188:191], v[52:55]
	v_mfma_f32_16x16x32_bf16 v[48:51], v[180:183], v[188:191], v[48:51]
	v_mfma_f32_16x16x32_bf16 v[36:39], v[172:175], v[196:199], v[36:39]
	v_mfma_f32_16x16x32_bf16 v[32:35], v[180:183], v[196:199], v[32:35]
	v_mfma_f32_16x16x32_bf16 v[20:23], v[172:175], v[204:207], v[20:23]
	v_mfma_f32_16x16x32_bf16 v[16:19], v[180:183], v[204:207], v[16:19]
	v_mfma_f32_16x16x32_bf16 v[4:7], v[172:175], v[212:215], v[4:7]
	v_mfma_f32_16x16x32_bf16 v[0:3], v[180:183], v[212:215], v[0:3]
	s_barrier
	s_add_i32 s76, s76, 2
	s_add_u32 s34, s34, 0x100
	s_addc_u32 s35, s35, 0
	s_add_u32 s74, s74, 0x100
	s_addc_u32 s75, s75, 0
	s_cmp_gt_u32 s76, 13

; #define PG8_STAGE(bufoff, gbase, voff) do { _Pragma("unroll") for (int _i = 0; _i < 2; ++_i) \
;         __builtin_amdgcn_global_load_lds((const unsigned*)((const char*)(gbase) + (voff)[_i]), (LAS unsigned*)(lds + (bufoff) + ldsw + _i * 8192), 16, 0, 0); } while (0)
; #define PG8_LDA(dst, b, h) do { _Pragma("unroll") for (int m = 0; m < 4; ++m) _Pragma("unroll") for (int k = 0; k < 2; ++k) dst[m][k] = *(const LAS bf16x8*)(lds + PG8_SA(b, h) + aoff + m * 2048 + k * 1024); } while (0)
; #define PG8_LDB(dst, b, h) do { _Pragma("unroll") for (int n = 0; n < 2; ++n) _Pragma("unroll") for (int k = 0; k < 2; ++k) dst[n][k] = *(const LAS bf16x8*)(lds + PG8_SB(b, h) + boff + n * 2048 + k * 1024); } while (0)
; #define PG8_MMA(ai, bj, At, Bt) do { __builtin_amdgcn_s_setprio(1); _Pragma("unroll") for (int m = 0; m < 4; ++m) _Pragma("unroll") for (int n = 0; n < 2; ++n) _Pragma("unroll") for (int k = 0; k < 2; ++k) \
;         acc[ai][bj][m][n] = __builtin_amdgcn_mfma_f32_16x16x32_bf16(Bt[n][k], At[m][k], acc[ai][bj][m][n], 0, 0, 0); __builtin_amdgcn_s_setprio(0); } while (0)
; #define PG8_WAIT_V(n) asm volatile("s_waitcnt vmcnt(" #n ")" ::: "memory")
; #define PG8_WAIT_L(n) asm volatile("s_waitcnt lgkmcnt(" #n ")" ::: "memory")
; #define PG8_BAR __builtin_amdgcn_s_barrier()
; #define PG8_SCHED __builtin_amdgcn_sched_barrier(0)
; template <class Epi, bool SP2 = false>
; __device__ __forceinline__ void gemm_phase(LAS unsigned char* lds, const Gemm g, const StaticOrder& S, const Epi& E) {
;     ...
;         const bool has_next = S.next(ui + 1, nxt);
;         const char* nA = has_next ? (const char*)g.A + (size_t)nxt.pm * tstepA : cA; const char* nB = has_next ? (const char*)g.Bt + (size_t)nxt.pn * tstepB : cB;
;         for (int t = 0; t < nt; t += 2) {
;             const bool last = (t == nt - 2);
;             const char* a1 = cA + (size_t)(t + 1) * kstep;
;             const char* a2 = last ? nA : cA + (size_t)(t + 2) * kstep; const char* b2 = last ? nB : cB + (size_t)(t + 2) * kstep;
;             const char* a3 = a2 + kstep; const char* b3 = b2 + kstep;
;             if constexpr (SP2) {
;             PG8_LDB(B0, 0, 0); PG8_LDB(B1, 0, 1); PG8_SCHED; PG8_LDA(At, 0, 0); PG8_STAGE(PG8_SA(1, 1), a1 + hstepA, voffA);
;             PG8_WAIT_V(8); PG8_WAIT_L(0); PG8_BAR; PG8_MMA(0, 0, At, B0); PG8_MMA(0, 1, At, B1); PG8_BAR; PG8_SCHED;
.LBB0_954:
	s_ashr_i32 s41, s40, 31
	s_lshl_b64 s[42:43], s[40:41], 19
	s_add_u32 s42, s24, s42
	s_addc_u32 s43, s25, s43
	s_and_b64 s[44:45], s[0:1], exec
	s_cselect_b32 s41, s43, s35
	s_cselect_b32 s74, s42, s34
	s_ashr_i32 s39, s38, 31
	s_lshl_b64 s[44:45], s[38:39], 19
	s_add_u32 s44, s3, s44
	s_addc_u32 s45, s33, s45
	s_and_b64 s[48:49], s[0:1], exec
	s_cselect_b32 s39, s45, s47
	s_cselect_b32 s75, s44, s46
	s_add_u32 s34, s34, 0x40080
	s_addc_u32 s35, s35, 0
	s_add_u32 s76, s46, 0x100
	s_addc_u32 s77, s47, 0
	s_mov_b32 s78, -2
	ds_read_b128 v[150:153], v147
	ds_read_b128 v[154:157], v147 offset:1024
	ds_read_b128 v[158:161], v147 offset:2048
	ds_read_b128 v[162:165], v147 offset:3072
	ds_read_b128 v[166:169], v148
	ds_read_b128 v[170:173], v148 offset:1024
	ds_read_b128 v[174:177], v148 offset:2048
	ds_read_b128 v[178:181], v148 offset:3072
	s_add_u32 s46, s34, 0xfffc0080
	s_addc_u32 s47, s35, -1
	s_cmp_eq_u32 s78, 12
	s_cselect_b32 s49, s41, s47
	s_cselect_b32 s48, s74, s46
	s_cselect_b32 s47, s39, s77
	s_cselect_b32 s46, s75, s76
	v_lshl_add_u64 v[214:215], s[34:35], 0, v[138:139]
	s_add_i32 m0, s53, 0xc000
	ds_read_b128 v[182:185], v149
	ds_read_b128 v[186:189], v149 offset:1024
	ds_read_b128 v[190:193], v149 offset:2048
	ds_read_b128 v[194:197], v149 offset:3072
	ds_read_b128 v[198:201], v149 offset:4096
	ds_read_b128 v[202:205], v149 offset:5120
	ds_read_b128 v[206:209], v149 offset:6144
	ds_read_b128 v[210:213], v149 offset:7168
	global_load_lds_dwordx4 v[214:215], off
	v_lshl_add_u64 v[214:215], s[34:35], 0, v[140:141]
	s_add_i32 m0, s53, 0xe000
	s_nop 0
	global_load_lds_dwordx4 v[214:215], off
	s_waitcnt vmcnt(24)
	s_waitcnt lgkmcnt(0)
	s_barrier
	v_mfma_f32_16x16x32_bf16 v[124:127], v[150:153], v[182:185], 0
	v_mfma_f32_16x16x32_bf16 v[120:123], v[158:161], v[182:185], 0
	v_mfma_f32_16x16x32_bf16 v[116:119], v[150:153], v[190:193], 0
	v_mfma_f32_16x16x32_bf16 v[112:115], v[158:161], v[190:193], 0
	v_mfma_f32_16x16x32_bf16 v[100:103], v[150:153], v[198:201], 0
	v_mfma_f32_16x16x32_bf16 v[96:99], v[158:161], v[198:201], 0
	v_mfma_f32_16x16x32_bf16 v[84:87], v[150:153], v[206:209], 0
	v_mfma_f32_16x16x32_bf16 v[80:83], v[158:161], v[206:209], 0
	v_mfma_f32_16x16x32_bf16 v[124:127], v[154:157], v[186:189], v[124:127]
	v_mfma_f32_16x16x32_bf16 v[120:123], v[162:165], v[186:189], v[120:123]
	v_mfma_f32_16x16x32_bf16 v[116:119], v[154:157], v[194:197], v[116:119]
	v_mfma_f32_16x16x32_bf16 v[112:115], v[162:165], v[194:197], v[112:115]
	v_mfma_f32_16x16x32_bf16 v[100:103], v[154:157], v[202:205], v[100:103]
	v_mfma_f32_16x16x32_bf16 v[96:99], v[162:165], v[202:205], v[96:99]
	v_mfma_f32_16x16x32_bf16 v[84:87], v[154:157], v[210:213], v[84:87]
	v_mfma_f32_16x16x32_bf16 v[80:83], v[162:165], v[210:213], v[80:83]
	v_mfma_f32_16x16x32_bf16 v[108:111], v[166:169], v[182:185], 0
	v_mfma_f32_16x16x32_bf16 v[104:107], v[174:177], v[182:185], 0
	v_mfma_f32_16x16x32_bf16 v[92:95], v[166:169], v[190:193], 0
	v_mfma_f32_16x16x32_bf16 v[88:91], v[174:177], v[190:193], 0
	v_mfma_f32_16x16x32_bf16 v[76:79], v[166:169], v[198:201], 0
	v_mfma_f32_16x16x32_bf16 v[72:75], v[174:177], v[198:201], 0
	v_mfma_f32_16x16x32_bf16 v[68:71], v[166:169], v[206:209], 0
	v_mfma_f32_16x16x32_bf16 v[64:67], v[174:177], v[206:209], 0
	v_mfma_f32_16x16x32_bf16 v[108:111], v[170:173], v[186:189], v[108:111]
	v_mfma_f32_16x16x32_bf16 v[104:107], v[178:181], v[186:189], v[104:107]
	v_mfma_f32_16x16x32_bf16 v[92:95], v[170:173], v[194:197], v[92:95]
	v_mfma_f32_16x16x32_bf16 v[88:91], v[178:181], v[194:197], v[88:91]
	v_mfma_f32_16x16x32_bf16 v[76:79], v[170:173], v[202:205], v[76:79]
	v_mfma_f32_16x16x32_bf16 v[72:75], v[178:181], v[202:205], v[72:75]
	v_mfma_f32_16x16x32_bf16 v[68:71], v[170:173], v[210:213], v[68:71]
	v_mfma_f32_16x16x32_bf16 v[64:67], v[178:181], v[210:213], v[64:67]
	s_barrier
	s_add_i32 s68, s63, s50
	v_lshl_add_u64 v[214:215], s[46:47], 0, v[134:135]
	s_mov_b32 m0, s68
	ds_read_b128 v[182:185], v149 offset:16384
	ds_read_b128 v[186:189], v149 offset:17408
	ds_read_b128 v[190:193], v149 offset:18432
	ds_read_b128 v[194:197], v149 offset:19456
	ds_read_b128 v[198:201], v149 offset:20480
	ds_read_b128 v[202:205], v149 offset:21504
	ds_read_b128 v[206:209], v149 offset:22528
	ds_read_b128 v[210:213], v149 offset:23552
	global_load_lds_dwordx4 v[214:215], off
	s_add_i32 m0, s68, 0x2000
	s_add_u32 s68, s46, 0x40000
	v_lshl_add_u64 v[216:217], s[46:47], 0, v[130:131]
	s_addc_u32 s69, s47, 0
	s_add_i32 s70, s64, s50
	global_load_lds_dwordx4 v[216:217], off
	v_lshl_add_u64 v[218:219], s[68:69], 0, v[134:135]
	s_mov_b32 m0, s70
	v_lshl_add_u64 v[220:221], s[48:49], 0, v[132:133]
	global_load_lds_dwordx4 v[218:219], off
	v_lshl_add_u64 v[218:219], s[68:69], 0, v[130:131]
	s_add_i32 m0, s70, 0x2000
	s_nop 0
	global_load_lds_dwordx4 v[218:219], off
	v_lshl_add_u64 v[218:219], s[48:49], 0, v[136:137]
	s_mov_b32 m0, s53
	s_nop 0
	global_load_lds_dwordx4 v[218:219], off
	s_mov_b32 m0, s54
	s_nop 0
	global_load_lds_dwordx4 v[220:221], off
	s_waitcnt vmcnt(8)
	s_waitcnt lgkmcnt(0)
	s_barrier
; #define PG8_STAGE(bufoff, gbase, voff) do { _Pragma("unroll") for (int _i = 0; _i < 2; ++_i) \
;         __builtin_amdgcn_global_load_lds((const unsigned*)((const char*)(gbase) + (voff)[_i]), (LAS unsigned*)(lds + (bufoff) + ldsw + _i * 8192), 16, 0, 0); } while (0)
; #define PG8_LDA(dst, b, h) do { _Pragma("unroll") for (int m = 0; m < 4; ++m) _Pragma("unroll") for (int k = 0; k < 2; ++k) dst[m][k] = *(const LAS bf16x8*)(lds + PG8_SA(b, h) + aoff + m * 2048 + k * 1024); } while (0)
; #define PG8_LDB(dst, b, h) do { _Pragma("unroll") for (int n = 0; n < 2; ++n) _Pragma("unroll") for (int k = 0; k < 2; ++k) dst[n][k] = *(const LAS bf16x8*)(lds + PG8_SB(b, h) + boff + n * 2048 + k * 1024); } while (0)
; #define PG8_MMA(ai, bj, At, Bt) do { __builtin_amdgcn_s_setprio(1); _Pragma("unroll") for (int m = 0; m < 4; ++m) _Pragma("unroll") for (int n = 0; n < 2; ++n) _Pragma("unroll") for (int k = 0; k < 2; ++k) \
;         acc[ai][bj][m][n] = __builtin_amdgcn_mfma_f32_16x16x32_bf16(Bt[n][k], At[m][k], acc[ai][bj][m][n], 0, 0, 0); __builtin_amdgcn_s_setprio(0); } while (0)
; #define PG8_WAIT_V(n) asm volatile("s_waitcnt vmcnt(" #n ")" ::: "memory")
; #define PG8_WAIT_L(n) asm volatile("s_waitcnt lgkmcnt(" #n ")" ::: "memory")
; #define PG8_BAR __builtin_amdgcn_s_barrier()
; #define PG8_SCHED __builtin_amdgcn_sched_barrier(0)
; template <class Epi, bool SP2 = false>
; __device__ __forceinline__ void gemm_phase(LAS unsigned char* lds, const Gemm g, const StaticOrder& S, const Epi& E) {
;     ...
;             PG8_WAIT_V(8); PG8_WAIT_L(0); PG8_BAR; PG8_MMA(1, 0, At, B0); PG8_MMA(1, 1, At, B1); PG8_BAR; PG8_SCHED;
;             PG8_LDB(B0, 1, 0); PG8_LDB(B1, 1, 1); PG8_SCHED; PG8_LDA(At, 1, 0); PG8_STAGE(PG8_SA(0, 1), a2 + hstepA, voffA);
;             PG8_WAIT_V(8); PG8_WAIT_L(0); PG8_BAR; PG8_MMA(0, 0, At, B0); PG8_MMA(0, 1, At, B1); PG8_BAR; PG8_SCHED;
	v_mfma_f32_16x16x32_bf16 v[60:63], v[150:153], v[182:185], 0
	v_mfma_f32_16x16x32_bf16 v[56:59], v[158:161], v[182:185], 0
	v_mfma_f32_16x16x32_bf16 v[52:55], v[150:153], v[190:193], 0
	v_mfma_f32_16x16x32_bf16 v[48:51], v[158:161], v[190:193], 0
	v_mfma_f32_16x16x32_bf16 v[36:39], v[150:153], v[198:201], 0
	v_mfma_f32_16x16x32_bf16 v[32:35], v[158:161], v[198:201], 0
	v_mfma_f32_16x16x32_bf16 v[20:23], v[150:153], v[206:209], 0
	v_mfma_f32_16x16x32_bf16 v[16:19], v[158:161], v[206:209], 0
	v_mfma_f32_16x16x32_bf16 v[60:63], v[154:157], v[186:189], v[60:63]
	v_mfma_f32_16x16x32_bf16 v[56:59], v[162:165], v[186:189], v[56:59]
	v_mfma_f32_16x16x32_bf16 v[52:55], v[154:157], v[194:197], v[52:55]
	v_mfma_f32_16x16x32_bf16 v[48:51], v[162:165], v[194:197], v[48:51]
	v_mfma_f32_16x16x32_bf16 v[36:39], v[154:157], v[202:205], v[36:39]
	v_mfma_f32_16x16x32_bf16 v[32:35], v[162:165], v[202:205], v[32:35]
	v_mfma_f32_16x16x32_bf16 v[20:23], v[154:157], v[210:213], v[20:23]
	v_mfma_f32_16x16x32_bf16 v[16:19], v[162:165], v[210:213], v[16:19]
	v_mfma_f32_16x16x32_bf16 v[44:47], v[166:169], v[182:185], 0
	v_mfma_f32_16x16x32_bf16 v[40:43], v[174:177], v[182:185], 0
	v_mfma_f32_16x16x32_bf16 v[28:31], v[166:169], v[190:193], 0
	v_mfma_f32_16x16x32_bf16 v[24:27], v[174:177], v[190:193], 0
	v_mfma_f32_16x16x32_bf16 v[12:15], v[166:169], v[198:201], 0
	v_mfma_f32_16x16x32_bf16 v[8:11], v[174:177], v[198:201], 0
	v_mfma_f32_16x16x32_bf16 v[4:7], v[166:169], v[206:209], 0
	v_mfma_f32_16x16x32_bf16 v[0:3], v[174:177], v[206:209], 0
	v_mfma_f32_16x16x32_bf16 v[44:47], v[170:173], v[186:189], v[44:47]
	v_mfma_f32_16x16x32_bf16 v[40:43], v[178:181], v[186:189], v[40:43]
	v_mfma_f32_16x16x32_bf16 v[28:31], v[170:173], v[194:197], v[28:31]
	v_mfma_f32_16x16x32_bf16 v[24:27], v[178:181], v[194:197], v[24:27]
	v_mfma_f32_16x16x32_bf16 v[12:15], v[170:173], v[202:205], v[12:15]
	v_mfma_f32_16x16x32_bf16 v[8:11], v[178:181], v[202:205], v[8:11]
	v_mfma_f32_16x16x32_bf16 v[4:7], v[170:173], v[210:213], v[4:7]
	v_mfma_f32_16x16x32_bf16 v[0:3], v[178:181], v[210:213], v[0:3]
	s_barrier
	s_add_i32 s68, 0, 0x18000
	s_add_i32 s69, 0, 0x1c000
	v_add_u32_e32 v162, s68, v146
	v_add_u32_e32 v178, s69, v146
	ds_read_b128 v[150:153], v162
	ds_read_b128 v[154:157], v162 offset:1024
	ds_read_b128 v[158:161], v162 offset:2048
	ds_read_b128 v[162:165], v162 offset:3072
	ds_read_b128 v[166:169], v178
	ds_read_b128 v[170:173], v178 offset:1024
	ds_read_b128 v[174:177], v178 offset:2048
	ds_read_b128 v[178:181], v178 offset:3072
	s_add_u32 s48, s48, 0x40000
	s_addc_u32 s49, s49, 0
	s_mov_b32 m0, s55
	v_lshl_add_u64 v[222:223], s[48:49], 0, v[136:137]
	ds_read_b128 v[182:185], v149 offset:32768
	ds_read_b128 v[186:189], v149 offset:33792
	ds_read_b128 v[190:193], v149 offset:34816
	ds_read_b128 v[194:197], v149 offset:35840
	ds_read_b128 v[198:201], v149 offset:36864
	ds_read_b128 v[202:205], v149 offset:37888
	ds_read_b128 v[206:209], v149 offset:38912
	ds_read_b128 v[210:213], v149 offset:39936
	global_load_lds_dwordx4 v[222:223], off
	v_lshl_add_u64 v[222:223], s[48:49], 0, v[132:133]
	s_mov_b32 m0, s56
	s_nop 0
	global_load_lds_dwordx4 v[222:223], off
	s_waitcnt vmcnt(8)
	s_waitcnt lgkmcnt(0)
	s_barrier
	v_mfma_f32_16x16x32_bf16 v[124:127], v[150:153], v[182:185], v[124:127]
	v_mfma_f32_16x16x32_bf16 v[120:123], v[158:161], v[182:185], v[120:123]
	v_mfma_f32_16x16x32_bf16 v[116:119], v[150:153], v[190:193], v[116:119]
	v_mfma_f32_16x16x32_bf16 v[112:115], v[158:161], v[190:193], v[112:115]
	v_mfma_f32_16x16x32_bf16 v[100:103], v[150:153], v[198:201], v[100:103]
	v_mfma_f32_16x16x32_bf16 v[96:99], v[158:161], v[198:201], v[96:99]
	v_mfma_f32_16x16x32_bf16 v[84:87], v[150:153], v[206:209], v[84:87]
	v_mfma_f32_16x16x32_bf16 v[80:83], v[158:161], v[206:209], v[80:83]
	v_mfma_f32_16x16x32_bf16 v[124:127], v[154:157], v[186:189], v[124:127]
	v_mfma_f32_16x16x32_bf16 v[120:123], v[162:165], v[186:189], v[120:123]
	v_mfma_f32_16x16x32_bf16 v[116:119], v[154:157], v[194:197], v[116:119]
	v_mfma_f32_16x16x32_bf16 v[112:115], v[162:165], v[194:197], v[112:115]
	v_mfma_f32_16x16x32_bf16 v[100:103], v[154:157], v[202:205], v[100:103]
	v_mfma_f32_16x16x32_bf16 v[96:99], v[162:165], v[202:205], v[96:99]
	v_mfma_f32_16x16x32_bf16 v[84:87], v[154:157], v[210:213], v[84:87]
	v_mfma_f32_16x16x32_bf16 v[80:83], v[162:165], v[210:213], v[80:83]
	v_mfma_f32_16x16x32_bf16 v[108:111], v[166:169], v[182:185], v[108:111]
	v_mfma_f32_16x16x32_bf16 v[104:107], v[174:177], v[182:185], v[104:107]
	v_mfma_f32_16x16x32_bf16 v[92:95], v[166:169], v[190:193], v[92:95]
	v_mfma_f32_16x16x32_bf16 v[88:91], v[174:177], v[190:193], v[88:91]
	v_mfma_f32_16x16x32_bf16 v[76:79], v[166:169], v[198:201], v[76:79]
	v_mfma_f32_16x16x32_bf16 v[72:75], v[174:177], v[198:201], v[72:75]
	v_mfma_f32_16x16x32_bf16 v[68:71], v[166:169], v[206:209], v[68:71]
	v_mfma_f32_16x16x32_bf16 v[64:67], v[174:177], v[206:209], v[64:67]
	v_mfma_f32_16x16x32_bf16 v[108:111], v[170:173], v[186:189], v[108:111]
	v_mfma_f32_16x16x32_bf16 v[104:107], v[178:181], v[186:189], v[104:107]
	v_mfma_f32_16x16x32_bf16 v[92:95], v[170:173], v[194:197], v[92:95]
	v_mfma_f32_16x16x32_bf16 v[88:91], v[178:181], v[194:197], v[88:91]
	v_mfma_f32_16x16x32_bf16 v[76:79], v[170:173], v[202:205], v[76:79]
	v_mfma_f32_16x16x32_bf16 v[72:75], v[178:181], v[202:205], v[72:75]
	v_mfma_f32_16x16x32_bf16 v[68:71], v[170:173], v[210:213], v[68:71]
	v_mfma_f32_16x16x32_bf16 v[64:67], v[178:181], v[210:213], v[64:67]
	s_barrier
; #define PG8_STAGE(bufoff, gbase, voff) do { _Pragma("unroll") for (int _i = 0; _i < 2; ++_i) \
;         __builtin_amdgcn_global_load_lds((const unsigned*)((const char*)(gbase) + (voff)[_i]), (LAS unsigned*)(lds + (bufoff) + ldsw + _i * 8192), 16, 0, 0); } while (0)
; #define PG8_LDA(dst, b, h) do { _Pragma("unroll") for (int m = 0; m < 4; ++m) _Pragma("unroll") for (int k = 0; k < 2; ++k) dst[m][k] = *(const LAS bf16x8*)(lds + PG8_SA(b, h) + aoff + m * 2048 + k * 1024); } while (0)
; #define PG8_MMA(ai, bj, At, Bt) do { __builtin_amdgcn_s_setprio(1); _Pragma("unroll") for (int m = 0; m < 4; ++m) _Pragma("unroll") for (int n = 0; n < 2; ++n) _Pragma("unroll") for (int k = 0; k < 2; ++k) \
;         acc[ai][bj][m][n] = __builtin_amdgcn_mfma_f32_16x16x32_bf16(Bt[n][k], At[m][k], acc[ai][bj][m][n], 0, 0, 0); __builtin_amdgcn_s_setprio(0); } while (0)
; #define PG8_WAIT_V(n) asm volatile("s_waitcnt vmcnt(" #n ")" ::: "memory")
; #define PG8_WAIT_L(n) asm volatile("s_waitcnt lgkmcnt(" #n ")" ::: "memory")
; #define PG8_BAR __builtin_amdgcn_s_barrier()
; #define PG8_SCHED __builtin_amdgcn_sched_barrier(0)
; template <class Epi, bool SP2 = false>
; __device__ __forceinline__ void gemm_phase(LAS unsigned char* lds, const Gemm g, const StaticOrder& S, const Epi& E) {
;     ...
;         for (int t = 0; t < nt; t += 2) {
;             const bool last = (t == nt - 2);
;     ...
;             PG8_LDA(At, 1, 1); PG8_STAGE(PG8_SB(1, 0), b3, voffB); PG8_STAGE(PG8_SB(1, 1), b3 + hstepB, voffB); PG8_STAGE(PG8_SA(1, 0), a3, voffA);
;             PG8_WAIT_V(8); PG8_WAIT_L(0); PG8_BAR; PG8_MMA(1, 0, At, B0); PG8_MMA(1, 1, At, B1); PG8_BAR; PG8_SCHED;
	s_add_i32 s48, s68, s50
	v_lshl_add_u64 v[214:215], v[214:215], 0, s[12:13]
	s_mov_b32 m0, s48
	ds_read_b128 v[182:185], v149 offset:49152
	ds_read_b128 v[186:189], v149 offset:50176
	ds_read_b128 v[190:193], v149 offset:51200
	ds_read_b128 v[194:197], v149 offset:52224
	ds_read_b128 v[198:201], v149 offset:53248
	ds_read_b128 v[202:205], v149 offset:54272
	ds_read_b128 v[206:209], v149 offset:55296
	ds_read_b128 v[210:213], v149 offset:56320
	global_load_lds_dwordx4 v[214:215], off
	s_add_i32 m0, s48, 0x2000
	s_add_u32 s46, s46, 0x40080
	v_lshl_add_u64 v[214:215], v[216:217], 0, s[12:13]
	s_addc_u32 s47, s47, 0
	s_add_i32 s48, s69, s50
	global_load_lds_dwordx4 v[214:215], off
	v_lshl_add_u64 v[214:215], s[46:47], 0, v[134:135]
	s_mov_b32 m0, s48
	s_nop 0
	global_load_lds_dwordx4 v[214:215], off
	v_lshl_add_u64 v[214:215], s[46:47], 0, v[130:131]
	s_add_i32 m0, s48, 0x2000
	s_nop 0
	global_load_lds_dwordx4 v[214:215], off
	v_lshl_add_u64 v[214:215], v[218:219], 0, s[12:13]
	s_mov_b32 m0, s59
	s_nop 0
	global_load_lds_dwordx4 v[214:215], off
	v_lshl_add_u64 v[214:215], v[220:221], 0, s[12:13]
	s_mov_b32 m0, s60
	s_nop 0
	global_load_lds_dwordx4 v[214:215], off
	s_waitcnt vmcnt(8)
	s_waitcnt lgkmcnt(0)
	s_barrier
	v_mfma_f32_16x16x32_bf16 v[60:63], v[150:153], v[182:185], v[60:63]
	v_mfma_f32_16x16x32_bf16 v[56:59], v[158:161], v[182:185], v[56:59]
	v_mfma_f32_16x16x32_bf16 v[52:55], v[150:153], v[190:193], v[52:55]
	v_mfma_f32_16x16x32_bf16 v[48:51], v[158:161], v[190:193], v[48:51]
	v_mfma_f32_16x16x32_bf16 v[36:39], v[150:153], v[198:201], v[36:39]
	v_mfma_f32_16x16x32_bf16 v[32:35], v[158:161], v[198:201], v[32:35]
	v_mfma_f32_16x16x32_bf16 v[20:23], v[150:153], v[206:209], v[20:23]
	v_mfma_f32_16x16x32_bf16 v[16:19], v[158:161], v[206:209], v[16:19]
	v_mfma_f32_16x16x32_bf16 v[60:63], v[154:157], v[186:189], v[60:63]
	v_mfma_f32_16x16x32_bf16 v[56:59], v[162:165], v[186:189], v[56:59]
	v_mfma_f32_16x16x32_bf16 v[52:55], v[154:157], v[194:197], v[52:55]
	v_mfma_f32_16x16x32_bf16 v[48:51], v[162:165], v[194:197], v[48:51]
	v_mfma_f32_16x16x32_bf16 v[36:39], v[154:157], v[202:205], v[36:39]
	v_mfma_f32_16x16x32_bf16 v[32:35], v[162:165], v[202:205], v[32:35]
	v_mfma_f32_16x16x32_bf16 v[20:23], v[154:157], v[210:213], v[20:23]
	v_mfma_f32_16x16x32_bf16 v[16:19], v[162:165], v[210:213], v[16:19]
	v_mfma_f32_16x16x32_bf16 v[44:47], v[166:169], v[182:185], v[44:47]
	v_mfma_f32_16x16x32_bf16 v[40:43], v[174:177], v[182:185], v[40:43]
	v_mfma_f32_16x16x32_bf16 v[28:31], v[166:169], v[190:193], v[28:31]
	v_mfma_f32_16x16x32_bf16 v[24:27], v[174:177], v[190:193], v[24:27]
	v_mfma_f32_16x16x32_bf16 v[12:15], v[166:169], v[198:201], v[12:15]
	v_mfma_f32_16x16x32_bf16 v[8:11], v[174:177], v[198:201], v[8:11]
	v_mfma_f32_16x16x32_bf16 v[4:7], v[166:169], v[206:209], v[4:7]
	v_mfma_f32_16x16x32_bf16 v[0:3], v[174:177], v[206:209], v[0:3]
	v_mfma_f32_16x16x32_bf16 v[44:47], v[170:173], v[186:189], v[44:47]
	v_mfma_f32_16x16x32_bf16 v[40:43], v[178:181], v[186:189], v[40:43]
	v_mfma_f32_16x16x32_bf16 v[28:31], v[170:173], v[194:197], v[28:31]
	v_mfma_f32_16x16x32_bf16 v[24:27], v[178:181], v[194:197], v[24:27]
	v_mfma_f32_16x16x32_bf16 v[12:15], v[170:173], v[202:205], v[12:15]
	v_mfma_f32_16x16x32_bf16 v[8:11], v[178:181], v[202:205], v[8:11]
	v_mfma_f32_16x16x32_bf16 v[4:7], v[170:173], v[210:213], v[4:7]
	v_mfma_f32_16x16x32_bf16 v[0:3], v[178:181], v[210:213], v[0:3]
	s_barrier
	s_add_i32 s78, s78, 2
	s_add_u32 s34, s34, 0x100
	s_addc_u32 s35, s35, 0
	s_add_u32 s76, s76, 0x100
	s_addc_u32 s77, s77, 0
	s_cmp_gt_u32 s78, 13

; #define PG8_STAGE(bufoff, gbase, voff) do { _Pragma("unroll") for (int _i = 0; _i < 2; ++_i) \
;         __builtin_amdgcn_global_load_lds((const unsigned*)((const char*)(gbase) + (voff)[_i]), (LAS unsigned*)(lds + (bufoff) + ldsw + _i * 8192), 16, 0, 0); } while (0)
; #define PG8_LDA(dst, b, h) do { _Pragma("unroll") for (int m = 0; m < 4; ++m) _Pragma("unroll") for (int k = 0; k < 2; ++k) dst[m][k] = *(const LAS bf16x8*)(lds + PG8_SA(b, h) + aoff + m * 2048 + k * 1024); } while (0)
; #define PG8_LDB(dst, b, h) do { _Pragma("unroll") for (int n = 0; n < 2; ++n) _Pragma("unroll") for (int k = 0; k < 2; ++k) dst[n][k] = *(const LAS bf16x8*)(lds + PG8_SB(b, h) + boff + n * 2048 + k * 1024); } while (0)
; #define PG8_BAR __builtin_amdgcn_s_barrier()
; template <class Epi, bool SP2 = false>
; __device__ __forceinline__ void gemm_phase(LAS unsigned char* lds, const Gemm g, const StaticOrder& S, const Epi& E) {
;     ...
;         const bool has_next = S.next(ui + 1, nxt);
;         const char* nA = has_next ? (const char*)g.A + (size_t)nxt.pm * tstepA : cA; const char* nB = has_next ? (const char*)g.Bt + (size_t)nxt.pn * tstepB : cB;
;         for (int t = 0; t < nt; t += 2) {
;             const bool last = (t == nt - 2);
;             const char* a1 = cA + (size_t)(t + 1) * kstep;
;             const char* a2 = last ? nA : cA + (size_t)(t + 2) * kstep; const char* b2 = last ? nB : cB + (size_t)(t + 2) * kstep;
;             const char* a3 = a2 + kstep; const char* b3 = b2 + kstep;
;             if constexpr (SP2) {
;             PG8_LDB(B0, 0, 0); PG8_LDB(B1, 0, 1); PG8_SCHED; PG8_LDA(At, 0, 0); PG8_STAGE(PG8_SA(1, 1), a1 + hstepA, voffA);
;             PG8_WAIT_V(8); PG8_WAIT_L(0); PG8_BAR; PG8_MMA(0, 0, At, B0); PG8_MMA(0, 1, At, B1); PG8_BAR; PG8_SCHED;
;             PG8_LDA(At, 0, 1); PG8_STAGE(PG8_SB(0, 0), b2, voffB); PG8_STAGE(PG8_SB(0, 1), b2 + hstepB, voffB); PG8_STAGE(PG8_SA(0, 0), a2, voffA);
;             PG8_WAIT_V(8); PG8_WAIT_L(0); PG8_BAR; PG8_MMA(1, 0, At, B0); PG8_MMA(1, 1, At, B1); PG8_BAR; PG8_SCHED;
;     ...
; #pragma unroll
;         for (int a = 0; a < 2; ++a)
; #pragma unroll
;             for (int b = 0; b < 2; ++b)
; #pragma unroll
;                 for (int m = 0; m < 4; ++m)
; #pragma unroll
;                     for (int n = 0; n < 2; ++n) acc[a][b][m][n] = (f32x4){0.f, 0.f, 0.f, 0.f};
;         cur = nxt; cA = nA; cB = nB; ++ui;
.LBB0_1076:
	s_ashr_i32 s19, s18, 31
	s_lshl_b64 s[20:21], s[18:19], 19
	s_add_u32 s20, s14, s20
	s_addc_u32 s21, s15, s21
	s_and_b64 s[24:25], s[0:1], exec
	s_cselect_b32 s19, s21, s29
	s_cselect_b32 s53, s20, s28
	s_ashr_i32 s13, s12, 31
	s_lshl_b64 s[24:25], s[12:13], 19
	s_add_u32 s24, s3, s24
	s_addc_u32 s25, s36, s25
	s_and_b64 s[34:35], s[0:1], exec
	s_cselect_b32 s13, s25, s31
	s_cselect_b32 s54, s24, s30
	s_add_u32 s28, s28, 0x40080
	s_addc_u32 s29, s29, 0
	s_add_u32 s55, s30, 0x100
	s_addc_u32 s56, s31, 0
	s_mov_b32 s57, -2
	ds_read_b128 v[152:155], v149
	ds_read_b128 v[156:159], v149 offset:1024
	ds_read_b128 v[160:163], v149 offset:2048
	ds_read_b128 v[164:167], v149 offset:3072
	ds_read_b128 v[168:171], v150
	ds_read_b128 v[172:175], v150 offset:1024
	ds_read_b128 v[176:179], v150 offset:2048
	ds_read_b128 v[180:183], v150 offset:3072
	s_add_u32 s30, s28, 0xfffc0080
	s_addc_u32 s31, s29, -1
	s_cmp_eq_u32 s57, 12
	s_cselect_b32 s35, s19, s31
	s_cselect_b32 s34, s53, s30
	s_cselect_b32 s31, s13, s56
	s_cselect_b32 s30, s54, s55
	v_lshl_add_u64 v[146:147], s[28:29], 0, v[138:139]
	s_add_i32 m0, s27, 0xc000
	ds_read_b128 v[184:187], v151
	ds_read_b128 v[188:191], v151 offset:1024
	ds_read_b128 v[192:195], v151 offset:2048
	ds_read_b128 v[196:199], v151 offset:3072
	ds_read_b128 v[200:203], v151 offset:4096
	ds_read_b128 v[204:207], v151 offset:5120
	ds_read_b128 v[208:211], v151 offset:6144
	ds_read_b128 v[212:215], v151 offset:7168
	global_load_lds_dwordx4 v[146:147], off
	v_lshl_add_u64 v[146:147], s[28:29], 0, v[140:141]
	s_add_i32 m0, s27, 0xe000
	s_nop 0
	global_load_lds_dwordx4 v[146:147], off
	s_waitcnt vmcnt(16)
	s_waitcnt lgkmcnt(0)
	s_barrier
	v_mfma_f32_16x16x32_bf16 v[124:127], v[152:155], v[184:187], 0
	v_mfma_f32_16x16x32_bf16 v[120:123], v[160:163], v[184:187], 0
	v_mfma_f32_16x16x32_bf16 v[108:111], v[152:155], v[192:195], 0
	v_mfma_f32_16x16x32_bf16 v[104:107], v[160:163], v[192:195], 0
	v_mfma_f32_16x16x32_bf16 v[92:95], v[152:155], v[200:203], 0
	v_mfma_f32_16x16x32_bf16 v[88:91], v[160:163], v[200:203], 0
	v_mfma_f32_16x16x32_bf16 v[76:79], v[152:155], v[208:211], 0
	v_mfma_f32_16x16x32_bf16 v[72:75], v[160:163], v[208:211], 0
	v_mfma_f32_16x16x32_bf16 v[124:127], v[156:159], v[188:191], v[124:127]
	v_mfma_f32_16x16x32_bf16 v[120:123], v[164:167], v[188:191], v[120:123]
	v_mfma_f32_16x16x32_bf16 v[108:111], v[156:159], v[196:199], v[108:111]
	v_mfma_f32_16x16x32_bf16 v[104:107], v[164:167], v[196:199], v[104:107]
	v_mfma_f32_16x16x32_bf16 v[92:95], v[156:159], v[204:207], v[92:95]
	v_mfma_f32_16x16x32_bf16 v[88:91], v[164:167], v[204:207], v[88:91]
	v_mfma_f32_16x16x32_bf16 v[76:79], v[156:159], v[212:215], v[76:79]
	v_mfma_f32_16x16x32_bf16 v[72:75], v[164:167], v[212:215], v[72:75]
	v_mfma_f32_16x16x32_bf16 v[116:119], v[168:171], v[184:187], 0
	v_mfma_f32_16x16x32_bf16 v[112:115], v[176:179], v[184:187], 0
	v_mfma_f32_16x16x32_bf16 v[100:103], v[168:171], v[192:195], 0
	v_mfma_f32_16x16x32_bf16 v[96:99], v[176:179], v[192:195], 0
	v_mfma_f32_16x16x32_bf16 v[84:87], v[168:171], v[200:203], 0
	v_mfma_f32_16x16x32_bf16 v[80:83], v[176:179], v[200:203], 0
	v_mfma_f32_16x16x32_bf16 v[68:71], v[168:171], v[208:211], 0
	v_mfma_f32_16x16x32_bf16 v[64:67], v[176:179], v[208:211], 0
	v_mfma_f32_16x16x32_bf16 v[116:119], v[172:175], v[188:191], v[116:119]
	v_mfma_f32_16x16x32_bf16 v[112:115], v[180:183], v[188:191], v[112:115]
	v_mfma_f32_16x16x32_bf16 v[100:103], v[172:175], v[196:199], v[100:103]
	v_mfma_f32_16x16x32_bf16 v[96:99], v[180:183], v[196:199], v[96:99]
	v_mfma_f32_16x16x32_bf16 v[84:87], v[172:175], v[204:207], v[84:87]
	v_mfma_f32_16x16x32_bf16 v[80:83], v[180:183], v[204:207], v[80:83]
	v_mfma_f32_16x16x32_bf16 v[68:71], v[172:175], v[212:215], v[68:71]
	v_mfma_f32_16x16x32_bf16 v[64:67], v[180:183], v[212:215], v[64:67]
	s_barrier
	s_add_i32 s58, s50, s37
	v_lshl_add_u64 v[146:147], s[30:31], 0, v[134:135]
	s_mov_b32 m0, s58
	ds_read_b128 v[184:187], v151 offset:16384
	ds_read_b128 v[188:191], v151 offset:17408
	ds_read_b128 v[192:195], v151 offset:18432
	ds_read_b128 v[196:199], v151 offset:19456
	ds_read_b128 v[200:203], v151 offset:20480
	ds_read_b128 v[204:207], v151 offset:21504
	ds_read_b128 v[208:211], v151 offset:22528
	ds_read_b128 v[212:215], v151 offset:23552
	global_load_lds_dwordx4 v[146:147], off
	s_add_i32 m0, s58, 0x2000
	s_add_u32 s58, s30, 0x40000
	v_lshl_add_u64 v[216:217], s[30:31], 0, v[130:131]
	s_addc_u32 s59, s31, 0
	s_add_i32 s60, s51, s37
	global_load_lds_dwordx4 v[216:217], off
	v_lshl_add_u64 v[218:219], s[58:59], 0, v[134:135]
	s_mov_b32 m0, s60
	v_lshl_add_u64 v[220:221], s[34:35], 0, v[132:133]
	global_load_lds_dwordx4 v[218:219], off
	v_lshl_add_u64 v[218:219], s[58:59], 0, v[130:131]
	s_add_i32 m0, s60, 0x2000
	s_nop 0
	global_load_lds_dwordx4 v[218:219], off
	v_lshl_add_u64 v[218:219], s[34:35], 0, v[136:137]
	s_mov_b32 m0, s27
	s_nop 0
	global_load_lds_dwordx4 v[218:219], off
	s_mov_b32 m0, s40
	s_nop 0
	global_load_lds_dwordx4 v[220:221], off
	s_waitcnt vmcnt(8)
	s_waitcnt lgkmcnt(0)
	s_barrier
; #define PG8_STAGE(bufoff, gbase, voff) do { _Pragma("unroll") for (int _i = 0; _i < 2; ++_i) \
;         __builtin_amdgcn_global_load_lds((const unsigned*)((const char*)(gbase) + (voff)[_i]), (LAS unsigned*)(lds + (bufoff) + ldsw + _i * 8192), 16, 0, 0); } while (0)
; #define PG8_LDA(dst, b, h) do { _Pragma("unroll") for (int m = 0; m < 4; ++m) _Pragma("unroll") for (int k = 0; k < 2; ++k) dst[m][k] = *(const LAS bf16x8*)(lds + PG8_SA(b, h) + aoff + m * 2048 + k * 1024); } while (0)
; #define PG8_LDB(dst, b, h) do { _Pragma("unroll") for (int n = 0; n < 2; ++n) _Pragma("unroll") for (int k = 0; k < 2; ++k) dst[n][k] = *(const LAS bf16x8*)(lds + PG8_SB(b, h) + boff + n * 2048 + k * 1024); } while (0)
; #define PG8_MMA(ai, bj, At, Bt) do { __builtin_amdgcn_s_setprio(1); _Pragma("unroll") for (int m = 0; m < 4; ++m) _Pragma("unroll") for (int n = 0; n < 2; ++n) _Pragma("unroll") for (int k = 0; k < 2; ++k) \
;         acc[ai][bj][m][n] = __builtin_amdgcn_mfma_f32_16x16x32_bf16(Bt[n][k], At[m][k], acc[ai][bj][m][n], 0, 0, 0); __builtin_amdgcn_s_setprio(0); } while (0)
; #define PG8_WAIT_V(n) asm volatile("s_waitcnt vmcnt(" #n ")" ::: "memory")
; #define PG8_WAIT_L(n) asm volatile("s_waitcnt lgkmcnt(" #n ")" ::: "memory")
; #define PG8_BAR __builtin_amdgcn_s_barrier()
; #define PG8_SCHED __builtin_amdgcn_sched_barrier(0)
; template <class Epi, bool SP2 = false>
; __device__ __forceinline__ void gemm_phase(LAS unsigned char* lds, const Gemm g, const StaticOrder& S, const Epi& E) {
;     ...
;             PG8_WAIT_V(8); PG8_WAIT_L(0); PG8_BAR; PG8_MMA(0, 0, At, B0); PG8_MMA(0, 1, At, B1); PG8_BAR; PG8_SCHED;
;             PG8_LDA(At, 0, 1); PG8_STAGE(PG8_SB(0, 0), b2, voffB); PG8_STAGE(PG8_SB(0, 1), b2 + hstepB, voffB); PG8_STAGE(PG8_SA(0, 0), a2, voffA);
;             PG8_WAIT_V(8); PG8_WAIT_L(0); PG8_BAR; PG8_MMA(1, 0, At, B0); PG8_MMA(1, 1, At, B1); PG8_BAR; PG8_SCHED;
;             PG8_LDB(B0, 1, 0); PG8_LDB(B1, 1, 1); PG8_SCHED; PG8_LDA(At, 1, 0); PG8_STAGE(PG8_SA(0, 1), a2 + hstepA, voffA);
;             PG8_WAIT_V(8); PG8_WAIT_L(0); PG8_BAR; PG8_MMA(0, 0, At, B0); PG8_MMA(0, 1, At, B1); PG8_BAR; PG8_SCHED;
	v_mfma_f32_16x16x32_bf16 v[60:63], v[152:155], v[184:187], 0
	v_mfma_f32_16x16x32_bf16 v[56:59], v[160:163], v[184:187], 0
	v_mfma_f32_16x16x32_bf16 v[44:47], v[152:155], v[192:195], 0
	v_mfma_f32_16x16x32_bf16 v[40:43], v[160:163], v[192:195], 0
	v_mfma_f32_16x16x32_bf16 v[28:31], v[152:155], v[200:203], 0
	v_mfma_f32_16x16x32_bf16 v[24:27], v[160:163], v[200:203], 0
	v_mfma_f32_16x16x32_bf16 v[12:15], v[152:155], v[208:211], 0
	v_mfma_f32_16x16x32_bf16 v[8:11], v[160:163], v[208:211], 0
	v_mfma_f32_16x16x32_bf16 v[60:63], v[156:159], v[188:191], v[60:63]
	v_mfma_f32_16x16x32_bf16 v[56:59], v[164:167], v[188:191], v[56:59]
	v_mfma_f32_16x16x32_bf16 v[44:47], v[156:159], v[196:199], v[44:47]
	v_mfma_f32_16x16x32_bf16 v[40:43], v[164:167], v[196:199], v[40:43]
	v_mfma_f32_16x16x32_bf16 v[28:31], v[156:159], v[204:207], v[28:31]
	v_mfma_f32_16x16x32_bf16 v[24:27], v[164:167], v[204:207], v[24:27]
	v_mfma_f32_16x16x32_bf16 v[12:15], v[156:159], v[212:215], v[12:15]
	v_mfma_f32_16x16x32_bf16 v[8:11], v[164:167], v[212:215], v[8:11]
	v_mfma_f32_16x16x32_bf16 v[52:55], v[168:171], v[184:187], 0
	v_mfma_f32_16x16x32_bf16 v[48:51], v[176:179], v[184:187], 0
	v_mfma_f32_16x16x32_bf16 v[36:39], v[168:171], v[192:195], 0
	v_mfma_f32_16x16x32_bf16 v[32:35], v[176:179], v[192:195], 0
	v_mfma_f32_16x16x32_bf16 v[20:23], v[168:171], v[200:203], 0
	v_mfma_f32_16x16x32_bf16 v[16:19], v[176:179], v[200:203], 0
	v_mfma_f32_16x16x32_bf16 v[4:7], v[168:171], v[208:211], 0
	v_mfma_f32_16x16x32_bf16 v[0:3], v[176:179], v[208:211], 0
	v_mfma_f32_16x16x32_bf16 v[52:55], v[172:175], v[188:191], v[52:55]
	v_mfma_f32_16x16x32_bf16 v[48:51], v[180:183], v[188:191], v[48:51]
	v_mfma_f32_16x16x32_bf16 v[36:39], v[172:175], v[196:199], v[36:39]
	v_mfma_f32_16x16x32_bf16 v[32:35], v[180:183], v[196:199], v[32:35]
	v_mfma_f32_16x16x32_bf16 v[20:23], v[172:175], v[204:207], v[20:23]
	v_mfma_f32_16x16x32_bf16 v[16:19], v[180:183], v[204:207], v[16:19]
	v_mfma_f32_16x16x32_bf16 v[4:7], v[172:175], v[212:215], v[4:7]
	v_mfma_f32_16x16x32_bf16 v[0:3], v[180:183], v[212:215], v[0:3]
	s_barrier
	s_add_i32 s58, 0, 0x18000
	s_add_i32 s59, 0, 0x1c000
	v_add_u32_e32 v164, s58, v148
	v_add_u32_e32 v180, s59, v148
	ds_read_b128 v[152:155], v164
	ds_read_b128 v[156:159], v164 offset:1024
	ds_read_b128 v[160:163], v164 offset:2048
	ds_read_b128 v[164:167], v164 offset:3072
	ds_read_b128 v[168:171], v180
	ds_read_b128 v[172:175], v180 offset:1024
	ds_read_b128 v[176:179], v180 offset:2048
	ds_read_b128 v[180:183], v180 offset:3072
	s_add_u32 s34, s34, 0x40000
	s_addc_u32 s35, s35, 0
	s_mov_b32 m0, s41
	v_lshl_add_u64 v[222:223], s[34:35], 0, v[136:137]
	ds_read_b128 v[184:187], v151 offset:32768
	ds_read_b128 v[188:191], v151 offset:33792
	ds_read_b128 v[192:195], v151 offset:34816
	ds_read_b128 v[196:199], v151 offset:35840
	ds_read_b128 v[200:203], v151 offset:36864
	ds_read_b128 v[204:207], v151 offset:37888
	ds_read_b128 v[208:211], v151 offset:38912
	ds_read_b128 v[212:215], v151 offset:39936
	global_load_lds_dwordx4 v[222:223], off
	v_lshl_add_u64 v[222:223], s[34:35], 0, v[132:133]
	s_mov_b32 m0, s42
	s_nop 0
	global_load_lds_dwordx4 v[222:223], off
	s_waitcnt vmcnt(8)
	s_waitcnt lgkmcnt(0)
	s_barrier
	v_mfma_f32_16x16x32_bf16 v[124:127], v[152:155], v[184:187], v[124:127]
	v_mfma_f32_16x16x32_bf16 v[120:123], v[160:163], v[184:187], v[120:123]
	v_mfma_f32_16x16x32_bf16 v[108:111], v[152:155], v[192:195], v[108:111]
	v_mfma_f32_16x16x32_bf16 v[104:107], v[160:163], v[192:195], v[104:107]
	v_mfma_f32_16x16x32_bf16 v[92:95], v[152:155], v[200:203], v[92:95]
	v_mfma_f32_16x16x32_bf16 v[88:91], v[160:163], v[200:203], v[88:91]
	v_mfma_f32_16x16x32_bf16 v[76:79], v[152:155], v[208:211], v[76:79]
	v_mfma_f32_16x16x32_bf16 v[72:75], v[160:163], v[208:211], v[72:75]
	v_mfma_f32_16x16x32_bf16 v[124:127], v[156:159], v[188:191], v[124:127]
	v_mfma_f32_16x16x32_bf16 v[120:123], v[164:167], v[188:191], v[120:123]
	v_mfma_f32_16x16x32_bf16 v[108:111], v[156:159], v[196:199], v[108:111]
	v_mfma_f32_16x16x32_bf16 v[104:107], v[164:167], v[196:199], v[104:107]
	v_mfma_f32_16x16x32_bf16 v[92:95], v[156:159], v[204:207], v[92:95]
	v_mfma_f32_16x16x32_bf16 v[88:91], v[164:167], v[204:207], v[88:91]
	v_mfma_f32_16x16x32_bf16 v[76:79], v[156:159], v[212:215], v[76:79]
	v_mfma_f32_16x16x32_bf16 v[72:75], v[164:167], v[212:215], v[72:75]
	v_mfma_f32_16x16x32_bf16 v[116:119], v[168:171], v[184:187], v[116:119]
	v_mfma_f32_16x16x32_bf16 v[112:115], v[176:179], v[184:187], v[112:115]
	v_mfma_f32_16x16x32_bf16 v[100:103], v[168:171], v[192:195], v[100:103]
	v_mfma_f32_16x16x32_bf16 v[96:99], v[176:179], v[192:195], v[96:99]
	v_mfma_f32_16x16x32_bf16 v[84:87], v[168:171], v[200:203], v[84:87]
	v_mfma_f32_16x16x32_bf16 v[80:83], v[176:179], v[200:203], v[80:83]
	v_mfma_f32_16x16x32_bf16 v[68:71], v[168:171], v[208:211], v[68:71]
	v_mfma_f32_16x16x32_bf16 v[64:67], v[176:179], v[208:211], v[64:67]
	v_mfma_f32_16x16x32_bf16 v[116:119], v[172:175], v[188:191], v[116:119]
	v_mfma_f32_16x16x32_bf16 v[112:115], v[180:183], v[188:191], v[112:115]
	v_mfma_f32_16x16x32_bf16 v[100:103], v[172:175], v[196:199], v[100:103]
	v_mfma_f32_16x16x32_bf16 v[96:99], v[180:183], v[196:199], v[96:99]
	v_mfma_f32_16x16x32_bf16 v[84:87], v[172:175], v[204:207], v[84:87]
	v_mfma_f32_16x16x32_bf16 v[80:83], v[180:183], v[204:207], v[80:83]
	v_mfma_f32_16x16x32_bf16 v[68:71], v[172:175], v[212:215], v[68:71]
	v_mfma_f32_16x16x32_bf16 v[64:67], v[180:183], v[212:215], v[64:67]
	s_barrier
; #define PG8_STAGE(bufoff, gbase, voff) do { _Pragma("unroll") for (int _i = 0; _i < 2; ++_i) \
;         __builtin_amdgcn_global_load_lds((const unsigned*)((const char*)(gbase) + (voff)[_i]), (LAS unsigned*)(lds + (bufoff) + ldsw + _i * 8192), 16, 0, 0); } while (0)
; #define PG8_LDA(dst, b, h) do { _Pragma("unroll") for (int m = 0; m < 4; ++m) _Pragma("unroll") for (int k = 0; k < 2; ++k) dst[m][k] = *(const LAS bf16x8*)(lds + PG8_SA(b, h) + aoff + m * 2048 + k * 1024); } while (0)
; #define PG8_LDB(dst, b, h) do { _Pragma("unroll") for (int n = 0; n < 2; ++n) _Pragma("unroll") for (int k = 0; k < 2; ++k) dst[n][k] = *(const LAS bf16x8*)(lds + PG8_SB(b, h) + boff + n * 2048 + k * 1024); } while (0)
; #define PG8_MMA(ai, bj, At, Bt) do { __builtin_amdgcn_s_setprio(1); _Pragma("unroll") for (int m = 0; m < 4; ++m) _Pragma("unroll") for (int n = 0; n < 2; ++n) _Pragma("unroll") for (int k = 0; k < 2; ++k) \
;         acc[ai][bj][m][n] = __builtin_amdgcn_mfma_f32_16x16x32_bf16(Bt[n][k], At[m][k], acc[ai][bj][m][n], 0, 0, 0); __builtin_amdgcn_s_setprio(0); } while (0)
; #define PG8_WAIT_V(n) asm volatile("s_waitcnt vmcnt(" #n ")" ::: "memory")
; #define PG8_WAIT_L(n) asm volatile("s_waitcnt lgkmcnt(" #n ")" ::: "memory")
; #define PG8_BAR __builtin_amdgcn_s_barrier()
; #define PG8_SCHED __builtin_amdgcn_sched_barrier(0)
; template <class Epi, bool SP2 = false>
; __device__ __forceinline__ void gemm_phase(LAS unsigned char* lds, const Gemm g, const StaticOrder& S, const Epi& E) {
;     ...
;         for (int t = 0; t < nt; t += 2) {
;     ...
;             PG8_LDB(B0, 1, 0); PG8_LDB(B1, 1, 1); PG8_SCHED; PG8_LDA(At, 1, 0); PG8_STAGE(PG8_SA(0, 1), a2 + hstepA, voffA);
;             PG8_WAIT_V(8); PG8_WAIT_L(0); PG8_BAR; PG8_MMA(0, 0, At, B0); PG8_MMA(0, 1, At, B1); PG8_BAR; PG8_SCHED;
;             PG8_LDA(At, 1, 1); PG8_STAGE(PG8_SB(1, 0), b3, voffB); PG8_STAGE(PG8_SB(1, 1), b3 + hstepB, voffB); PG8_STAGE(PG8_SA(1, 0), a3, voffA);
;             PG8_WAIT_V(8); PG8_WAIT_L(0); PG8_BAR; PG8_MMA(1, 0, At, B0); PG8_MMA(1, 1, At, B1); PG8_BAR; PG8_SCHED;
	s_add_i32 s34, s58, s37
	v_lshl_add_u64 v[146:147], v[146:147], 0, s[8:9]
	s_mov_b32 m0, s34
	ds_read_b128 v[184:187], v151 offset:49152
	ds_read_b128 v[188:191], v151 offset:50176
	ds_read_b128 v[192:195], v151 offset:51200
	ds_read_b128 v[196:199], v151 offset:52224
	ds_read_b128 v[200:203], v151 offset:53248
	ds_read_b128 v[204:207], v151 offset:54272
	ds_read_b128 v[208:211], v151 offset:55296
	ds_read_b128 v[212:215], v151 offset:56320
	global_load_lds_dwordx4 v[146:147], off
	s_add_i32 m0, s34, 0x2000
	s_add_u32 s30, s30, 0x40080
	v_lshl_add_u64 v[146:147], v[216:217], 0, s[8:9]
	s_addc_u32 s31, s31, 0
	s_add_i32 s34, s59, s37
	global_load_lds_dwordx4 v[146:147], off
	v_lshl_add_u64 v[146:147], s[30:31], 0, v[134:135]
	s_mov_b32 m0, s34
	s_nop 0
	global_load_lds_dwordx4 v[146:147], off
	v_lshl_add_u64 v[146:147], s[30:31], 0, v[130:131]
	s_add_i32 m0, s34, 0x2000
	s_nop 0
	global_load_lds_dwordx4 v[146:147], off
	v_lshl_add_u64 v[146:147], v[218:219], 0, s[8:9]
	s_mov_b32 m0, s46
	s_nop 0
	global_load_lds_dwordx4 v[146:147], off
	v_lshl_add_u64 v[146:147], v[220:221], 0, s[8:9]
	s_mov_b32 m0, s47
	s_nop 0
	global_load_lds_dwordx4 v[146:147], off
	s_waitcnt vmcnt(8)
	s_waitcnt lgkmcnt(0)
	s_barrier
	v_mfma_f32_16x16x32_bf16 v[60:63], v[152:155], v[184:187], v[60:63]
	v_mfma_f32_16x16x32_bf16 v[56:59], v[160:163], v[184:187], v[56:59]
	v_mfma_f32_16x16x32_bf16 v[44:47], v[152:155], v[192:195], v[44:47]
	v_mfma_f32_16x16x32_bf16 v[40:43], v[160:163], v[192:195], v[40:43]
	v_mfma_f32_16x16x32_bf16 v[28:31], v[152:155], v[200:203], v[28:31]
	v_mfma_f32_16x16x32_bf16 v[24:27], v[160:163], v[200:203], v[24:27]
	v_mfma_f32_16x16x32_bf16 v[12:15], v[152:155], v[208:211], v[12:15]
	v_mfma_f32_16x16x32_bf16 v[8:11], v[160:163], v[208:211], v[8:11]
	v_mfma_f32_16x16x32_bf16 v[60:63], v[156:159], v[188:191], v[60:63]
	v_mfma_f32_16x16x32_bf16 v[56:59], v[164:167], v[188:191], v[56:59]
	v_mfma_f32_16x16x32_bf16 v[44:47], v[156:159], v[196:199], v[44:47]
	v_mfma_f32_16x16x32_bf16 v[40:43], v[164:167], v[196:199], v[40:43]
	v_mfma_f32_16x16x32_bf16 v[28:31], v[156:159], v[204:207], v[28:31]
	v_mfma_f32_16x16x32_bf16 v[24:27], v[164:167], v[204:207], v[24:27]
	v_mfma_f32_16x16x32_bf16 v[12:15], v[156:159], v[212:215], v[12:15]
	v_mfma_f32_16x16x32_bf16 v[8:11], v[164:167], v[212:215], v[8:11]
	v_mfma_f32_16x16x32_bf16 v[52:55], v[168:171], v[184:187], v[52:55]
	v_mfma_f32_16x16x32_bf16 v[48:51], v[176:179], v[184:187], v[48:51]
	v_mfma_f32_16x16x32_bf16 v[36:39], v[168:171], v[192:195], v[36:39]
	v_mfma_f32_16x16x32_bf16 v[32:35], v[176:179], v[192:195], v[32:35]
	v_mfma_f32_16x16x32_bf16 v[20:23], v[168:171], v[200:203], v[20:23]
	v_mfma_f32_16x16x32_bf16 v[16:19], v[176:179], v[200:203], v[16:19]
	v_mfma_f32_16x16x32_bf16 v[4:7], v[168:171], v[208:211], v[4:7]
	v_mfma_f32_16x16x32_bf16 v[0:3], v[176:179], v[208:211], v[0:3]
	v_mfma_f32_16x16x32_bf16 v[52:55], v[172:175], v[188:191], v[52:55]
	v_mfma_f32_16x16x32_bf16 v[48:51], v[180:183], v[188:191], v[48:51]
	v_mfma_f32_16x16x32_bf16 v[36:39], v[172:175], v[196:199], v[36:39]
	v_mfma_f32_16x16x32_bf16 v[32:35], v[180:183], v[196:199], v[32:35]
	v_mfma_f32_16x16x32_bf16 v[20:23], v[172:175], v[204:207], v[20:23]
	v_mfma_f32_16x16x32_bf16 v[16:19], v[180:183], v[204:207], v[16:19]
	v_mfma_f32_16x16x32_bf16 v[4:7], v[172:175], v[212:215], v[4:7]
	v_mfma_f32_16x16x32_bf16 v[0:3], v[180:183], v[212:215], v[0:3]
	s_barrier
	s_add_i32 s57, s57, 2
	s_add_u32 s28, s28, 0x100
	s_addc_u32 s29, s29, 0
	s_add_u32 s55, s55, 0x100
	s_addc_u32 s56, s56, 0
	s_cmp_gt_u32 s57, 13

; #define PG8_STAGE(bufoff, gbase, voff) do { _Pragma("unroll") for (int _i = 0; _i < 2; ++_i) \
;         __builtin_amdgcn_global_load_lds((const unsigned*)((const char*)(gbase) + (voff)[_i]), (LAS unsigned*)(lds + (bufoff) + ldsw + _i * 8192), 16, 0, 0); } while (0)
; #define PG8_LDA(dst, b, h) do { _Pragma("unroll") for (int m = 0; m < 4; ++m) _Pragma("unroll") for (int k = 0; k < 2; ++k) dst[m][k] = *(const LAS bf16x8*)(lds + PG8_SA(b, h) + aoff + m * 2048 + k * 1024); } while (0)
; #define PG8_LDB(dst, b, h) do { _Pragma("unroll") for (int n = 0; n < 2; ++n) _Pragma("unroll") for (int k = 0; k < 2; ++k) dst[n][k] = *(const LAS bf16x8*)(lds + PG8_SB(b, h) + boff + n * 2048 + k * 1024); } while (0)
; #define PG8_BAR __builtin_amdgcn_s_barrier()
; template <class Epi, bool SP2 = false>
; __device__ __forceinline__ void gemm_phase(LAS unsigned char* lds, const Gemm g, const StaticOrder& S, const Epi& E) {
;     ...
;         const bool has_next = S.next(ui + 1, nxt);
;         const char* nA = has_next ? (const char*)g.A + (size_t)nxt.pm * tstepA : cA; const char* nB = has_next ? (const char*)g.Bt + (size_t)nxt.pn * tstepB : cB;
;         for (int t = 0; t < nt; t += 2) {
;             const bool last = (t == nt - 2);
;             const char* a1 = cA + (size_t)(t + 1) * kstep;
;             const char* a2 = last ? nA : cA + (size_t)(t + 2) * kstep; const char* b2 = last ? nB : cB + (size_t)(t + 2) * kstep;
;             const char* a3 = a2 + kstep; const char* b3 = b2 + kstep;
;             if constexpr (SP2) {
;             PG8_LDB(B0, 0, 0); PG8_LDB(B1, 0, 1); PG8_SCHED; PG8_LDA(At, 0, 0); PG8_STAGE(PG8_SA(1, 1), a1 + hstepA, voffA);
;             PG8_WAIT_V(8); PG8_WAIT_L(0); PG8_BAR; PG8_MMA(0, 0, At, B0); PG8_MMA(0, 1, At, B1); PG8_BAR; PG8_SCHED;
;             PG8_LDA(At, 0, 1); PG8_STAGE(PG8_SB(0, 0), b2, voffB); PG8_STAGE(PG8_SB(0, 1), b2 + hstepB, voffB); PG8_STAGE(PG8_SA(0, 0), a2, voffA);
;             PG8_WAIT_V(8); PG8_WAIT_L(0); PG8_BAR; PG8_MMA(1, 0, At, B0); PG8_MMA(1, 1, At, B1); PG8_BAR; PG8_SCHED;
;     ...
; #pragma unroll
;         for (int a = 0; a < 2; ++a)
; #pragma unroll
;             for (int b = 0; b < 2; ++b)
; #pragma unroll
;                 for (int m = 0; m < 4; ++m)
; #pragma unroll
;                     for (int n = 0; n < 2; ++n) acc[a][b][m][n] = (f32x4){0.f, 0.f, 0.f, 0.f};
;         cur = nxt; cA = nA; cB = nB; ++ui;
.LBB0_1147:
	s_add_u32 s30, s30, 0xb0080
	s_addc_u32 s31, s31, 0
	s_add_u32 s62, s34, 0x100
	s_addc_u32 s63, s35, 0
	s_mov_b32 s64, -2
	ds_read_b128 v[150:153], v147
	ds_read_b128 v[154:157], v147 offset:1024
	ds_read_b128 v[158:161], v147 offset:2048
	ds_read_b128 v[162:165], v147 offset:3072
	ds_read_b128 v[166:169], v148
	ds_read_b128 v[170:173], v148 offset:1024
	ds_read_b128 v[174:177], v148 offset:2048
	ds_read_b128 v[178:181], v148 offset:3072
	s_add_u32 s34, s30, 0xfff50080
	s_addc_u32 s35, s31, -1
	s_cmp_eq_u32 s64, 40
	s_cselect_b32 s37, s5, s35
	s_cselect_b32 s36, s4, s34
	s_cselect_b32 s35, s29, s63
	s_cselect_b32 s34, s28, s62
	v_lshl_add_u64 v[214:215], s[30:31], 0, v[138:139]
	s_add_i32 m0, s41, 0xc000
	ds_read_b128 v[182:185], v149
	ds_read_b128 v[186:189], v149 offset:1024
	ds_read_b128 v[190:193], v149 offset:2048
	ds_read_b128 v[194:197], v149 offset:3072
	ds_read_b128 v[198:201], v149 offset:4096
	ds_read_b128 v[202:205], v149 offset:5120
	ds_read_b128 v[206:209], v149 offset:6144
	ds_read_b128 v[210:213], v149 offset:7168
	global_load_lds_dwordx4 v[214:215], off
	v_lshl_add_u64 v[214:215], s[30:31], 0, v[140:141]
	s_add_i32 m0, s41, 0xe000
	s_nop 0
	global_load_lds_dwordx4 v[214:215], off
	s_waitcnt vmcnt(24)
	s_waitcnt lgkmcnt(0)
	s_barrier
	v_mfma_f32_16x16x32_bf16 v[124:127], v[150:153], v[182:185], 0
	v_mfma_f32_16x16x32_bf16 v[120:123], v[158:161], v[182:185], 0
	v_mfma_f32_16x16x32_bf16 v[116:119], v[150:153], v[190:193], 0
	v_mfma_f32_16x16x32_bf16 v[112:115], v[158:161], v[190:193], 0
	v_mfma_f32_16x16x32_bf16 v[100:103], v[150:153], v[198:201], 0
	v_mfma_f32_16x16x32_bf16 v[96:99], v[158:161], v[198:201], 0
	v_mfma_f32_16x16x32_bf16 v[84:87], v[150:153], v[206:209], 0
	v_mfma_f32_16x16x32_bf16 v[80:83], v[158:161], v[206:209], 0
	v_mfma_f32_16x16x32_bf16 v[124:127], v[154:157], v[186:189], v[124:127]
	v_mfma_f32_16x16x32_bf16 v[120:123], v[162:165], v[186:189], v[120:123]
	v_mfma_f32_16x16x32_bf16 v[116:119], v[154:157], v[194:197], v[116:119]
	v_mfma_f32_16x16x32_bf16 v[112:115], v[162:165], v[194:197], v[112:115]
	v_mfma_f32_16x16x32_bf16 v[100:103], v[154:157], v[202:205], v[100:103]
	v_mfma_f32_16x16x32_bf16 v[96:99], v[162:165], v[202:205], v[96:99]
	v_mfma_f32_16x16x32_bf16 v[84:87], v[154:157], v[210:213], v[84:87]
	v_mfma_f32_16x16x32_bf16 v[80:83], v[162:165], v[210:213], v[80:83]
	v_mfma_f32_16x16x32_bf16 v[108:111], v[166:169], v[182:185], 0
	v_mfma_f32_16x16x32_bf16 v[104:107], v[174:177], v[182:185], 0
	v_mfma_f32_16x16x32_bf16 v[92:95], v[166:169], v[190:193], 0
	v_mfma_f32_16x16x32_bf16 v[88:91], v[174:177], v[190:193], 0
	v_mfma_f32_16x16x32_bf16 v[76:79], v[166:169], v[198:201], 0
	v_mfma_f32_16x16x32_bf16 v[72:75], v[174:177], v[198:201], 0
	v_mfma_f32_16x16x32_bf16 v[68:71], v[166:169], v[206:209], 0
	v_mfma_f32_16x16x32_bf16 v[64:67], v[174:177], v[206:209], 0
	v_mfma_f32_16x16x32_bf16 v[108:111], v[170:173], v[186:189], v[108:111]
	v_mfma_f32_16x16x32_bf16 v[104:107], v[178:181], v[186:189], v[104:107]
	v_mfma_f32_16x16x32_bf16 v[92:95], v[170:173], v[194:197], v[92:95]
	v_mfma_f32_16x16x32_bf16 v[88:91], v[178:181], v[194:197], v[88:91]
	v_mfma_f32_16x16x32_bf16 v[76:79], v[170:173], v[202:205], v[76:79]
	v_mfma_f32_16x16x32_bf16 v[72:75], v[178:181], v[202:205], v[72:75]
	v_mfma_f32_16x16x32_bf16 v[68:71], v[170:173], v[210:213], v[68:71]
	v_mfma_f32_16x16x32_bf16 v[64:67], v[178:181], v[210:213], v[64:67]
	s_barrier
	s_add_i32 s65, s52, s38
	v_lshl_add_u64 v[214:215], s[34:35], 0, v[134:135]
	s_mov_b32 m0, s65
	ds_read_b128 v[182:185], v149 offset:16384
	ds_read_b128 v[186:189], v149 offset:17408
	ds_read_b128 v[190:193], v149 offset:18432
	ds_read_b128 v[194:197], v149 offset:19456
	ds_read_b128 v[198:201], v149 offset:20480
	ds_read_b128 v[202:205], v149 offset:21504
	ds_read_b128 v[206:209], v149 offset:22528
	ds_read_b128 v[210:213], v149 offset:23552
	global_load_lds_dwordx4 v[214:215], off
	s_add_i32 m0, s65, 0x2000
	s_add_u32 s66, s34, 0xb0000
	v_lshl_add_u64 v[216:217], s[34:35], 0, v[130:131]
	s_addc_u32 s67, s35, 0
	s_add_i32 s65, s53, s38
	global_load_lds_dwordx4 v[216:217], off
	v_lshl_add_u64 v[218:219], s[66:67], 0, v[134:135]
	s_mov_b32 m0, s65
	v_lshl_add_u64 v[220:221], s[36:37], 0, v[132:133]
	global_load_lds_dwordx4 v[218:219], off
	v_lshl_add_u64 v[218:219], s[66:67], 0, v[130:131]
	s_add_i32 m0, s65, 0x2000
	s_nop 0
	global_load_lds_dwordx4 v[218:219], off
	v_lshl_add_u64 v[218:219], s[36:37], 0, v[136:137]
	s_mov_b32 m0, s41
	s_nop 0
	global_load_lds_dwordx4 v[218:219], off
	s_mov_b32 m0, s42
	s_nop 0
	global_load_lds_dwordx4 v[220:221], off
	s_waitcnt vmcnt(8)
	s_waitcnt lgkmcnt(0)
	s_barrier
; #define PG8_STAGE(bufoff, gbase, voff) do { _Pragma("unroll") for (int _i = 0; _i < 2; ++_i) \
;         __builtin_amdgcn_global_load_lds((const unsigned*)((const char*)(gbase) + (voff)[_i]), (LAS unsigned*)(lds + (bufoff) + ldsw + _i * 8192), 16, 0, 0); } while (0)
; #define PG8_LDA(dst, b, h) do { _Pragma("unroll") for (int m = 0; m < 4; ++m) _Pragma("unroll") for (int k = 0; k < 2; ++k) dst[m][k] = *(const LAS bf16x8*)(lds + PG8_SA(b, h) + aoff + m * 2048 + k * 1024); } while (0)
; #define PG8_LDB(dst, b, h) do { _Pragma("unroll") for (int n = 0; n < 2; ++n) _Pragma("unroll") for (int k = 0; k < 2; ++k) dst[n][k] = *(const LAS bf16x8*)(lds + PG8_SB(b, h) + boff + n * 2048 + k * 1024); } while (0)
; #define PG8_MMA(ai, bj, At, Bt) do { __builtin_amdgcn_s_setprio(1); _Pragma("unroll") for (int m = 0; m < 4; ++m) _Pragma("unroll") for (int n = 0; n < 2; ++n) _Pragma("unroll") for (int k = 0; k < 2; ++k) \
;         acc[ai][bj][m][n] = __builtin_amdgcn_mfma_f32_16x16x32_bf16(Bt[n][k], At[m][k], acc[ai][bj][m][n], 0, 0, 0); __builtin_amdgcn_s_setprio(0); } while (0)
; #define PG8_WAIT_V(n) asm volatile("s_waitcnt vmcnt(" #n ")" ::: "memory")
; #define PG8_WAIT_L(n) asm volatile("s_waitcnt lgkmcnt(" #n ")" ::: "memory")
; #define PG8_BAR __builtin_amdgcn_s_barrier()
; #define PG8_SCHED __builtin_amdgcn_sched_barrier(0)
; template <class Epi, bool SP2 = false>
; __device__ __forceinline__ void gemm_phase(LAS unsigned char* lds, const Gemm g, const StaticOrder& S, const Epi& E) {
;     ...
;             PG8_WAIT_V(8); PG8_WAIT_L(0); PG8_BAR; PG8_MMA(0, 0, At, B0); PG8_MMA(0, 1, At, B1); PG8_BAR; PG8_SCHED;
;             PG8_LDA(At, 0, 1); PG8_STAGE(PG8_SB(0, 0), b2, voffB); PG8_STAGE(PG8_SB(0, 1), b2 + hstepB, voffB); PG8_STAGE(PG8_SA(0, 0), a2, voffA);
;             PG8_WAIT_V(8); PG8_WAIT_L(0); PG8_BAR; PG8_MMA(1, 0, At, B0); PG8_MMA(1, 1, At, B1); PG8_BAR; PG8_SCHED;
;             PG8_LDB(B0, 1, 0); PG8_LDB(B1, 1, 1); PG8_SCHED; PG8_LDA(At, 1, 0); PG8_STAGE(PG8_SA(0, 1), a2 + hstepA, voffA);
;             PG8_WAIT_V(8); PG8_WAIT_L(0); PG8_BAR; PG8_MMA(0, 0, At, B0); PG8_MMA(0, 1, At, B1); PG8_BAR; PG8_SCHED;
	v_mfma_f32_16x16x32_bf16 v[60:63], v[150:153], v[182:185], 0
	v_mfma_f32_16x16x32_bf16 v[56:59], v[158:161], v[182:185], 0
	v_mfma_f32_16x16x32_bf16 v[52:55], v[150:153], v[190:193], 0
	v_mfma_f32_16x16x32_bf16 v[48:51], v[158:161], v[190:193], 0
	v_mfma_f32_16x16x32_bf16 v[36:39], v[150:153], v[198:201], 0
	v_mfma_f32_16x16x32_bf16 v[32:35], v[158:161], v[198:201], 0
	v_mfma_f32_16x16x32_bf16 v[20:23], v[150:153], v[206:209], 0
	v_mfma_f32_16x16x32_bf16 v[16:19], v[158:161], v[206:209], 0
	v_mfma_f32_16x16x32_bf16 v[60:63], v[154:157], v[186:189], v[60:63]
	v_mfma_f32_16x16x32_bf16 v[56:59], v[162:165], v[186:189], v[56:59]
	v_mfma_f32_16x16x32_bf16 v[52:55], v[154:157], v[194:197], v[52:55]
	v_mfma_f32_16x16x32_bf16 v[48:51], v[162:165], v[194:197], v[48:51]
	v_mfma_f32_16x16x32_bf16 v[36:39], v[154:157], v[202:205], v[36:39]
	v_mfma_f32_16x16x32_bf16 v[32:35], v[162:165], v[202:205], v[32:35]
	v_mfma_f32_16x16x32_bf16 v[20:23], v[154:157], v[210:213], v[20:23]
	v_mfma_f32_16x16x32_bf16 v[16:19], v[162:165], v[210:213], v[16:19]
	v_mfma_f32_16x16x32_bf16 v[44:47], v[166:169], v[182:185], 0
	v_mfma_f32_16x16x32_bf16 v[40:43], v[174:177], v[182:185], 0
	v_mfma_f32_16x16x32_bf16 v[28:31], v[166:169], v[190:193], 0
	v_mfma_f32_16x16x32_bf16 v[24:27], v[174:177], v[190:193], 0
	v_mfma_f32_16x16x32_bf16 v[12:15], v[166:169], v[198:201], 0
	v_mfma_f32_16x16x32_bf16 v[8:11], v[174:177], v[198:201], 0
	v_mfma_f32_16x16x32_bf16 v[4:7], v[166:169], v[206:209], 0
	v_mfma_f32_16x16x32_bf16 v[0:3], v[174:177], v[206:209], 0
	v_mfma_f32_16x16x32_bf16 v[44:47], v[170:173], v[186:189], v[44:47]
	v_mfma_f32_16x16x32_bf16 v[40:43], v[178:181], v[186:189], v[40:43]
	v_mfma_f32_16x16x32_bf16 v[28:31], v[170:173], v[194:197], v[28:31]
	v_mfma_f32_16x16x32_bf16 v[24:27], v[178:181], v[194:197], v[24:27]
	v_mfma_f32_16x16x32_bf16 v[12:15], v[170:173], v[202:205], v[12:15]
	v_mfma_f32_16x16x32_bf16 v[8:11], v[178:181], v[202:205], v[8:11]
	v_mfma_f32_16x16x32_bf16 v[4:7], v[170:173], v[210:213], v[4:7]
	v_mfma_f32_16x16x32_bf16 v[0:3], v[178:181], v[210:213], v[0:3]
	s_barrier
	s_add_i32 s65, 0, 0x18000
	s_add_i32 s66, 0, 0x1c000
	v_add_u32_e32 v162, s65, v146
	v_add_u32_e32 v178, s66, v146
	ds_read_b128 v[150:153], v162
	ds_read_b128 v[154:157], v162 offset:1024
	ds_read_b128 v[158:161], v162 offset:2048
	ds_read_b128 v[162:165], v162 offset:3072
	ds_read_b128 v[166:169], v178
	ds_read_b128 v[170:173], v178 offset:1024
	ds_read_b128 v[174:177], v178 offset:2048
	ds_read_b128 v[178:181], v178 offset:3072
	s_add_u32 s36, s36, 0xb0000
	s_addc_u32 s37, s37, 0
	s_mov_b32 m0, s43
	v_lshl_add_u64 v[222:223], s[36:37], 0, v[136:137]
	ds_read_b128 v[182:185], v149 offset:32768
	ds_read_b128 v[186:189], v149 offset:33792
	ds_read_b128 v[190:193], v149 offset:34816
	ds_read_b128 v[194:197], v149 offset:35840
	ds_read_b128 v[198:201], v149 offset:36864
	ds_read_b128 v[202:205], v149 offset:37888
	ds_read_b128 v[206:209], v149 offset:38912
	ds_read_b128 v[210:213], v149 offset:39936
	global_load_lds_dwordx4 v[222:223], off
	v_lshl_add_u64 v[222:223], s[36:37], 0, v[132:133]
	s_mov_b32 m0, s44
	s_nop 0
	global_load_lds_dwordx4 v[222:223], off
	s_waitcnt vmcnt(8)
	s_waitcnt lgkmcnt(0)
	s_barrier
	v_mfma_f32_16x16x32_bf16 v[124:127], v[150:153], v[182:185], v[124:127]
	v_mfma_f32_16x16x32_bf16 v[120:123], v[158:161], v[182:185], v[120:123]
	v_mfma_f32_16x16x32_bf16 v[116:119], v[150:153], v[190:193], v[116:119]
	v_mfma_f32_16x16x32_bf16 v[112:115], v[158:161], v[190:193], v[112:115]
	v_mfma_f32_16x16x32_bf16 v[100:103], v[150:153], v[198:201], v[100:103]
	v_mfma_f32_16x16x32_bf16 v[96:99], v[158:161], v[198:201], v[96:99]
	v_mfma_f32_16x16x32_bf16 v[84:87], v[150:153], v[206:209], v[84:87]
	v_mfma_f32_16x16x32_bf16 v[80:83], v[158:161], v[206:209], v[80:83]
	v_mfma_f32_16x16x32_bf16 v[124:127], v[154:157], v[186:189], v[124:127]
	v_mfma_f32_16x16x32_bf16 v[120:123], v[162:165], v[186:189], v[120:123]
	v_mfma_f32_16x16x32_bf16 v[116:119], v[154:157], v[194:197], v[116:119]
	v_mfma_f32_16x16x32_bf16 v[112:115], v[162:165], v[194:197], v[112:115]
	v_mfma_f32_16x16x32_bf16 v[100:103], v[154:157], v[202:205], v[100:103]
	v_mfma_f32_16x16x32_bf16 v[96:99], v[162:165], v[202:205], v[96:99]
	v_mfma_f32_16x16x32_bf16 v[84:87], v[154:157], v[210:213], v[84:87]
	v_mfma_f32_16x16x32_bf16 v[80:83], v[162:165], v[210:213], v[80:83]
	v_mfma_f32_16x16x32_bf16 v[108:111], v[166:169], v[182:185], v[108:111]
	v_mfma_f32_16x16x32_bf16 v[104:107], v[174:177], v[182:185], v[104:107]
	v_mfma_f32_16x16x32_bf16 v[92:95], v[166:169], v[190:193], v[92:95]
	v_mfma_f32_16x16x32_bf16 v[88:91], v[174:177], v[190:193], v[88:91]
	v_mfma_f32_16x16x32_bf16 v[76:79], v[166:169], v[198:201], v[76:79]
	v_mfma_f32_16x16x32_bf16 v[72:75], v[174:177], v[198:201], v[72:75]
	v_mfma_f32_16x16x32_bf16 v[68:71], v[166:169], v[206:209], v[68:71]
	v_mfma_f32_16x16x32_bf16 v[64:67], v[174:177], v[206:209], v[64:67]
	v_mfma_f32_16x16x32_bf16 v[108:111], v[170:173], v[186:189], v[108:111]
	v_mfma_f32_16x16x32_bf16 v[104:107], v[178:181], v[186:189], v[104:107]
	v_mfma_f32_16x16x32_bf16 v[92:95], v[170:173], v[194:197], v[92:95]
	v_mfma_f32_16x16x32_bf16 v[88:91], v[178:181], v[194:197], v[88:91]
	v_mfma_f32_16x16x32_bf16 v[76:79], v[170:173], v[202:205], v[76:79]
	v_mfma_f32_16x16x32_bf16 v[72:75], v[178:181], v[202:205], v[72:75]
	v_mfma_f32_16x16x32_bf16 v[68:71], v[170:173], v[210:213], v[68:71]
	v_mfma_f32_16x16x32_bf16 v[64:67], v[178:181], v[210:213], v[64:67]
	s_barrier
; #define PG8_STAGE(bufoff, gbase, voff) do { _Pragma("unroll") for (int _i = 0; _i < 2; ++_i) \
;         __builtin_amdgcn_global_load_lds((const unsigned*)((const char*)(gbase) + (voff)[_i]), (LAS unsigned*)(lds + (bufoff) + ldsw + _i * 8192), 16, 0, 0); } while (0)
; #define PG8_LDA(dst, b, h) do { _Pragma("unroll") for (int m = 0; m < 4; ++m) _Pragma("unroll") for (int k = 0; k < 2; ++k) dst[m][k] = *(const LAS bf16x8*)(lds + PG8_SA(b, h) + aoff + m * 2048 + k * 1024); } while (0)
; #define PG8_LDB(dst, b, h) do { _Pragma("unroll") for (int n = 0; n < 2; ++n) _Pragma("unroll") for (int k = 0; k < 2; ++k) dst[n][k] = *(const LAS bf16x8*)(lds + PG8_SB(b, h) + boff + n * 2048 + k * 1024); } while (0)
; #define PG8_MMA(ai, bj, At, Bt) do { __builtin_amdgcn_s_setprio(1); _Pragma("unroll") for (int m = 0; m < 4; ++m) _Pragma("unroll") for (int n = 0; n < 2; ++n) _Pragma("unroll") for (int k = 0; k < 2; ++k) \
;         acc[ai][bj][m][n] = __builtin_amdgcn_mfma_f32_16x16x32_bf16(Bt[n][k], At[m][k], acc[ai][bj][m][n], 0, 0, 0); __builtin_amdgcn_s_setprio(0); } while (0)
; #define PG8_WAIT_V(n) asm volatile("s_waitcnt vmcnt(" #n ")" ::: "memory")
; #define PG8_WAIT_L(n) asm volatile("s_waitcnt lgkmcnt(" #n ")" ::: "memory")
; #define PG8_BAR __builtin_amdgcn_s_barrier()
; #define PG8_SCHED __builtin_amdgcn_sched_barrier(0)
; template <class Epi, bool SP2 = false>
; __device__ __forceinline__ void gemm_phase(LAS unsigned char* lds, const Gemm g, const StaticOrder& S, const Epi& E) {
;     ...
;         for (int t = 0; t < nt; t += 2) {
;     ...
;             PG8_LDB(B0, 1, 0); PG8_LDB(B1, 1, 1); PG8_SCHED; PG8_LDA(At, 1, 0); PG8_STAGE(PG8_SA(0, 1), a2 + hstepA, voffA);
;             PG8_WAIT_V(8); PG8_WAIT_L(0); PG8_BAR; PG8_MMA(0, 0, At, B0); PG8_MMA(0, 1, At, B1); PG8_BAR; PG8_SCHED;
;             PG8_LDA(At, 1, 1); PG8_STAGE(PG8_SB(1, 0), b3, voffB); PG8_STAGE(PG8_SB(1, 1), b3 + hstepB, voffB); PG8_STAGE(PG8_SA(1, 0), a3, voffA);
;             PG8_WAIT_V(8); PG8_WAIT_L(0); PG8_BAR; PG8_MMA(1, 0, At, B0); PG8_MMA(1, 1, At, B1); PG8_BAR; PG8_SCHED;
	s_add_i32 s36, s65, s38
	v_lshl_add_u64 v[214:215], v[214:215], 0, s[10:11]
	s_mov_b32 m0, s36
	ds_read_b128 v[182:185], v149 offset:49152
	ds_read_b128 v[186:189], v149 offset:50176
	ds_read_b128 v[190:193], v149 offset:51200
	ds_read_b128 v[194:197], v149 offset:52224
	ds_read_b128 v[198:201], v149 offset:53248
	ds_read_b128 v[202:205], v149 offset:54272
	ds_read_b128 v[206:209], v149 offset:55296
	ds_read_b128 v[210:213], v149 offset:56320
	global_load_lds_dwordx4 v[214:215], off
	s_add_i32 m0, s36, 0x2000
	s_add_u32 s34, s34, 0xb0080
	v_lshl_add_u64 v[214:215], v[216:217], 0, s[10:11]
	s_addc_u32 s35, s35, 0
	s_add_i32 s36, s66, s38
	global_load_lds_dwordx4 v[214:215], off
	v_lshl_add_u64 v[214:215], s[34:35], 0, v[134:135]
	s_mov_b32 m0, s36
	s_nop 0
	global_load_lds_dwordx4 v[214:215], off
	v_lshl_add_u64 v[214:215], s[34:35], 0, v[130:131]
	s_add_i32 m0, s36, 0x2000
	s_nop 0
	global_load_lds_dwordx4 v[214:215], off
	v_lshl_add_u64 v[214:215], v[218:219], 0, s[10:11]
	s_mov_b32 m0, s48
	s_nop 0
	global_load_lds_dwordx4 v[214:215], off
	v_lshl_add_u64 v[214:215], v[220:221], 0, s[10:11]
	s_mov_b32 m0, s49
	s_nop 0
	global_load_lds_dwordx4 v[214:215], off
	s_waitcnt vmcnt(8)
	s_waitcnt lgkmcnt(0)
	s_barrier
	v_mfma_f32_16x16x32_bf16 v[60:63], v[150:153], v[182:185], v[60:63]
	v_mfma_f32_16x16x32_bf16 v[56:59], v[158:161], v[182:185], v[56:59]
	v_mfma_f32_16x16x32_bf16 v[52:55], v[150:153], v[190:193], v[52:55]
	v_mfma_f32_16x16x32_bf16 v[48:51], v[158:161], v[190:193], v[48:51]
	v_mfma_f32_16x16x32_bf16 v[36:39], v[150:153], v[198:201], v[36:39]
	v_mfma_f32_16x16x32_bf16 v[32:35], v[158:161], v[198:201], v[32:35]
	v_mfma_f32_16x16x32_bf16 v[20:23], v[150:153], v[206:209], v[20:23]
	v_mfma_f32_16x16x32_bf16 v[16:19], v[158:161], v[206:209], v[16:19]
	v_mfma_f32_16x16x32_bf16 v[60:63], v[154:157], v[186:189], v[60:63]
	v_mfma_f32_16x16x32_bf16 v[56:59], v[162:165], v[186:189], v[56:59]
	v_mfma_f32_16x16x32_bf16 v[52:55], v[154:157], v[194:197], v[52:55]
	v_mfma_f32_16x16x32_bf16 v[48:51], v[162:165], v[194:197], v[48:51]
	v_mfma_f32_16x16x32_bf16 v[36:39], v[154:157], v[202:205], v[36:39]
	v_mfma_f32_16x16x32_bf16 v[32:35], v[162:165], v[202:205], v[32:35]
	v_mfma_f32_16x16x32_bf16 v[20:23], v[154:157], v[210:213], v[20:23]
	v_mfma_f32_16x16x32_bf16 v[16:19], v[162:165], v[210:213], v[16:19]
	v_mfma_f32_16x16x32_bf16 v[44:47], v[166:169], v[182:185], v[44:47]
	v_mfma_f32_16x16x32_bf16 v[40:43], v[174:177], v[182:185], v[40:43]
	v_mfma_f32_16x16x32_bf16 v[28:31], v[166:169], v[190:193], v[28:31]
	v_mfma_f32_16x16x32_bf16 v[24:27], v[174:177], v[190:193], v[24:27]
	v_mfma_f32_16x16x32_bf16 v[12:15], v[166:169], v[198:201], v[12:15]
	v_mfma_f32_16x16x32_bf16 v[8:11], v[174:177], v[198:201], v[8:11]
	v_mfma_f32_16x16x32_bf16 v[4:7], v[166:169], v[206:209], v[4:7]
	v_mfma_f32_16x16x32_bf16 v[0:3], v[174:177], v[206:209], v[0:3]
	v_mfma_f32_16x16x32_bf16 v[44:47], v[170:173], v[186:189], v[44:47]
	v_mfma_f32_16x16x32_bf16 v[40:43], v[178:181], v[186:189], v[40:43]
	v_mfma_f32_16x16x32_bf16 v[28:31], v[170:173], v[194:197], v[28:31]
	v_mfma_f32_16x16x32_bf16 v[24:27], v[178:181], v[194:197], v[24:27]
	v_mfma_f32_16x16x32_bf16 v[12:15], v[170:173], v[202:205], v[12:15]
	v_mfma_f32_16x16x32_bf16 v[8:11], v[178:181], v[202:205], v[8:11]
	v_mfma_f32_16x16x32_bf16 v[4:7], v[170:173], v[210:213], v[4:7]
	v_mfma_f32_16x16x32_bf16 v[0:3], v[178:181], v[210:213], v[0:3]
	s_barrier
	s_add_i32 s64, s64, 2
	s_add_u32 s30, s30, 0x100
	s_addc_u32 s31, s31, 0
	s_add_u32 s62, s62, 0x100
	s_addc_u32 s63, s63, 0
	s_cmp_gt_u32 s64, 41
